# K-loops: the lgkmcnt(8) wait before the phase-1/5 barrier removed (with the rotated stage layout the B-fragment buffer is refilled two phases later, so the reads no longer have to complete before that
# speedup vs baseline: 1.0035x; 1.0035x over previous
.LBB0_122:
	v_mov_b64_e32 v[0:1], 0x180
	s_ashr_i32 s15, s14, 31
	v_cmp_lt_i64_e32 vcc, s[16:17], v[0:1]
	s_lshl_b64 s[16:17], s[14:15], 19
	s_add_u32 s16, s30, s16
	s_addc_u32 s17, s31, s17
	s_and_b64 s[18:19], vcc, exec
	s_cselect_b32 s7, s17, s21
	s_cselect_b32 s9, s16, s20
	s_ashr_i32 s13, s12, 31
	s_lshl_b64 s[18:19], s[12:13], 19
	s_add_u32 s18, s34, s18
	s_addc_u32 s19, s35, s19
	s_and_b64 s[22:23], vcc, exec
	s_cselect_b32 s13, s19, s3
	s_cselect_b32 s15, s18, s2
	s_add_u32 s20, s20, 0x40080
	s_addc_u32 s21, s21, 0
	s_add_u32 s50, s2, 0x100
	s_addc_u32 s51, s3, 0
	s_mov_b32 s52, -2
	s_add_u32 s2, s20, 0xfffc0080
	s_addc_u32 s3, s21, -1
	ds_read_b128 v[24:27], v164
	ds_read_b128 v[28:31], v164 offset:1024
	ds_read_b128 v[32:35], v164 offset:2048
	ds_read_b128 v[36:39], v164 offset:3072
	s_cmp_eq_u32 s52, 12
	s_cselect_b32 s23, s7, s3
	s_cselect_b32 s22, s9, s2
	s_cselect_b32 s3, s13, s51
	s_cselect_b32 s2, s15, s50
	ds_read_b128 v[154:157], v165
	ds_read_b128 v[158:161], v165 offset:1024
	ds_read_b128 v[180:183], v165 offset:2048
	ds_read_b128 v[184:187], v165 offset:3072
	ds_read_b128 v[188:191], v165 offset:4096
	ds_read_b128 v[192:195], v165 offset:5120
	ds_read_b128 v[196:199], v165 offset:6144
	ds_read_b128 v[200:203], v165 offset:7168
	s_barrier
	s_waitcnt lgkmcnt(0)
	v_mfma_f32_16x16x32_bf16 v[140:143], v[24:27], v[154:157], 0
	v_mfma_f32_16x16x32_bf16 v[136:139], v[32:35], v[154:157], 0
	v_mfma_f32_16x16x32_bf16 v[124:127], v[24:27], v[180:183], 0
	v_mfma_f32_16x16x32_bf16 v[120:123], v[32:35], v[180:183], 0
	v_mfma_f32_16x16x32_bf16 v[108:111], v[24:27], v[188:191], 0
	v_mfma_f32_16x16x32_bf16 v[104:107], v[32:35], v[188:191], 0
	v_mfma_f32_16x16x32_bf16 v[92:95], v[24:27], v[196:199], 0
	v_mfma_f32_16x16x32_bf16 v[88:91], v[32:35], v[196:199], 0
	v_mfma_f32_16x16x32_bf16 v[140:143], v[28:31], v[158:161], v[140:143]
	v_mfma_f32_16x16x32_bf16 v[136:139], v[36:39], v[158:161], v[136:139]
	v_mfma_f32_16x16x32_bf16 v[124:127], v[28:31], v[184:187], v[124:127]
	v_mfma_f32_16x16x32_bf16 v[120:123], v[36:39], v[184:187], v[120:123]
	v_mfma_f32_16x16x32_bf16 v[108:111], v[28:31], v[192:195], v[108:111]
	v_mfma_f32_16x16x32_bf16 v[104:107], v[36:39], v[192:195], v[104:107]
	v_mfma_f32_16x16x32_bf16 v[92:95], v[28:31], v[200:203], v[92:95]
	v_mfma_f32_16x16x32_bf16 v[88:91], v[36:39], v[200:203], v[88:91]
	s_barrier
	s_add_i32 m0, s37, 0xc000
	ds_read_b128 v[204:207], v164 offset:16384
	ds_read_b128 v[208:211], v164 offset:17408
	ds_read_b128 v[212:215], v164 offset:18432
	global_load_lds_dwordx4 v150, s[20:21]
	s_add_i32 m0, s37, 0xe000
	ds_read_b128 v[216:219], v164 offset:19456
	global_load_lds_dwordx4 v152, s[20:21]
	s_add_u32 s98, s2, 0x80
	s_addc_u32 s99, s3, 0
	s_barrier
	s_waitcnt lgkmcnt(0)
	v_mfma_f32_16x16x32_bf16 v[132:135], v[204:207], v[154:157], 0
	v_mfma_f32_16x16x32_bf16 v[128:131], v[212:215], v[154:157], 0
	v_mfma_f32_16x16x32_bf16 v[116:119], v[204:207], v[180:183], 0
	v_mfma_f32_16x16x32_bf16 v[112:115], v[212:215], v[180:183], 0
	v_mfma_f32_16x16x32_bf16 v[100:103], v[204:207], v[188:191], 0
	v_mfma_f32_16x16x32_bf16 v[96:99], v[212:215], v[188:191], 0
	v_mfma_f32_16x16x32_bf16 v[84:87], v[204:207], v[196:199], 0
	v_mfma_f32_16x16x32_bf16 v[80:83], v[212:215], v[196:199], 0
	v_mfma_f32_16x16x32_bf16 v[132:135], v[208:211], v[158:161], v[132:135]
	v_mfma_f32_16x16x32_bf16 v[128:131], v[216:219], v[158:161], v[128:131]
	v_mfma_f32_16x16x32_bf16 v[116:119], v[208:211], v[184:187], v[116:119]
	v_mfma_f32_16x16x32_bf16 v[112:115], v[216:219], v[184:187], v[112:115]
	v_mfma_f32_16x16x32_bf16 v[100:103], v[208:211], v[192:195], v[100:103]
	v_mfma_f32_16x16x32_bf16 v[96:99], v[216:219], v[192:195], v[96:99]
	v_mfma_f32_16x16x32_bf16 v[84:87], v[208:211], v[200:203], v[84:87]
	v_mfma_f32_16x16x32_bf16 v[80:83], v[216:219], v[200:203], v[80:83]
	s_add_u32 s100, s22, 0x80
	s_addc_u32 s101, s23, 0
	s_barrier
	ds_read_b128 v[154:157], v165 offset:16384
	ds_read_b128 v[158:161], v165 offset:17408
	ds_read_b128 v[180:183], v165 offset:18432
	ds_read_b128 v[184:187], v165 offset:19456
	ds_read_b128 v[188:191], v165 offset:20480
	ds_read_b128 v[192:195], v165 offset:21504
	ds_read_b128 v[196:199], v165 offset:22528
	ds_read_b128 v[200:203], v165 offset:23552
	s_add_i32 m0, s36, 0x10000
	s_nop 0
	global_load_lds_dwordx4 v168, s[2:3]
	s_add_i32 m0, s36, 0x12000
	s_nop 0
	global_load_lds_dwordx4 v148, s[2:3]
	s_barrier
	s_waitcnt lgkmcnt(0)
	v_mfma_f32_16x16x32_bf16 v[76:79], v[24:27], v[154:157], 0
	v_mfma_f32_16x16x32_bf16 v[72:75], v[32:35], v[154:157], 0
	v_mfma_f32_16x16x32_bf16 v[60:63], v[24:27], v[180:183], 0
	v_mfma_f32_16x16x32_bf16 v[56:59], v[32:35], v[180:183], 0
	v_mfma_f32_16x16x32_bf16 v[44:47], v[24:27], v[188:191], 0
	v_mfma_f32_16x16x32_bf16 v[40:43], v[32:35], v[188:191], 0
	v_mfma_f32_16x16x32_bf16 v[12:15], v[24:27], v[196:199], 0
	v_mfma_f32_16x16x32_bf16 v[8:11], v[32:35], v[196:199], 0
	v_mfma_f32_16x16x32_bf16 v[76:79], v[28:31], v[158:161], v[76:79]
	v_mfma_f32_16x16x32_bf16 v[72:75], v[36:39], v[158:161], v[72:75]
	v_mfma_f32_16x16x32_bf16 v[60:63], v[28:31], v[184:187], v[60:63]
	v_mfma_f32_16x16x32_bf16 v[56:59], v[36:39], v[184:187], v[56:59]
	v_mfma_f32_16x16x32_bf16 v[44:47], v[28:31], v[192:195], v[44:47]
	v_mfma_f32_16x16x32_bf16 v[40:43], v[36:39], v[192:195], v[40:43]
	v_mfma_f32_16x16x32_bf16 v[12:15], v[28:31], v[200:203], v[12:15]
	v_mfma_f32_16x16x32_bf16 v[8:11], v[36:39], v[200:203], v[8:11]
	s_barrier
	s_mov_b32 m0, s37
	s_nop 0
	global_load_lds_dwordx4 v144, s[22:23]
	s_mov_b32 m0, s38
	s_nop 0
	global_load_lds_dwordx4 v146, s[22:23]
	s_add_i32 m0, s36, 0x14000
	s_add_u32 s54, s2, 0x40000
	s_addc_u32 s55, s3, 0
	global_load_lds_dwordx4 v168, s[54:55]
	s_add_i32 m0, s36, 0x16000
	s_add_u32 s22, s22, 0x40000
	s_addc_u32 s23, s23, 0
	global_load_lds_dwordx4 v148, s[54:55]
	s_waitcnt vmcnt(6)
	s_barrier
	v_mfma_f32_16x16x32_bf16 v[20:23], v[204:207], v[188:191], 0
	v_mfma_f32_16x16x32_bf16 v[16:19], v[212:215], v[188:191], 0
	v_mfma_f32_16x16x32_bf16 v[4:7], v[204:207], v[196:199], 0
	v_mfma_f32_16x16x32_bf16 v[0:3], v[212:215], v[196:199], 0
	v_mfma_f32_16x16x32_bf16 v[24:27], v[204:207], v[154:157], 0
	v_mfma_f32_16x16x32_bf16 v[28:31], v[212:215], v[154:157], 0
	v_mfma_f32_16x16x32_bf16 v[32:35], v[204:207], v[180:183], 0
	v_mfma_f32_16x16x32_bf16 v[36:39], v[212:215], v[180:183], 0
	v_mfma_f32_16x16x32_bf16 v[20:23], v[208:211], v[192:195], v[20:23]
	v_mfma_f32_16x16x32_bf16 v[16:19], v[216:219], v[192:195], v[16:19]
	v_mfma_f32_16x16x32_bf16 v[4:7], v[208:211], v[200:203], v[4:7]
	v_mfma_f32_16x16x32_bf16 v[0:3], v[216:219], v[200:203], v[0:3]
	v_mfma_f32_16x16x32_bf16 v[24:27], v[208:211], v[158:161], v[24:27]
	v_mfma_f32_16x16x32_bf16 v[28:31], v[216:219], v[158:161], v[28:31]
	v_mfma_f32_16x16x32_bf16 v[32:35], v[208:211], v[184:187], v[32:35]
	v_mfma_f32_16x16x32_bf16 v[36:39], v[216:219], v[184:187], v[36:39]
	s_barrier
	ds_read_b128 v[48:51], v164 offset:32768
	ds_read_b128 v[52:55], v164 offset:33792
	ds_read_b128 v[64:67], v164 offset:34816
	ds_read_b128 v[68:71], v164 offset:35840
	ds_read_b128 v[154:157], v165 offset:32768
	ds_read_b128 v[158:161], v165 offset:33792
	ds_read_b128 v[180:183], v165 offset:34816
	ds_read_b128 v[184:187], v165 offset:35840
	ds_read_b128 v[188:191], v165 offset:36864
	ds_read_b128 v[192:195], v165 offset:37888
	ds_read_b128 v[196:199], v165 offset:38912
	ds_read_b128 v[200:203], v165 offset:39936
	s_barrier
	s_waitcnt lgkmcnt(0)
	v_mfma_f32_16x16x32_bf16 v[140:143], v[48:51], v[154:157], v[140:143]
	v_mfma_f32_16x16x32_bf16 v[136:139], v[64:67], v[154:157], v[136:139]
	v_mfma_f32_16x16x32_bf16 v[124:127], v[48:51], v[180:183], v[124:127]
	v_mfma_f32_16x16x32_bf16 v[120:123], v[64:67], v[180:183], v[120:123]
	v_mfma_f32_16x16x32_bf16 v[108:111], v[48:51], v[188:191], v[108:111]
	v_mfma_f32_16x16x32_bf16 v[104:107], v[64:67], v[188:191], v[104:107]
	v_mfma_f32_16x16x32_bf16 v[92:95], v[48:51], v[196:199], v[92:95]
	v_mfma_f32_16x16x32_bf16 v[88:91], v[64:67], v[196:199], v[88:91]
	v_mfma_f32_16x16x32_bf16 v[140:143], v[52:55], v[158:161], v[140:143]
	v_mfma_f32_16x16x32_bf16 v[136:139], v[68:71], v[158:161], v[136:139]
	v_mfma_f32_16x16x32_bf16 v[124:127], v[52:55], v[184:187], v[124:127]
	v_mfma_f32_16x16x32_bf16 v[120:123], v[68:71], v[184:187], v[120:123]
	v_mfma_f32_16x16x32_bf16 v[108:111], v[52:55], v[192:195], v[108:111]
	v_mfma_f32_16x16x32_bf16 v[104:107], v[68:71], v[192:195], v[104:107]
	v_mfma_f32_16x16x32_bf16 v[92:95], v[52:55], v[200:203], v[92:95]
	v_mfma_f32_16x16x32_bf16 v[88:91], v[68:71], v[200:203], v[88:91]
	s_barrier
	s_mov_b32 m0, s39
	ds_read_b128 v[204:207], v164 offset:49152
	ds_read_b128 v[208:211], v164 offset:50176
	ds_read_b128 v[212:215], v164 offset:51200
	global_load_lds_dwordx4 v144, s[22:23]
	s_mov_b32 m0, s40
	ds_read_b128 v[216:219], v164 offset:52224
	global_load_lds_dwordx4 v146, s[22:23]
	s_barrier
	s_waitcnt lgkmcnt(0)
	v_mfma_f32_16x16x32_bf16 v[132:135], v[204:207], v[154:157], v[132:135]
	v_mfma_f32_16x16x32_bf16 v[128:131], v[212:215], v[154:157], v[128:131]
	v_mfma_f32_16x16x32_bf16 v[116:119], v[204:207], v[180:183], v[116:119]
	v_mfma_f32_16x16x32_bf16 v[112:115], v[212:215], v[180:183], v[112:115]
	v_mfma_f32_16x16x32_bf16 v[100:103], v[204:207], v[188:191], v[100:103]
	v_mfma_f32_16x16x32_bf16 v[96:99], v[212:215], v[188:191], v[96:99]
	v_mfma_f32_16x16x32_bf16 v[84:87], v[204:207], v[196:199], v[84:87]
	v_mfma_f32_16x16x32_bf16 v[80:83], v[212:215], v[196:199], v[80:83]
	v_mfma_f32_16x16x32_bf16 v[132:135], v[208:211], v[158:161], v[132:135]
	v_mfma_f32_16x16x32_bf16 v[128:131], v[216:219], v[158:161], v[128:131]
	v_mfma_f32_16x16x32_bf16 v[116:119], v[208:211], v[184:187], v[116:119]
	v_mfma_f32_16x16x32_bf16 v[112:115], v[216:219], v[184:187], v[112:115]
	v_mfma_f32_16x16x32_bf16 v[100:103], v[208:211], v[192:195], v[100:103]
	v_mfma_f32_16x16x32_bf16 v[96:99], v[216:219], v[192:195], v[96:99]
	v_mfma_f32_16x16x32_bf16 v[84:87], v[208:211], v[200:203], v[84:87]
	v_mfma_f32_16x16x32_bf16 v[80:83], v[216:219], v[200:203], v[80:83]
	s_barrier
	ds_read_b128 v[154:157], v165 offset:49152
	ds_read_b128 v[158:161], v165 offset:50176
	ds_read_b128 v[180:183], v165 offset:51200
	ds_read_b128 v[184:187], v165 offset:52224
	ds_read_b128 v[188:191], v165 offset:53248
	ds_read_b128 v[192:195], v165 offset:54272
	ds_read_b128 v[196:199], v165 offset:55296
	ds_read_b128 v[200:203], v165 offset:56320
	s_add_i32 m0, s36, 0x18000
	s_nop 0
	global_load_lds_dwordx4 v168, s[98:99]
	s_add_i32 m0, s36, 0x1a000
	s_nop 0
	global_load_lds_dwordx4 v148, s[98:99]
	s_barrier
	s_waitcnt lgkmcnt(0)
	v_mfma_f32_16x16x32_bf16 v[76:79], v[48:51], v[154:157], v[76:79]
	v_mfma_f32_16x16x32_bf16 v[72:75], v[64:67], v[154:157], v[72:75]
	v_mfma_f32_16x16x32_bf16 v[60:63], v[48:51], v[180:183], v[60:63]
	v_mfma_f32_16x16x32_bf16 v[56:59], v[64:67], v[180:183], v[56:59]
	v_mfma_f32_16x16x32_bf16 v[44:47], v[48:51], v[188:191], v[44:47]
	v_mfma_f32_16x16x32_bf16 v[40:43], v[64:67], v[188:191], v[40:43]
	v_mfma_f32_16x16x32_bf16 v[12:15], v[48:51], v[196:199], v[12:15]
	v_mfma_f32_16x16x32_bf16 v[8:11], v[64:67], v[196:199], v[8:11]
	v_mfma_f32_16x16x32_bf16 v[76:79], v[52:55], v[158:161], v[76:79]
	v_mfma_f32_16x16x32_bf16 v[72:75], v[68:71], v[158:161], v[72:75]
	v_mfma_f32_16x16x32_bf16 v[60:63], v[52:55], v[184:187], v[60:63]
	v_mfma_f32_16x16x32_bf16 v[56:59], v[68:71], v[184:187], v[56:59]
	v_mfma_f32_16x16x32_bf16 v[44:47], v[52:55], v[192:195], v[44:47]
	v_mfma_f32_16x16x32_bf16 v[40:43], v[68:71], v[192:195], v[40:43]
	v_mfma_f32_16x16x32_bf16 v[12:15], v[52:55], v[200:203], v[12:15]
	v_mfma_f32_16x16x32_bf16 v[8:11], v[68:71], v[200:203], v[8:11]
	s_barrier
	s_mov_b32 m0, s45
	s_nop 0
	global_load_lds_dwordx4 v144, s[100:101]
	s_mov_b32 m0, s46
	s_nop 0
	global_load_lds_dwordx4 v146, s[100:101]
	s_add_i32 m0, s36, 0x1c000
	s_add_u32 s2, s2, 0x40080
	s_addc_u32 s3, s3, 0
	global_load_lds_dwordx4 v168, s[2:3]
	s_add_i32 m0, s36, 0x1e000
	s_add_i32 s52, s52, 2
	global_load_lds_dwordx4 v148, s[2:3]
	s_waitcnt vmcnt(6)
	s_barrier
	v_mfma_f32_16x16x32_bf16 v[24:27], v[204:207], v[154:157], v[24:27]
	v_mfma_f32_16x16x32_bf16 v[68:71], v[208:211], v[158:161], v[24:27]
	v_mfma_f32_16x16x32_bf16 v[24:27], v[212:215], v[154:157], v[28:31]
	v_mfma_f32_16x16x32_bf16 v[64:67], v[216:219], v[158:161], v[24:27]
	v_mfma_f32_16x16x32_bf16 v[24:27], v[204:207], v[180:183], v[32:35]
	v_mfma_f32_16x16x32_bf16 v[52:55], v[208:211], v[184:187], v[24:27]
	v_mfma_f32_16x16x32_bf16 v[24:27], v[212:215], v[180:183], v[36:39]
	v_mfma_f32_16x16x32_bf16 v[20:23], v[204:207], v[188:191], v[20:23]
	v_mfma_f32_16x16x32_bf16 v[16:19], v[212:215], v[188:191], v[16:19]
	v_mfma_f32_16x16x32_bf16 v[4:7], v[204:207], v[196:199], v[4:7]
	v_mfma_f32_16x16x32_bf16 v[0:3], v[212:215], v[196:199], v[0:3]
	v_mfma_f32_16x16x32_bf16 v[48:51], v[216:219], v[184:187], v[24:27]
	v_mfma_f32_16x16x32_bf16 v[20:23], v[208:211], v[192:195], v[20:23]
	v_mfma_f32_16x16x32_bf16 v[16:19], v[216:219], v[192:195], v[16:19]
	v_mfma_f32_16x16x32_bf16 v[4:7], v[208:211], v[200:203], v[4:7]
	v_mfma_f32_16x16x32_bf16 v[0:3], v[216:219], v[200:203], v[0:3]
	s_add_u32 s20, s20, 0x100
	s_addc_u32 s21, s21, 0
	s_add_u32 s50, s50, 0x100
	s_addc_u32 s51, s51, 0
	s_cmp_gt_u32 s52, 13
	s_barrier
.LBB0_123:
	s_add_u32 s2, s20, 0xfffc0080
	s_addc_u32 s3, s21, -1
	ds_read_b128 v[24:27], v164
	ds_read_b128 v[28:31], v164 offset:1024
	ds_read_b128 v[32:35], v164 offset:2048
	ds_read_b128 v[36:39], v164 offset:3072
	s_cmp_eq_u32 s52, 12
	s_cselect_b32 s23, s7, s3
	s_cselect_b32 s22, s9, s2
	s_cselect_b32 s3, s13, s51
	s_cselect_b32 s2, s15, s50
	ds_read_b128 v[154:157], v165
	ds_read_b128 v[158:161], v165 offset:1024
	ds_read_b128 v[180:183], v165 offset:2048
	ds_read_b128 v[184:187], v165 offset:3072
	ds_read_b128 v[188:191], v165 offset:4096
	ds_read_b128 v[192:195], v165 offset:5120
	ds_read_b128 v[196:199], v165 offset:6144
	ds_read_b128 v[200:203], v165 offset:7168
	s_barrier
	s_waitcnt lgkmcnt(0)
	v_mfma_f32_16x16x32_bf16 v[140:143], v[24:27], v[154:157], v[140:143]
	v_mfma_f32_16x16x32_bf16 v[136:139], v[32:35], v[154:157], v[136:139]
	v_mfma_f32_16x16x32_bf16 v[124:127], v[24:27], v[180:183], v[124:127]
	v_mfma_f32_16x16x32_bf16 v[120:123], v[32:35], v[180:183], v[120:123]
	v_mfma_f32_16x16x32_bf16 v[108:111], v[24:27], v[188:191], v[108:111]
	v_mfma_f32_16x16x32_bf16 v[104:107], v[32:35], v[188:191], v[104:107]
	v_mfma_f32_16x16x32_bf16 v[92:95], v[24:27], v[196:199], v[92:95]
	v_mfma_f32_16x16x32_bf16 v[88:91], v[32:35], v[196:199], v[88:91]
	v_mfma_f32_16x16x32_bf16 v[140:143], v[28:31], v[158:161], v[140:143]
	v_mfma_f32_16x16x32_bf16 v[136:139], v[36:39], v[158:161], v[136:139]
	v_mfma_f32_16x16x32_bf16 v[124:127], v[28:31], v[184:187], v[124:127]
	v_mfma_f32_16x16x32_bf16 v[120:123], v[36:39], v[184:187], v[120:123]
	v_mfma_f32_16x16x32_bf16 v[108:111], v[28:31], v[192:195], v[108:111]
	v_mfma_f32_16x16x32_bf16 v[104:107], v[36:39], v[192:195], v[104:107]
	v_mfma_f32_16x16x32_bf16 v[92:95], v[28:31], v[200:203], v[92:95]
	v_mfma_f32_16x16x32_bf16 v[88:91], v[36:39], v[200:203], v[88:91]
	s_barrier
	s_add_i32 m0, s37, 0xc000
	ds_read_b128 v[204:207], v164 offset:16384
	ds_read_b128 v[208:211], v164 offset:17408
	ds_read_b128 v[212:215], v164 offset:18432
	global_load_lds_dwordx4 v150, s[20:21]
	s_add_i32 m0, s37, 0xe000
	ds_read_b128 v[216:219], v164 offset:19456
	global_load_lds_dwordx4 v152, s[20:21]
	s_add_u32 s98, s2, 0x80
	s_addc_u32 s99, s3, 0
	s_barrier
	s_waitcnt lgkmcnt(0)
	v_mfma_f32_16x16x32_bf16 v[132:135], v[204:207], v[154:157], v[132:135]
	v_mfma_f32_16x16x32_bf16 v[128:131], v[212:215], v[154:157], v[128:131]
	v_mfma_f32_16x16x32_bf16 v[116:119], v[204:207], v[180:183], v[116:119]
	v_mfma_f32_16x16x32_bf16 v[112:115], v[212:215], v[180:183], v[112:115]
	v_mfma_f32_16x16x32_bf16 v[100:103], v[204:207], v[188:191], v[100:103]
	v_mfma_f32_16x16x32_bf16 v[96:99], v[212:215], v[188:191], v[96:99]
	v_mfma_f32_16x16x32_bf16 v[84:87], v[204:207], v[196:199], v[84:87]
	v_mfma_f32_16x16x32_bf16 v[80:83], v[212:215], v[196:199], v[80:83]
	v_mfma_f32_16x16x32_bf16 v[132:135], v[208:211], v[158:161], v[132:135]
	v_mfma_f32_16x16x32_bf16 v[128:131], v[216:219], v[158:161], v[128:131]
	v_mfma_f32_16x16x32_bf16 v[116:119], v[208:211], v[184:187], v[116:119]
	v_mfma_f32_16x16x32_bf16 v[112:115], v[216:219], v[184:187], v[112:115]
	v_mfma_f32_16x16x32_bf16 v[100:103], v[208:211], v[192:195], v[100:103]
	v_mfma_f32_16x16x32_bf16 v[96:99], v[216:219], v[192:195], v[96:99]
	v_mfma_f32_16x16x32_bf16 v[84:87], v[208:211], v[200:203], v[84:87]
	v_mfma_f32_16x16x32_bf16 v[80:83], v[216:219], v[200:203], v[80:83]
	s_add_u32 s100, s22, 0x80
	s_addc_u32 s101, s23, 0
	s_barrier
	ds_read_b128 v[154:157], v165 offset:16384
	ds_read_b128 v[158:161], v165 offset:17408
	ds_read_b128 v[180:183], v165 offset:18432
	ds_read_b128 v[184:187], v165 offset:19456
	ds_read_b128 v[188:191], v165 offset:20480
	ds_read_b128 v[192:195], v165 offset:21504
	ds_read_b128 v[196:199], v165 offset:22528
	ds_read_b128 v[200:203], v165 offset:23552
	s_add_i32 m0, s36, 0x10000
	s_nop 0
	global_load_lds_dwordx4 v168, s[2:3]
	s_add_i32 m0, s36, 0x12000
	s_nop 0
	global_load_lds_dwordx4 v148, s[2:3]
	s_barrier
	s_waitcnt lgkmcnt(0)
	v_mfma_f32_16x16x32_bf16 v[76:79], v[24:27], v[154:157], v[76:79]
	v_mfma_f32_16x16x32_bf16 v[72:75], v[32:35], v[154:157], v[72:75]
	v_mfma_f32_16x16x32_bf16 v[60:63], v[24:27], v[180:183], v[60:63]
	v_mfma_f32_16x16x32_bf16 v[56:59], v[32:35], v[180:183], v[56:59]
	v_mfma_f32_16x16x32_bf16 v[44:47], v[24:27], v[188:191], v[44:47]
	v_mfma_f32_16x16x32_bf16 v[40:43], v[32:35], v[188:191], v[40:43]
	v_mfma_f32_16x16x32_bf16 v[12:15], v[24:27], v[196:199], v[12:15]
	v_mfma_f32_16x16x32_bf16 v[8:11], v[32:35], v[196:199], v[8:11]
	v_mfma_f32_16x16x32_bf16 v[76:79], v[28:31], v[158:161], v[76:79]
	v_mfma_f32_16x16x32_bf16 v[72:75], v[36:39], v[158:161], v[72:75]
	v_mfma_f32_16x16x32_bf16 v[60:63], v[28:31], v[184:187], v[60:63]
	v_mfma_f32_16x16x32_bf16 v[56:59], v[36:39], v[184:187], v[56:59]
	v_mfma_f32_16x16x32_bf16 v[44:47], v[28:31], v[192:195], v[44:47]
	v_mfma_f32_16x16x32_bf16 v[40:43], v[36:39], v[192:195], v[40:43]
	v_mfma_f32_16x16x32_bf16 v[12:15], v[28:31], v[200:203], v[12:15]
	v_mfma_f32_16x16x32_bf16 v[8:11], v[36:39], v[200:203], v[8:11]
	s_barrier
	s_mov_b32 m0, s37
	s_nop 0
	global_load_lds_dwordx4 v144, s[22:23]
	s_mov_b32 m0, s38
	s_nop 0
	global_load_lds_dwordx4 v146, s[22:23]
	s_add_i32 m0, s36, 0x14000
	s_add_u32 s54, s2, 0x40000
	s_addc_u32 s55, s3, 0
	global_load_lds_dwordx4 v168, s[54:55]
	s_add_i32 m0, s36, 0x16000
	s_add_u32 s22, s22, 0x40000
	s_addc_u32 s23, s23, 0
	global_load_lds_dwordx4 v148, s[54:55]
	s_waitcnt vmcnt(6)
	s_barrier
	v_mfma_f32_16x16x32_bf16 v[20:23], v[204:207], v[188:191], v[20:23]
	v_mfma_f32_16x16x32_bf16 v[16:19], v[212:215], v[188:191], v[16:19]
	v_mfma_f32_16x16x32_bf16 v[4:7], v[204:207], v[196:199], v[4:7]
	v_mfma_f32_16x16x32_bf16 v[0:3], v[212:215], v[196:199], v[0:3]
	v_mfma_f32_16x16x32_bf16 v[24:27], v[204:207], v[154:157], v[68:71]
	v_mfma_f32_16x16x32_bf16 v[28:31], v[212:215], v[154:157], v[64:67]
	v_mfma_f32_16x16x32_bf16 v[32:35], v[204:207], v[180:183], v[52:55]
	v_mfma_f32_16x16x32_bf16 v[36:39], v[212:215], v[180:183], v[48:51]
	v_mfma_f32_16x16x32_bf16 v[20:23], v[208:211], v[192:195], v[20:23]
	v_mfma_f32_16x16x32_bf16 v[16:19], v[216:219], v[192:195], v[16:19]
	v_mfma_f32_16x16x32_bf16 v[4:7], v[208:211], v[200:203], v[4:7]
	v_mfma_f32_16x16x32_bf16 v[0:3], v[216:219], v[200:203], v[0:3]
	v_mfma_f32_16x16x32_bf16 v[24:27], v[208:211], v[158:161], v[24:27]
	v_mfma_f32_16x16x32_bf16 v[28:31], v[216:219], v[158:161], v[28:31]
	v_mfma_f32_16x16x32_bf16 v[32:35], v[208:211], v[184:187], v[32:35]
	v_mfma_f32_16x16x32_bf16 v[36:39], v[216:219], v[184:187], v[36:39]
	s_barrier
	ds_read_b128 v[48:51], v164 offset:32768
	ds_read_b128 v[52:55], v164 offset:33792
	ds_read_b128 v[64:67], v164 offset:34816
	ds_read_b128 v[68:71], v164 offset:35840
	ds_read_b128 v[154:157], v165 offset:32768
	ds_read_b128 v[158:161], v165 offset:33792
	ds_read_b128 v[180:183], v165 offset:34816
	ds_read_b128 v[184:187], v165 offset:35840
	ds_read_b128 v[188:191], v165 offset:36864
	ds_read_b128 v[192:195], v165 offset:37888
	ds_read_b128 v[196:199], v165 offset:38912
	ds_read_b128 v[200:203], v165 offset:39936
	s_barrier
	s_waitcnt lgkmcnt(0)
	v_mfma_f32_16x16x32_bf16 v[140:143], v[48:51], v[154:157], v[140:143]
	v_mfma_f32_16x16x32_bf16 v[136:139], v[64:67], v[154:157], v[136:139]
	v_mfma_f32_16x16x32_bf16 v[124:127], v[48:51], v[180:183], v[124:127]
	v_mfma_f32_16x16x32_bf16 v[120:123], v[64:67], v[180:183], v[120:123]
	v_mfma_f32_16x16x32_bf16 v[108:111], v[48:51], v[188:191], v[108:111]
	v_mfma_f32_16x16x32_bf16 v[104:107], v[64:67], v[188:191], v[104:107]
	v_mfma_f32_16x16x32_bf16 v[92:95], v[48:51], v[196:199], v[92:95]
	v_mfma_f32_16x16x32_bf16 v[88:91], v[64:67], v[196:199], v[88:91]
	v_mfma_f32_16x16x32_bf16 v[140:143], v[52:55], v[158:161], v[140:143]
	v_mfma_f32_16x16x32_bf16 v[136:139], v[68:71], v[158:161], v[136:139]
	v_mfma_f32_16x16x32_bf16 v[124:127], v[52:55], v[184:187], v[124:127]
	v_mfma_f32_16x16x32_bf16 v[120:123], v[68:71], v[184:187], v[120:123]
	v_mfma_f32_16x16x32_bf16 v[108:111], v[52:55], v[192:195], v[108:111]
	v_mfma_f32_16x16x32_bf16 v[104:107], v[68:71], v[192:195], v[104:107]
	v_mfma_f32_16x16x32_bf16 v[92:95], v[52:55], v[200:203], v[92:95]
	v_mfma_f32_16x16x32_bf16 v[88:91], v[68:71], v[200:203], v[88:91]
	s_barrier
	s_mov_b32 m0, s39
	ds_read_b128 v[204:207], v164 offset:49152
	ds_read_b128 v[208:211], v164 offset:50176
	ds_read_b128 v[212:215], v164 offset:51200
	global_load_lds_dwordx4 v144, s[22:23]
	s_mov_b32 m0, s40
	ds_read_b128 v[216:219], v164 offset:52224
	global_load_lds_dwordx4 v146, s[22:23]
	s_barrier
	s_waitcnt lgkmcnt(0)
	v_mfma_f32_16x16x32_bf16 v[132:135], v[204:207], v[154:157], v[132:135]
	v_mfma_f32_16x16x32_bf16 v[128:131], v[212:215], v[154:157], v[128:131]
	v_mfma_f32_16x16x32_bf16 v[116:119], v[204:207], v[180:183], v[116:119]
	v_mfma_f32_16x16x32_bf16 v[112:115], v[212:215], v[180:183], v[112:115]
	v_mfma_f32_16x16x32_bf16 v[100:103], v[204:207], v[188:191], v[100:103]
	v_mfma_f32_16x16x32_bf16 v[96:99], v[212:215], v[188:191], v[96:99]
	v_mfma_f32_16x16x32_bf16 v[84:87], v[204:207], v[196:199], v[84:87]
	v_mfma_f32_16x16x32_bf16 v[80:83], v[212:215], v[196:199], v[80:83]
	v_mfma_f32_16x16x32_bf16 v[132:135], v[208:211], v[158:161], v[132:135]
	v_mfma_f32_16x16x32_bf16 v[128:131], v[216:219], v[158:161], v[128:131]
	v_mfma_f32_16x16x32_bf16 v[116:119], v[208:211], v[184:187], v[116:119]
	v_mfma_f32_16x16x32_bf16 v[112:115], v[216:219], v[184:187], v[112:115]
	v_mfma_f32_16x16x32_bf16 v[100:103], v[208:211], v[192:195], v[100:103]
	v_mfma_f32_16x16x32_bf16 v[96:99], v[216:219], v[192:195], v[96:99]
	v_mfma_f32_16x16x32_bf16 v[84:87], v[208:211], v[200:203], v[84:87]
	v_mfma_f32_16x16x32_bf16 v[80:83], v[216:219], v[200:203], v[80:83]
	s_barrier
	ds_read_b128 v[154:157], v165 offset:49152
	ds_read_b128 v[158:161], v165 offset:50176
	ds_read_b128 v[180:183], v165 offset:51200
	ds_read_b128 v[184:187], v165 offset:52224
	ds_read_b128 v[188:191], v165 offset:53248
	ds_read_b128 v[192:195], v165 offset:54272
	ds_read_b128 v[196:199], v165 offset:55296
	ds_read_b128 v[200:203], v165 offset:56320
	s_add_i32 m0, s36, 0x18000
	s_nop 0
	global_load_lds_dwordx4 v168, s[98:99]
	s_add_i32 m0, s36, 0x1a000
	s_nop 0
	global_load_lds_dwordx4 v148, s[98:99]
	s_barrier
	s_waitcnt lgkmcnt(0)
	v_mfma_f32_16x16x32_bf16 v[76:79], v[48:51], v[154:157], v[76:79]
	v_mfma_f32_16x16x32_bf16 v[72:75], v[64:67], v[154:157], v[72:75]
	v_mfma_f32_16x16x32_bf16 v[60:63], v[48:51], v[180:183], v[60:63]
	v_mfma_f32_16x16x32_bf16 v[56:59], v[64:67], v[180:183], v[56:59]
	v_mfma_f32_16x16x32_bf16 v[44:47], v[48:51], v[188:191], v[44:47]
	v_mfma_f32_16x16x32_bf16 v[40:43], v[64:67], v[188:191], v[40:43]
	v_mfma_f32_16x16x32_bf16 v[12:15], v[48:51], v[196:199], v[12:15]
	v_mfma_f32_16x16x32_bf16 v[8:11], v[64:67], v[196:199], v[8:11]
	v_mfma_f32_16x16x32_bf16 v[76:79], v[52:55], v[158:161], v[76:79]
	v_mfma_f32_16x16x32_bf16 v[72:75], v[68:71], v[158:161], v[72:75]
	v_mfma_f32_16x16x32_bf16 v[60:63], v[52:55], v[184:187], v[60:63]
	v_mfma_f32_16x16x32_bf16 v[56:59], v[68:71], v[184:187], v[56:59]
	v_mfma_f32_16x16x32_bf16 v[44:47], v[52:55], v[192:195], v[44:47]
	v_mfma_f32_16x16x32_bf16 v[40:43], v[68:71], v[192:195], v[40:43]
	v_mfma_f32_16x16x32_bf16 v[12:15], v[52:55], v[200:203], v[12:15]
	v_mfma_f32_16x16x32_bf16 v[8:11], v[68:71], v[200:203], v[8:11]
	s_barrier
	s_mov_b32 m0, s45
	s_nop 0
	global_load_lds_dwordx4 v144, s[100:101]
	s_mov_b32 m0, s46
	s_nop 0
	global_load_lds_dwordx4 v146, s[100:101]
	s_add_i32 m0, s36, 0x1c000
	s_add_u32 s2, s2, 0x40080
	s_addc_u32 s3, s3, 0
	global_load_lds_dwordx4 v168, s[2:3]
	s_add_i32 m0, s36, 0x1e000
	s_add_i32 s52, s52, 2
	global_load_lds_dwordx4 v148, s[2:3]
	s_waitcnt vmcnt(6)
	s_barrier
	v_mfma_f32_16x16x32_bf16 v[24:27], v[204:207], v[154:157], v[24:27]
	v_mfma_f32_16x16x32_bf16 v[68:71], v[208:211], v[158:161], v[24:27]
	v_mfma_f32_16x16x32_bf16 v[24:27], v[212:215], v[154:157], v[28:31]
	v_mfma_f32_16x16x32_bf16 v[64:67], v[216:219], v[158:161], v[24:27]
	v_mfma_f32_16x16x32_bf16 v[24:27], v[204:207], v[180:183], v[32:35]
	v_mfma_f32_16x16x32_bf16 v[52:55], v[208:211], v[184:187], v[24:27]
	v_mfma_f32_16x16x32_bf16 v[24:27], v[212:215], v[180:183], v[36:39]
	v_mfma_f32_16x16x32_bf16 v[20:23], v[204:207], v[188:191], v[20:23]
	v_mfma_f32_16x16x32_bf16 v[16:19], v[212:215], v[188:191], v[16:19]
	v_mfma_f32_16x16x32_bf16 v[4:7], v[204:207], v[196:199], v[4:7]
	v_mfma_f32_16x16x32_bf16 v[0:3], v[212:215], v[196:199], v[0:3]
	v_mfma_f32_16x16x32_bf16 v[48:51], v[216:219], v[184:187], v[24:27]
	v_mfma_f32_16x16x32_bf16 v[20:23], v[208:211], v[192:195], v[20:23]
	v_mfma_f32_16x16x32_bf16 v[16:19], v[216:219], v[192:195], v[16:19]
	v_mfma_f32_16x16x32_bf16 v[4:7], v[208:211], v[200:203], v[4:7]
	v_mfma_f32_16x16x32_bf16 v[0:3], v[216:219], v[200:203], v[0:3]
	s_add_u32 s20, s20, 0x100
	s_addc_u32 s21, s21, 0
	s_add_u32 s50, s50, 0x100
	s_addc_u32 s51, s51, 0
	s_cmp_gt_u32 s52, 13
	s_barrier
	s_cbranch_scc0 .LBB0_123
	s_lshl_b32 s2, s6, 8
	s_add_i32 s3, s2, s43
	s_lshl_b32 s2, s8, 8
	s_cmp_gt_i32 s8, 3
	s_cselect_b64 s[20:21], -1, 0
	s_and_b64 s[22:23], s[20:21], exec
	s_mov_b32 s7, 0x8982000
	s_cselect_b32 s7, s7, 0x7182000
	s_add_u32 s22, s26, s7
	s_addc_u32 s23, s25, 0
	s_add_i32 s7, s6, -16
	v_mov_b32_e32 v160, v163
	v_mov_b32_e32 v24, v162
	s_lshr_b32 s7, s7, 3
	s_add_i32 s96, s7, 1
	v_add_u32_e32 v154, s3, v24
	s_lshl_b64 s[50:51], s[96:97], 11
	v_ashrrev_i32_e32 v155, 31, v154
	s_cmp_gt_i32 s6, 15
	v_lshl_add_u64 v[156:157], v[154:155], 2, s[10:11]
	s_cselect_b32 s7, s51, 0
	s_cselect_b32 s6, s50, 0
	global_load_dword v166, v[156:157], off
	global_load_dword v191, v[156:157], off offset:64
	global_load_dword v192, v[156:157], off offset:128
	global_load_dword v193, v[156:157], off offset:192
	global_load_dword v194, v[156:157], off offset:512
	global_load_dword v195, v[156:157], off offset:576
	global_load_dword v196, v[156:157], off offset:640
	global_load_dword v197, v[156:157], off offset:704
	s_lshl_b64 s[6:7], s[6:7], 2
	s_add_u32 s9, s41, s6
	s_addc_u32 s13, s42, s7
	s_ashr_i32 s3, s2, 31
	s_lshl_b64 s[6:7], s[2:3], 2
	s_add_u32 s3, s9, s6
	s_addc_u32 s7, s13, s7
	v_lshlrev_b32_e32 v158, 3, v160
	s_add_u32 s6, s3, s49
	s_addc_u32 s7, s7, 0
	v_ashrrev_i32_e32 v159, 31, v158
	v_lshl_add_u64 v[24:25], v[158:159], 2, s[6:7]
	global_load_dwordx4 v[36:39], v[24:25], off
	global_load_dwordx4 v[32:35], v[24:25], off offset:16
	global_load_dwordx4 v[28:31], v[24:25], off offset:512
	s_nop 0
	global_load_dwordx4 v[24:27], v[24:25], off offset:528
	s_and_b32 s2, s2, 0x300
	s_or_b32 s2, s2, s44
	v_add_u32_e32 v158, s2, v158
	v_cmp_eq_u32_e64 s[6:7], 0, v160
	v_lshlrev_b64 v[160:161], 11, v[154:155]
	s_cmp_lt_i32 s8, 4
	s_waitcnt vmcnt(0)
	v_ashrrev_i32_e32 v159, 31, v158
	v_lshl_add_u64 v[158:159], v[158:159], 1, s[22:23]
	v_lshl_add_u64 v[160:161], v[158:159], 0, v[160:161]
	v_lshl_add_u64 v[156:157], v[154:155], 2, s[0:1]
	s_and_b64 s[6:7], s[6:7], s[20:21]
	s_mov_b64 s[2:3], 0x8000
	s_mov_b64 s[50:51], 0x28000
	v_mov_b32_e32 v180, 0xc0135761
	v_mov_b32_e32 v181, 0xc0135761
	v_mov_b32_e32 v182, 0xbdd2d3e7
	v_mov_b32_e32 v183, 0xbdd2d3e7
	v_fmamk_f32 v166, v166, 0x3a800000, v225
	v_fmamk_f32 v190, v191, 0x3a800000, v225
	v_fmamk_f32 v192, v192, 0x3a800000, v225
	v_fmamk_f32 v188, v193, 0x3a800000, v225
	v_fmamk_f32 v194, v194, 0x3a800000, v225
	v_fmamk_f32 v186, v195, 0x3a800000, v225
	v_fmamk_f32 v196, v196, 0x3a800000, v225
	v_fmamk_f32 v184, v197, 0x3a800000, v225
	v_rsq_f32_e32 v166, v166
	v_rsq_f32_e32 v190, v190
	v_rsq_f32_e32 v192, v192
	v_rsq_f32_e32 v188, v188
	v_rsq_f32_e32 v194, v194
	v_rsq_f32_e32 v186, v186
	v_rsq_f32_e32 v196, v196
	v_rsq_f32_e32 v184, v184
	v_pk_fma_f32 v[140:141], v[140:141], v[166:167], v[36:37] op_sel_hi:[1,0,1]
	v_pk_fma_f32 v[142:143], v[142:143], v[166:167], v[38:39] op_sel_hi:[1,0,1]
	v_pk_fma_f32 v[136:137], v[136:137], v[166:167], v[32:33] op_sel_hi:[1,0,1]
	v_pk_fma_f32 v[138:139], v[138:139], v[166:167], v[34:35] op_sel_hi:[1,0,1]
	v_pk_fma_f32 v[132:133], v[132:133], v[166:167], v[28:29] op_sel_hi:[1,0,1]
	v_pk_fma_f32 v[134:135], v[134:135], v[166:167], v[30:31] op_sel_hi:[1,0,1]
	v_pk_fma_f32 v[128:129], v[128:129], v[166:167], v[24:25] op_sel_hi:[1,0,1]
	v_pk_fma_f32 v[130:131], v[130:131], v[166:167], v[26:27] op_sel_hi:[1,0,1]
	v_pk_fma_f32 v[124:125], v[124:125], v[190:191], v[36:37] op_sel_hi:[1,0,1]
	v_pk_fma_f32 v[126:127], v[126:127], v[190:191], v[38:39] op_sel_hi:[1,0,1]
	v_pk_fma_f32 v[120:121], v[120:121], v[190:191], v[32:33] op_sel_hi:[1,0,1]
	v_pk_fma_f32 v[122:123], v[122:123], v[190:191], v[34:35] op_sel_hi:[1,0,1]
	v_pk_fma_f32 v[116:117], v[116:117], v[190:191], v[28:29] op_sel_hi:[1,0,1]
	v_pk_fma_f32 v[118:119], v[118:119], v[190:191], v[30:31] op_sel_hi:[1,0,1]
	v_pk_fma_f32 v[112:113], v[112:113], v[190:191], v[24:25] op_sel_hi:[1,0,1]
	v_pk_fma_f32 v[114:115], v[114:115], v[190:191], v[26:27] op_sel_hi:[1,0,1]
	v_pk_fma_f32 v[108:109], v[108:109], v[192:193], v[36:37] op_sel_hi:[1,0,1]
	v_pk_fma_f32 v[110:111], v[110:111], v[192:193], v[38:39] op_sel_hi:[1,0,1]
	v_pk_fma_f32 v[104:105], v[104:105], v[192:193], v[32:33] op_sel_hi:[1,0,1]
	v_pk_fma_f32 v[106:107], v[106:107], v[192:193], v[34:35] op_sel_hi:[1,0,1]
	v_pk_fma_f32 v[100:101], v[100:101], v[192:193], v[28:29] op_sel_hi:[1,0,1]
	v_pk_fma_f32 v[102:103], v[102:103], v[192:193], v[30:31] op_sel_hi:[1,0,1]
	v_pk_fma_f32 v[96:97], v[96:97], v[192:193], v[24:25] op_sel_hi:[1,0,1]
	v_pk_fma_f32 v[98:99], v[98:99], v[192:193], v[26:27] op_sel_hi:[1,0,1]
	v_pk_fma_f32 v[92:93], v[92:93], v[188:189], v[36:37] op_sel_hi:[1,0,1]
	v_pk_fma_f32 v[94:95], v[94:95], v[188:189], v[38:39] op_sel_hi:[1,0,1]
	v_pk_fma_f32 v[88:89], v[88:89], v[188:189], v[32:33] op_sel_hi:[1,0,1]
	v_pk_fma_f32 v[90:91], v[90:91], v[188:189], v[34:35] op_sel_hi:[1,0,1]
	v_pk_fma_f32 v[84:85], v[84:85], v[188:189], v[28:29] op_sel_hi:[1,0,1]
	v_pk_fma_f32 v[86:87], v[86:87], v[188:189], v[30:31] op_sel_hi:[1,0,1]
	v_pk_fma_f32 v[80:81], v[80:81], v[188:189], v[24:25] op_sel_hi:[1,0,1]
	v_pk_fma_f32 v[82:83], v[82:83], v[188:189], v[26:27] op_sel_hi:[1,0,1]
	v_pk_fma_f32 v[76:77], v[76:77], v[194:195], v[36:37] op_sel_hi:[1,0,1]
	v_pk_fma_f32 v[78:79], v[78:79], v[194:195], v[38:39] op_sel_hi:[1,0,1]
	v_pk_fma_f32 v[72:73], v[72:73], v[194:195], v[32:33] op_sel_hi:[1,0,1]
	v_pk_fma_f32 v[74:75], v[74:75], v[194:195], v[34:35] op_sel_hi:[1,0,1]
	v_pk_fma_f32 v[68:69], v[68:69], v[194:195], v[28:29] op_sel_hi:[1,0,1]
	v_pk_fma_f32 v[70:71], v[70:71], v[194:195], v[30:31] op_sel_hi:[1,0,1]
	v_pk_fma_f32 v[64:65], v[64:65], v[194:195], v[24:25] op_sel_hi:[1,0,1]
	v_pk_fma_f32 v[66:67], v[66:67], v[194:195], v[26:27] op_sel_hi:[1,0,1]
	v_pk_fma_f32 v[60:61], v[60:61], v[186:187], v[36:37] op_sel_hi:[1,0,1]
	v_pk_fma_f32 v[62:63], v[62:63], v[186:187], v[38:39] op_sel_hi:[1,0,1]
	v_pk_fma_f32 v[56:57], v[56:57], v[186:187], v[32:33] op_sel_hi:[1,0,1]
	v_pk_fma_f32 v[58:59], v[58:59], v[186:187], v[34:35] op_sel_hi:[1,0,1]
	v_pk_fma_f32 v[52:53], v[52:53], v[186:187], v[28:29] op_sel_hi:[1,0,1]
	v_pk_fma_f32 v[54:55], v[54:55], v[186:187], v[30:31] op_sel_hi:[1,0,1]
	v_pk_fma_f32 v[48:49], v[48:49], v[186:187], v[24:25] op_sel_hi:[1,0,1]
	v_pk_fma_f32 v[50:51], v[50:51], v[186:187], v[26:27] op_sel_hi:[1,0,1]
	v_pk_fma_f32 v[44:45], v[44:45], v[196:197], v[36:37] op_sel_hi:[1,0,1]
	v_pk_fma_f32 v[46:47], v[46:47], v[196:197], v[38:39] op_sel_hi:[1,0,1]
	v_pk_fma_f32 v[40:41], v[40:41], v[196:197], v[32:33] op_sel_hi:[1,0,1]
	v_pk_fma_f32 v[42:43], v[42:43], v[196:197], v[34:35] op_sel_hi:[1,0,1]
	v_pk_fma_f32 v[20:21], v[20:21], v[196:197], v[28:29] op_sel_hi:[1,0,1]
	v_pk_fma_f32 v[22:23], v[22:23], v[196:197], v[30:31] op_sel_hi:[1,0,1]
	v_pk_fma_f32 v[16:17], v[16:17], v[196:197], v[24:25] op_sel_hi:[1,0,1]
	v_pk_fma_f32 v[18:19], v[18:19], v[196:197], v[26:27] op_sel_hi:[1,0,1]
	v_pk_fma_f32 v[12:13], v[12:13], v[184:185], v[36:37] op_sel_hi:[1,0,1]
	v_pk_fma_f32 v[14:15], v[14:15], v[184:185], v[38:39] op_sel_hi:[1,0,1]
	v_pk_fma_f32 v[8:9], v[8:9], v[184:185], v[32:33] op_sel_hi:[1,0,1]
	v_pk_fma_f32 v[10:11], v[10:11], v[184:185], v[34:35] op_sel_hi:[1,0,1]
	v_pk_fma_f32 v[4:5], v[4:5], v[184:185], v[28:29] op_sel_hi:[1,0,1]
	v_pk_fma_f32 v[6:7], v[6:7], v[184:185], v[30:31] op_sel_hi:[1,0,1]
	v_pk_fma_f32 v[0:1], v[0:1], v[184:185], v[24:25] op_sel_hi:[1,0,1]
	v_pk_fma_f32 v[2:3], v[2:3], v[184:185], v[26:27] op_sel_hi:[1,0,1]
	v_pk_mul_f32 v[24:25], v[140:141], v[140:141]
	v_pk_mul_f32 v[26:27], v[142:143], v[142:143]
	v_pk_mul_f32 v[28:29], v[136:137], v[136:137]
	v_pk_mul_f32 v[30:31], v[138:139], v[138:139]
	v_pk_mul_f32 v[32:33], v[132:133], v[132:133]
	v_pk_mul_f32 v[34:35], v[134:135], v[134:135]
	v_pk_mul_f32 v[36:37], v[128:129], v[128:129]
	v_pk_mul_f32 v[38:39], v[130:131], v[130:131]
	v_pk_fma_f32 v[24:25], v[24:25], v[182:183], v[180:181]
	v_pk_fma_f32 v[26:27], v[26:27], v[182:183], v[180:181]
	v_pk_fma_f32 v[28:29], v[28:29], v[182:183], v[180:181]
	v_pk_fma_f32 v[30:31], v[30:31], v[182:183], v[180:181]
	v_pk_fma_f32 v[32:33], v[32:33], v[182:183], v[180:181]
	v_pk_fma_f32 v[34:35], v[34:35], v[182:183], v[180:181]
	v_pk_fma_f32 v[36:37], v[36:37], v[182:183], v[180:181]
	v_pk_fma_f32 v[38:39], v[38:39], v[182:183], v[180:181]
	v_pk_mul_f32 v[24:25], v[24:25], v[140:141]
	v_pk_mul_f32 v[26:27], v[26:27], v[142:143]
	v_pk_mul_f32 v[28:29], v[28:29], v[136:137]
	v_pk_mul_f32 v[30:31], v[30:31], v[138:139]
	v_pk_mul_f32 v[32:33], v[32:33], v[132:133]
	v_pk_mul_f32 v[34:35], v[34:35], v[134:135]
	v_pk_mul_f32 v[36:37], v[36:37], v[128:129]
	v_pk_mul_f32 v[38:39], v[38:39], v[130:131]
	v_exp_f32_e32 v24, v24
	v_exp_f32_e32 v25, v25
	v_exp_f32_e32 v26, v26
	v_exp_f32_e32 v27, v27
	v_exp_f32_e32 v28, v28
	v_exp_f32_e32 v29, v29
	v_exp_f32_e32 v30, v30
	v_exp_f32_e32 v31, v31
	v_exp_f32_e32 v32, v32
	v_exp_f32_e32 v33, v33
	v_exp_f32_e32 v34, v34
	v_exp_f32_e32 v35, v35
	v_exp_f32_e32 v36, v36
	v_exp_f32_e32 v37, v37
	v_exp_f32_e32 v38, v38
	v_exp_f32_e32 v39, v39
	v_pk_add_f32 v[24:25], v[24:25], 1.0 op_sel_hi:[1,0]
	v_pk_add_f32 v[26:27], v[26:27], 1.0 op_sel_hi:[1,0]
	v_pk_add_f32 v[28:29], v[28:29], 1.0 op_sel_hi:[1,0]
	v_pk_add_f32 v[30:31], v[30:31], 1.0 op_sel_hi:[1,0]
	v_pk_add_f32 v[32:33], v[32:33], 1.0 op_sel_hi:[1,0]
	v_pk_add_f32 v[34:35], v[34:35], 1.0 op_sel_hi:[1,0]
	v_pk_add_f32 v[36:37], v[36:37], 1.0 op_sel_hi:[1,0]
	v_pk_add_f32 v[38:39], v[38:39], 1.0 op_sel_hi:[1,0]
	v_rcp_f32_e32 v24, v24
	v_rcp_f32_e32 v25, v25
	v_rcp_f32_e32 v26, v26
	v_rcp_f32_e32 v27, v27
	v_rcp_f32_e32 v28, v28
	v_rcp_f32_e32 v29, v29
	v_rcp_f32_e32 v30, v30
	v_rcp_f32_e32 v31, v31
	v_rcp_f32_e32 v32, v32
	v_rcp_f32_e32 v33, v33
	v_rcp_f32_e32 v34, v34
	v_rcp_f32_e32 v35, v35
	v_rcp_f32_e32 v36, v36
	v_rcp_f32_e32 v37, v37
	v_rcp_f32_e32 v38, v38
	v_rcp_f32_e32 v39, v39
	v_pk_mul_f32 v[140:141], v[140:141], v[24:25]
	v_pk_mul_f32 v[142:143], v[142:143], v[26:27]
	v_pk_mul_f32 v[136:137], v[136:137], v[28:29]
	v_pk_mul_f32 v[138:139], v[138:139], v[30:31]
	v_pk_mul_f32 v[132:133], v[132:133], v[32:33]
	v_pk_mul_f32 v[134:135], v[134:135], v[34:35]
	v_pk_mul_f32 v[128:129], v[128:129], v[36:37]
	v_pk_mul_f32 v[130:131], v[130:131], v[38:39]
	v_cvt_pk_bf16_f32 v24, v140, v141
	v_cvt_pk_bf16_f32 v25, v142, v143
	v_cvt_pk_bf16_f32 v26, v136, v137
	v_cvt_pk_bf16_f32 v27, v138, v139
	v_cvt_pk_bf16_f32 v28, v132, v133
	v_cvt_pk_bf16_f32 v29, v134, v135
	v_cvt_pk_bf16_f32 v30, v128, v129
	v_cvt_pk_bf16_f32 v31, v130, v131
	global_store_dwordx4 v[160:161], v[24:27], off
	global_store_dwordx4 v[160:161], v[28:31], off offset:256
	s_and_b64 vcc, exec, s[20:21]
	s_cbranch_vccz .Lio_skip_0
	v_pk_mul_f32 v[32:33], v[140:141], v[140:141]
	v_pk_fma_f32 v[32:33], v[142:143], v[142:143], v[32:33]
	v_pk_fma_f32 v[32:33], v[136:137], v[136:137], v[32:33]
	v_pk_fma_f32 v[32:33], v[138:139], v[138:139], v[32:33]
	v_pk_fma_f32 v[32:33], v[132:133], v[132:133], v[32:33]
	v_pk_fma_f32 v[32:33], v[134:135], v[134:135], v[32:33]
	v_pk_fma_f32 v[32:33], v[128:129], v[128:129], v[32:33]
	v_pk_fma_f32 v[32:33], v[130:131], v[130:131], v[32:33]
	s_nop 0
	v_add_f32_e32 v32, v32, v33
	v_mov_b32_e32 v33, v32
	s_nop 1
	v_permlane16_swap_b32_e32 v32, v33
	v_add_f32_e32 v32, v32, v33
	v_mov_b32_e32 v33, v32
	s_nop 1
	v_permlane32_swap_b32_e32 v32, v33
	s_and_saveexec_b64 vcc, s[6:7]
	v_add_f32_e32 v32, v32, v33
	global_atomic_add_f32 v[156:157], v32, off
	s_mov_b64 exec, vcc

.Lie_done_b:
.LBB0_354:
	s_ashr_i32 s31, s30, 31
	v_cmp_lt_i64_e32 vcc, s[8:9], v[170:171]
	s_lshl_b64 s[8:9], s[30:31], 19
	s_add_u32 s34, s52, s8
	s_addc_u32 s35, s53, s9
	s_and_b64 s[8:9], vcc, exec
	s_cselect_b32 s1, s35, s7
	s_cselect_b32 s31, s34, s6
	s_ashr_i32 s29, s28, 31
	s_lshl_b64 s[8:9], s[28:29], 19
	s_add_u32 s36, s43, s8
	s_addc_u32 s37, s42, s9
	s_and_b64 s[8:9], vcc, exec
	s_cselect_b32 s29, s37, s3
	s_cselect_b32 s38, s36, s2
	s_add_u32 s6, s6, 0x40080
	s_addc_u32 s7, s7, 0
	s_add_u32 s39, s2, 0x100
	s_addc_u32 s40, s3, 0
	s_mov_b32 s41, -2
	s_add_u32 s2, s6, 0xfffc0080
	s_addc_u32 s3, s7, -1
	ds_read_b128 v[128:131], v208
	ds_read_b128 v[132:135], v208 offset:1024
	ds_read_b128 v[136:139], v208 offset:2048
	ds_read_b128 v[140:143], v208 offset:3072
	s_cmp_eq_u32 s41, 12
	s_cselect_b32 s9, s1, s3
	s_cselect_b32 s8, s31, s2
	s_cselect_b32 s3, s29, s40
	s_cselect_b32 s2, s38, s39
	ds_read_b128 v[144:147], v209
	ds_read_b128 v[148:151], v209 offset:1024
	ds_read_b128 v[152:155], v209 offset:2048
	ds_read_b128 v[156:159], v209 offset:3072
	ds_read_b128 v[180:183], v209 offset:4096
	ds_read_b128 v[184:187], v209 offset:5120
	ds_read_b128 v[188:191], v209 offset:6144
	ds_read_b128 v[192:195], v209 offset:7168
	s_barrier
	s_waitcnt lgkmcnt(0)
	v_mfma_f32_16x16x32_bf16 v[124:127], v[128:131], v[144:147], 0
	v_mfma_f32_16x16x32_bf16 v[120:123], v[136:139], v[144:147], 0
	v_mfma_f32_16x16x32_bf16 v[116:119], v[128:131], v[152:155], 0
	v_mfma_f32_16x16x32_bf16 v[112:115], v[136:139], v[152:155], 0
	v_mfma_f32_16x16x32_bf16 v[100:103], v[128:131], v[180:183], 0
	v_mfma_f32_16x16x32_bf16 v[96:99], v[136:139], v[180:183], 0
	v_mfma_f32_16x16x32_bf16 v[84:87], v[128:131], v[188:191], 0
	v_mfma_f32_16x16x32_bf16 v[80:83], v[136:139], v[188:191], 0
	v_mfma_f32_16x16x32_bf16 v[124:127], v[132:135], v[148:151], v[124:127]
	v_mfma_f32_16x16x32_bf16 v[120:123], v[140:143], v[148:151], v[120:123]
	v_mfma_f32_16x16x32_bf16 v[116:119], v[132:135], v[156:159], v[116:119]
	v_mfma_f32_16x16x32_bf16 v[112:115], v[140:143], v[156:159], v[112:115]
	v_mfma_f32_16x16x32_bf16 v[100:103], v[132:135], v[184:187], v[100:103]
	v_mfma_f32_16x16x32_bf16 v[96:99], v[140:143], v[184:187], v[96:99]
	v_mfma_f32_16x16x32_bf16 v[84:87], v[132:135], v[192:195], v[84:87]
	v_mfma_f32_16x16x32_bf16 v[80:83], v[140:143], v[192:195], v[80:83]
	s_barrier
	s_add_i32 m0, s21, 0xc000
	ds_read_b128 v[196:199], v208 offset:16384
	ds_read_b128 v[200:203], v208 offset:17408
	ds_read_b128 v[210:213], v208 offset:18432
	global_load_lds_dwordx4 v164, s[6:7]
	s_add_i32 m0, s21, 0xe000
	ds_read_b128 v[214:217], v208 offset:19456
	global_load_lds_dwordx4 v166, s[6:7]
	s_add_u32 s98, s2, 0x80
	s_addc_u32 s99, s3, 0
	s_barrier
	s_waitcnt lgkmcnt(0)
	v_mfma_f32_16x16x32_bf16 v[108:111], v[196:199], v[144:147], 0
	v_mfma_f32_16x16x32_bf16 v[104:107], v[210:213], v[144:147], 0
	v_mfma_f32_16x16x32_bf16 v[92:95], v[196:199], v[152:155], 0
	v_mfma_f32_16x16x32_bf16 v[88:91], v[210:213], v[152:155], 0
	v_mfma_f32_16x16x32_bf16 v[76:79], v[196:199], v[180:183], 0
	v_mfma_f32_16x16x32_bf16 v[72:75], v[210:213], v[180:183], 0
	v_mfma_f32_16x16x32_bf16 v[68:71], v[196:199], v[188:191], 0
	v_mfma_f32_16x16x32_bf16 v[64:67], v[210:213], v[188:191], 0
	v_mfma_f32_16x16x32_bf16 v[108:111], v[200:203], v[148:151], v[108:111]
	v_mfma_f32_16x16x32_bf16 v[104:107], v[214:217], v[148:151], v[104:107]
	v_mfma_f32_16x16x32_bf16 v[92:95], v[200:203], v[156:159], v[92:95]
	v_mfma_f32_16x16x32_bf16 v[88:91], v[214:217], v[156:159], v[88:91]
	v_mfma_f32_16x16x32_bf16 v[76:79], v[200:203], v[184:187], v[76:79]
	v_mfma_f32_16x16x32_bf16 v[72:75], v[214:217], v[184:187], v[72:75]
	v_mfma_f32_16x16x32_bf16 v[68:71], v[200:203], v[192:195], v[68:71]
	v_mfma_f32_16x16x32_bf16 v[64:67], v[214:217], v[192:195], v[64:67]
	s_add_u32 s100, s8, 0x80
	s_addc_u32 s101, s9, 0
	s_barrier
	ds_read_b128 v[144:147], v209 offset:16384
	ds_read_b128 v[148:151], v209 offset:17408
	ds_read_b128 v[152:155], v209 offset:18432
	ds_read_b128 v[156:159], v209 offset:19456
	ds_read_b128 v[180:183], v209 offset:20480
	ds_read_b128 v[184:187], v209 offset:21504
	ds_read_b128 v[188:191], v209 offset:22528
	ds_read_b128 v[192:195], v209 offset:23552
	s_add_i32 m0, s54, 0x10000
	s_nop 0
	global_load_lds_dwordx4 v160, s[2:3]
	s_add_i32 m0, s54, 0x12000
	s_nop 0
	global_load_lds_dwordx4 v162, s[2:3]
	s_barrier
	s_waitcnt lgkmcnt(0)
	v_mfma_f32_16x16x32_bf16 v[60:63], v[128:131], v[144:147], 0
	v_mfma_f32_16x16x32_bf16 v[56:59], v[136:139], v[144:147], 0
	v_mfma_f32_16x16x32_bf16 v[52:55], v[128:131], v[152:155], 0
	v_mfma_f32_16x16x32_bf16 v[48:51], v[136:139], v[152:155], 0
	v_mfma_f32_16x16x32_bf16 v[36:39], v[128:131], v[180:183], 0
	v_mfma_f32_16x16x32_bf16 v[32:35], v[136:139], v[180:183], 0
	v_mfma_f32_16x16x32_bf16 v[20:23], v[128:131], v[188:191], 0
	v_mfma_f32_16x16x32_bf16 v[16:19], v[136:139], v[188:191], 0
	v_mfma_f32_16x16x32_bf16 v[60:63], v[132:135], v[148:151], v[60:63]
	v_mfma_f32_16x16x32_bf16 v[56:59], v[140:143], v[148:151], v[56:59]
	v_mfma_f32_16x16x32_bf16 v[52:55], v[132:135], v[156:159], v[52:55]
	v_mfma_f32_16x16x32_bf16 v[48:51], v[140:143], v[156:159], v[48:51]
	v_mfma_f32_16x16x32_bf16 v[36:39], v[132:135], v[184:187], v[36:39]
	v_mfma_f32_16x16x32_bf16 v[32:35], v[140:143], v[184:187], v[32:35]
	v_mfma_f32_16x16x32_bf16 v[20:23], v[132:135], v[192:195], v[20:23]
	v_mfma_f32_16x16x32_bf16 v[16:19], v[140:143], v[192:195], v[16:19]
	s_barrier
	s_mov_b32 m0, s21
	s_nop 0
	global_load_lds_dwordx4 v160, s[8:9]
	s_mov_b32 m0, s55
	s_nop 0
	global_load_lds_dwordx4 v162, s[8:9]
	s_add_i32 m0, s54, 0x14000
	s_add_u32 s64, s2, 0x40000
	s_addc_u32 s65, s3, 0
	global_load_lds_dwordx4 v160, s[64:65]
	s_add_i32 m0, s54, 0x16000
	s_add_u32 s8, s8, 0x40000
	s_addc_u32 s9, s9, 0
	global_load_lds_dwordx4 v162, s[64:65]
	s_waitcnt vmcnt(6)
	s_barrier
	v_mfma_f32_16x16x32_bf16 v[44:47], v[196:199], v[144:147], 0
	v_mfma_f32_16x16x32_bf16 v[40:43], v[210:213], v[144:147], 0
	v_mfma_f32_16x16x32_bf16 v[28:31], v[196:199], v[152:155], 0
	v_mfma_f32_16x16x32_bf16 v[24:27], v[210:213], v[152:155], 0
	v_mfma_f32_16x16x32_bf16 v[12:15], v[196:199], v[180:183], 0
	v_mfma_f32_16x16x32_bf16 v[8:11], v[210:213], v[180:183], 0
	v_mfma_f32_16x16x32_bf16 v[4:7], v[196:199], v[188:191], 0
	v_mfma_f32_16x16x32_bf16 v[0:3], v[210:213], v[188:191], 0
	v_mfma_f32_16x16x32_bf16 v[44:47], v[200:203], v[148:151], v[44:47]
	v_mfma_f32_16x16x32_bf16 v[40:43], v[214:217], v[148:151], v[40:43]
	v_mfma_f32_16x16x32_bf16 v[28:31], v[200:203], v[156:159], v[28:31]
	v_mfma_f32_16x16x32_bf16 v[24:27], v[214:217], v[156:159], v[24:27]
	v_mfma_f32_16x16x32_bf16 v[12:15], v[200:203], v[184:187], v[12:15]
	v_mfma_f32_16x16x32_bf16 v[8:11], v[214:217], v[184:187], v[8:11]
	v_mfma_f32_16x16x32_bf16 v[4:7], v[200:203], v[192:195], v[4:7]
	v_mfma_f32_16x16x32_bf16 v[0:3], v[214:217], v[192:195], v[0:3]
	s_barrier
	ds_read_b128 v[128:131], v208 offset:32768
	ds_read_b128 v[132:135], v208 offset:33792
	ds_read_b128 v[136:139], v208 offset:34816
	ds_read_b128 v[140:143], v208 offset:35840
	ds_read_b128 v[144:147], v209 offset:32768
	ds_read_b128 v[148:151], v209 offset:33792
	ds_read_b128 v[152:155], v209 offset:34816
	ds_read_b128 v[156:159], v209 offset:35840
	ds_read_b128 v[180:183], v209 offset:36864
	ds_read_b128 v[184:187], v209 offset:37888
	ds_read_b128 v[188:191], v209 offset:38912
	ds_read_b128 v[192:195], v209 offset:39936
	s_barrier
	s_waitcnt lgkmcnt(0)
	v_mfma_f32_16x16x32_bf16 v[124:127], v[128:131], v[144:147], v[124:127]
	v_mfma_f32_16x16x32_bf16 v[120:123], v[136:139], v[144:147], v[120:123]
	v_mfma_f32_16x16x32_bf16 v[116:119], v[128:131], v[152:155], v[116:119]
	v_mfma_f32_16x16x32_bf16 v[112:115], v[136:139], v[152:155], v[112:115]
	v_mfma_f32_16x16x32_bf16 v[100:103], v[128:131], v[180:183], v[100:103]
	v_mfma_f32_16x16x32_bf16 v[96:99], v[136:139], v[180:183], v[96:99]
	v_mfma_f32_16x16x32_bf16 v[84:87], v[128:131], v[188:191], v[84:87]
	v_mfma_f32_16x16x32_bf16 v[80:83], v[136:139], v[188:191], v[80:83]
	v_mfma_f32_16x16x32_bf16 v[124:127], v[132:135], v[148:151], v[124:127]
	v_mfma_f32_16x16x32_bf16 v[120:123], v[140:143], v[148:151], v[120:123]
	v_mfma_f32_16x16x32_bf16 v[116:119], v[132:135], v[156:159], v[116:119]
	v_mfma_f32_16x16x32_bf16 v[112:115], v[140:143], v[156:159], v[112:115]
	v_mfma_f32_16x16x32_bf16 v[100:103], v[132:135], v[184:187], v[100:103]
	v_mfma_f32_16x16x32_bf16 v[96:99], v[140:143], v[184:187], v[96:99]
	v_mfma_f32_16x16x32_bf16 v[84:87], v[132:135], v[192:195], v[84:87]
	v_mfma_f32_16x16x32_bf16 v[80:83], v[140:143], v[192:195], v[80:83]
	s_barrier
	s_mov_b32 m0, s56
	ds_read_b128 v[196:199], v208 offset:49152
	ds_read_b128 v[200:203], v208 offset:50176
	ds_read_b128 v[210:213], v208 offset:51200
	global_load_lds_dwordx4 v160, s[8:9]
	s_mov_b32 m0, s57
	ds_read_b128 v[214:217], v208 offset:52224
	global_load_lds_dwordx4 v162, s[8:9]
	s_barrier
	s_waitcnt lgkmcnt(0)
	v_mfma_f32_16x16x32_bf16 v[108:111], v[196:199], v[144:147], v[108:111]
	v_mfma_f32_16x16x32_bf16 v[104:107], v[210:213], v[144:147], v[104:107]
	v_mfma_f32_16x16x32_bf16 v[92:95], v[196:199], v[152:155], v[92:95]
	v_mfma_f32_16x16x32_bf16 v[88:91], v[210:213], v[152:155], v[88:91]
	v_mfma_f32_16x16x32_bf16 v[76:79], v[196:199], v[180:183], v[76:79]
	v_mfma_f32_16x16x32_bf16 v[72:75], v[210:213], v[180:183], v[72:75]
	v_mfma_f32_16x16x32_bf16 v[68:71], v[196:199], v[188:191], v[68:71]
	v_mfma_f32_16x16x32_bf16 v[64:67], v[210:213], v[188:191], v[64:67]
	v_mfma_f32_16x16x32_bf16 v[108:111], v[200:203], v[148:151], v[108:111]
	v_mfma_f32_16x16x32_bf16 v[104:107], v[214:217], v[148:151], v[104:107]
	v_mfma_f32_16x16x32_bf16 v[92:95], v[200:203], v[156:159], v[92:95]
	v_mfma_f32_16x16x32_bf16 v[88:91], v[214:217], v[156:159], v[88:91]
	v_mfma_f32_16x16x32_bf16 v[76:79], v[200:203], v[184:187], v[76:79]
	v_mfma_f32_16x16x32_bf16 v[72:75], v[214:217], v[184:187], v[72:75]
	v_mfma_f32_16x16x32_bf16 v[68:71], v[200:203], v[192:195], v[68:71]
	v_mfma_f32_16x16x32_bf16 v[64:67], v[214:217], v[192:195], v[64:67]
	s_barrier
	ds_read_b128 v[144:147], v209 offset:49152
	ds_read_b128 v[148:151], v209 offset:50176
	ds_read_b128 v[152:155], v209 offset:51200
	ds_read_b128 v[156:159], v209 offset:52224
	ds_read_b128 v[180:183], v209 offset:53248
	ds_read_b128 v[184:187], v209 offset:54272
	ds_read_b128 v[188:191], v209 offset:55296
	ds_read_b128 v[192:195], v209 offset:56320
	s_add_i32 m0, s54, 0x18000
	s_nop 0
	global_load_lds_dwordx4 v160, s[98:99]
	s_add_i32 m0, s54, 0x1a000
	s_nop 0
	global_load_lds_dwordx4 v162, s[98:99]
	s_barrier
	s_waitcnt lgkmcnt(0)
	v_mfma_f32_16x16x32_bf16 v[60:63], v[128:131], v[144:147], v[60:63]
	v_mfma_f32_16x16x32_bf16 v[56:59], v[136:139], v[144:147], v[56:59]
	v_mfma_f32_16x16x32_bf16 v[52:55], v[128:131], v[152:155], v[52:55]
	v_mfma_f32_16x16x32_bf16 v[48:51], v[136:139], v[152:155], v[48:51]
	v_mfma_f32_16x16x32_bf16 v[36:39], v[128:131], v[180:183], v[36:39]
	v_mfma_f32_16x16x32_bf16 v[32:35], v[136:139], v[180:183], v[32:35]
	v_mfma_f32_16x16x32_bf16 v[20:23], v[128:131], v[188:191], v[20:23]
	v_mfma_f32_16x16x32_bf16 v[16:19], v[136:139], v[188:191], v[16:19]
	v_mfma_f32_16x16x32_bf16 v[60:63], v[132:135], v[148:151], v[60:63]
	v_mfma_f32_16x16x32_bf16 v[56:59], v[140:143], v[148:151], v[56:59]
	v_mfma_f32_16x16x32_bf16 v[52:55], v[132:135], v[156:159], v[52:55]
	v_mfma_f32_16x16x32_bf16 v[48:51], v[140:143], v[156:159], v[48:51]
	v_mfma_f32_16x16x32_bf16 v[36:39], v[132:135], v[184:187], v[36:39]
	v_mfma_f32_16x16x32_bf16 v[32:35], v[140:143], v[184:187], v[32:35]
	v_mfma_f32_16x16x32_bf16 v[20:23], v[132:135], v[192:195], v[20:23]
	v_mfma_f32_16x16x32_bf16 v[16:19], v[140:143], v[192:195], v[16:19]
	s_barrier
	s_mov_b32 m0, s60
	s_nop 0
	global_load_lds_dwordx4 v160, s[100:101]
	s_mov_b32 m0, s61
	s_nop 0
	global_load_lds_dwordx4 v162, s[100:101]
	s_add_i32 m0, s54, 0x1c000
	s_add_u32 s2, s2, 0x40080
	s_addc_u32 s3, s3, 0
	global_load_lds_dwordx4 v160, s[2:3]
	s_add_i32 m0, s54, 0x1e000
	s_add_i32 s41, s41, 2
	global_load_lds_dwordx4 v162, s[2:3]
	s_waitcnt vmcnt(6)
	s_barrier
	v_mfma_f32_16x16x32_bf16 v[44:47], v[196:199], v[144:147], v[44:47]
	v_mfma_f32_16x16x32_bf16 v[40:43], v[210:213], v[144:147], v[40:43]
	v_mfma_f32_16x16x32_bf16 v[28:31], v[196:199], v[152:155], v[28:31]
	v_mfma_f32_16x16x32_bf16 v[24:27], v[210:213], v[152:155], v[24:27]
	v_mfma_f32_16x16x32_bf16 v[12:15], v[196:199], v[180:183], v[12:15]
	v_mfma_f32_16x16x32_bf16 v[8:11], v[210:213], v[180:183], v[8:11]
	v_mfma_f32_16x16x32_bf16 v[4:7], v[196:199], v[188:191], v[4:7]
	v_mfma_f32_16x16x32_bf16 v[0:3], v[210:213], v[188:191], v[0:3]
	v_mfma_f32_16x16x32_bf16 v[44:47], v[200:203], v[148:151], v[44:47]
	v_mfma_f32_16x16x32_bf16 v[40:43], v[214:217], v[148:151], v[40:43]
	v_mfma_f32_16x16x32_bf16 v[28:31], v[200:203], v[156:159], v[28:31]
	v_mfma_f32_16x16x32_bf16 v[24:27], v[214:217], v[156:159], v[24:27]
	v_mfma_f32_16x16x32_bf16 v[12:15], v[200:203], v[184:187], v[12:15]
	v_mfma_f32_16x16x32_bf16 v[8:11], v[214:217], v[184:187], v[8:11]
	v_mfma_f32_16x16x32_bf16 v[4:7], v[200:203], v[192:195], v[4:7]
	v_mfma_f32_16x16x32_bf16 v[0:3], v[214:217], v[192:195], v[0:3]
	s_add_u32 s6, s6, 0x100
	s_addc_u32 s7, s7, 0
	s_add_u32 s39, s39, 0x100
	s_addc_u32 s40, s40, 0
	s_cmp_gt_u32 s41, 13
	s_barrier
.LBB0_355:
	s_add_u32 s2, s6, 0xfffc0080
	s_addc_u32 s3, s7, -1
	ds_read_b128 v[128:131], v208
	ds_read_b128 v[132:135], v208 offset:1024
	ds_read_b128 v[136:139], v208 offset:2048
	ds_read_b128 v[140:143], v208 offset:3072
	s_cmp_eq_u32 s41, 12
	s_cselect_b32 s9, s1, s3
	s_cselect_b32 s8, s31, s2
	s_cselect_b32 s3, s29, s40
	s_cselect_b32 s2, s38, s39
	ds_read_b128 v[144:147], v209
	ds_read_b128 v[148:151], v209 offset:1024
	ds_read_b128 v[152:155], v209 offset:2048
	ds_read_b128 v[156:159], v209 offset:3072
	ds_read_b128 v[180:183], v209 offset:4096
	ds_read_b128 v[184:187], v209 offset:5120
	ds_read_b128 v[188:191], v209 offset:6144
	ds_read_b128 v[192:195], v209 offset:7168
	s_barrier
	s_waitcnt lgkmcnt(0)
	v_mfma_f32_16x16x32_bf16 v[124:127], v[128:131], v[144:147], v[124:127]
	v_mfma_f32_16x16x32_bf16 v[120:123], v[136:139], v[144:147], v[120:123]
	v_mfma_f32_16x16x32_bf16 v[116:119], v[128:131], v[152:155], v[116:119]
	v_mfma_f32_16x16x32_bf16 v[112:115], v[136:139], v[152:155], v[112:115]
	v_mfma_f32_16x16x32_bf16 v[100:103], v[128:131], v[180:183], v[100:103]
	v_mfma_f32_16x16x32_bf16 v[96:99], v[136:139], v[180:183], v[96:99]
	v_mfma_f32_16x16x32_bf16 v[84:87], v[128:131], v[188:191], v[84:87]
	v_mfma_f32_16x16x32_bf16 v[80:83], v[136:139], v[188:191], v[80:83]
	v_mfma_f32_16x16x32_bf16 v[124:127], v[132:135], v[148:151], v[124:127]
	v_mfma_f32_16x16x32_bf16 v[120:123], v[140:143], v[148:151], v[120:123]
	v_mfma_f32_16x16x32_bf16 v[116:119], v[132:135], v[156:159], v[116:119]
	v_mfma_f32_16x16x32_bf16 v[112:115], v[140:143], v[156:159], v[112:115]
	v_mfma_f32_16x16x32_bf16 v[100:103], v[132:135], v[184:187], v[100:103]
	v_mfma_f32_16x16x32_bf16 v[96:99], v[140:143], v[184:187], v[96:99]
	v_mfma_f32_16x16x32_bf16 v[84:87], v[132:135], v[192:195], v[84:87]
	v_mfma_f32_16x16x32_bf16 v[80:83], v[140:143], v[192:195], v[80:83]
	s_barrier
	s_add_i32 m0, s21, 0xc000
	ds_read_b128 v[196:199], v208 offset:16384
	ds_read_b128 v[200:203], v208 offset:17408
	ds_read_b128 v[210:213], v208 offset:18432
	global_load_lds_dwordx4 v164, s[6:7]
	s_add_i32 m0, s21, 0xe000
	ds_read_b128 v[214:217], v208 offset:19456
	global_load_lds_dwordx4 v166, s[6:7]
	s_add_u32 s98, s2, 0x80
	s_addc_u32 s99, s3, 0
	s_barrier
	s_waitcnt lgkmcnt(0)
	v_mfma_f32_16x16x32_bf16 v[108:111], v[196:199], v[144:147], v[108:111]
	v_mfma_f32_16x16x32_bf16 v[104:107], v[210:213], v[144:147], v[104:107]
	v_mfma_f32_16x16x32_bf16 v[92:95], v[196:199], v[152:155], v[92:95]
	v_mfma_f32_16x16x32_bf16 v[88:91], v[210:213], v[152:155], v[88:91]
	v_mfma_f32_16x16x32_bf16 v[76:79], v[196:199], v[180:183], v[76:79]
	v_mfma_f32_16x16x32_bf16 v[72:75], v[210:213], v[180:183], v[72:75]
	v_mfma_f32_16x16x32_bf16 v[68:71], v[196:199], v[188:191], v[68:71]
	v_mfma_f32_16x16x32_bf16 v[64:67], v[210:213], v[188:191], v[64:67]
	v_mfma_f32_16x16x32_bf16 v[108:111], v[200:203], v[148:151], v[108:111]
	v_mfma_f32_16x16x32_bf16 v[104:107], v[214:217], v[148:151], v[104:107]
	v_mfma_f32_16x16x32_bf16 v[92:95], v[200:203], v[156:159], v[92:95]
	v_mfma_f32_16x16x32_bf16 v[88:91], v[214:217], v[156:159], v[88:91]
	v_mfma_f32_16x16x32_bf16 v[76:79], v[200:203], v[184:187], v[76:79]
	v_mfma_f32_16x16x32_bf16 v[72:75], v[214:217], v[184:187], v[72:75]
	v_mfma_f32_16x16x32_bf16 v[68:71], v[200:203], v[192:195], v[68:71]
	v_mfma_f32_16x16x32_bf16 v[64:67], v[214:217], v[192:195], v[64:67]
	s_add_u32 s100, s8, 0x80
	s_addc_u32 s101, s9, 0
	s_barrier
	ds_read_b128 v[144:147], v209 offset:16384
	ds_read_b128 v[148:151], v209 offset:17408
	ds_read_b128 v[152:155], v209 offset:18432
	ds_read_b128 v[156:159], v209 offset:19456
	ds_read_b128 v[180:183], v209 offset:20480
	ds_read_b128 v[184:187], v209 offset:21504
	ds_read_b128 v[188:191], v209 offset:22528
	ds_read_b128 v[192:195], v209 offset:23552
	s_add_i32 m0, s54, 0x10000
	s_nop 0
	global_load_lds_dwordx4 v160, s[2:3]
	s_add_i32 m0, s54, 0x12000
	s_nop 0
	global_load_lds_dwordx4 v162, s[2:3]
	s_barrier
	s_waitcnt lgkmcnt(0)
	v_mfma_f32_16x16x32_bf16 v[60:63], v[128:131], v[144:147], v[60:63]
	v_mfma_f32_16x16x32_bf16 v[56:59], v[136:139], v[144:147], v[56:59]
	v_mfma_f32_16x16x32_bf16 v[52:55], v[128:131], v[152:155], v[52:55]
	v_mfma_f32_16x16x32_bf16 v[48:51], v[136:139], v[152:155], v[48:51]
	v_mfma_f32_16x16x32_bf16 v[36:39], v[128:131], v[180:183], v[36:39]
	v_mfma_f32_16x16x32_bf16 v[32:35], v[136:139], v[180:183], v[32:35]
	v_mfma_f32_16x16x32_bf16 v[20:23], v[128:131], v[188:191], v[20:23]
	v_mfma_f32_16x16x32_bf16 v[16:19], v[136:139], v[188:191], v[16:19]
	v_mfma_f32_16x16x32_bf16 v[60:63], v[132:135], v[148:151], v[60:63]
	v_mfma_f32_16x16x32_bf16 v[56:59], v[140:143], v[148:151], v[56:59]
	v_mfma_f32_16x16x32_bf16 v[52:55], v[132:135], v[156:159], v[52:55]
	v_mfma_f32_16x16x32_bf16 v[48:51], v[140:143], v[156:159], v[48:51]
	v_mfma_f32_16x16x32_bf16 v[36:39], v[132:135], v[184:187], v[36:39]
	v_mfma_f32_16x16x32_bf16 v[32:35], v[140:143], v[184:187], v[32:35]
	v_mfma_f32_16x16x32_bf16 v[20:23], v[132:135], v[192:195], v[20:23]
	v_mfma_f32_16x16x32_bf16 v[16:19], v[140:143], v[192:195], v[16:19]
	s_barrier
	s_mov_b32 m0, s21
	s_nop 0
	global_load_lds_dwordx4 v160, s[8:9]
	s_mov_b32 m0, s55
	s_nop 0
	global_load_lds_dwordx4 v162, s[8:9]
	s_add_i32 m0, s54, 0x14000
	s_add_u32 s64, s2, 0x40000
	s_addc_u32 s65, s3, 0
	global_load_lds_dwordx4 v160, s[64:65]
	s_add_i32 m0, s54, 0x16000
	s_add_u32 s8, s8, 0x40000
	s_addc_u32 s9, s9, 0
	global_load_lds_dwordx4 v162, s[64:65]
	s_waitcnt vmcnt(6)
	s_barrier
	v_mfma_f32_16x16x32_bf16 v[44:47], v[196:199], v[144:147], v[44:47]
	v_mfma_f32_16x16x32_bf16 v[40:43], v[210:213], v[144:147], v[40:43]
	v_mfma_f32_16x16x32_bf16 v[28:31], v[196:199], v[152:155], v[28:31]
	v_mfma_f32_16x16x32_bf16 v[24:27], v[210:213], v[152:155], v[24:27]
	v_mfma_f32_16x16x32_bf16 v[12:15], v[196:199], v[180:183], v[12:15]
	v_mfma_f32_16x16x32_bf16 v[8:11], v[210:213], v[180:183], v[8:11]
	v_mfma_f32_16x16x32_bf16 v[4:7], v[196:199], v[188:191], v[4:7]
	v_mfma_f32_16x16x32_bf16 v[0:3], v[210:213], v[188:191], v[0:3]
	v_mfma_f32_16x16x32_bf16 v[44:47], v[200:203], v[148:151], v[44:47]
	v_mfma_f32_16x16x32_bf16 v[40:43], v[214:217], v[148:151], v[40:43]
	v_mfma_f32_16x16x32_bf16 v[28:31], v[200:203], v[156:159], v[28:31]
	v_mfma_f32_16x16x32_bf16 v[24:27], v[214:217], v[156:159], v[24:27]
	v_mfma_f32_16x16x32_bf16 v[12:15], v[200:203], v[184:187], v[12:15]
	v_mfma_f32_16x16x32_bf16 v[8:11], v[214:217], v[184:187], v[8:11]
	v_mfma_f32_16x16x32_bf16 v[4:7], v[200:203], v[192:195], v[4:7]
	v_mfma_f32_16x16x32_bf16 v[0:3], v[214:217], v[192:195], v[0:3]
	s_barrier
	ds_read_b128 v[128:131], v208 offset:32768
	ds_read_b128 v[132:135], v208 offset:33792
	ds_read_b128 v[136:139], v208 offset:34816
	ds_read_b128 v[140:143], v208 offset:35840
	ds_read_b128 v[144:147], v209 offset:32768
	ds_read_b128 v[148:151], v209 offset:33792
	ds_read_b128 v[152:155], v209 offset:34816
	ds_read_b128 v[156:159], v209 offset:35840
	ds_read_b128 v[180:183], v209 offset:36864
	ds_read_b128 v[184:187], v209 offset:37888
	ds_read_b128 v[188:191], v209 offset:38912
	ds_read_b128 v[192:195], v209 offset:39936
	s_barrier
	s_waitcnt lgkmcnt(0)
	v_mfma_f32_16x16x32_bf16 v[124:127], v[128:131], v[144:147], v[124:127]
	v_mfma_f32_16x16x32_bf16 v[120:123], v[136:139], v[144:147], v[120:123]
	v_mfma_f32_16x16x32_bf16 v[116:119], v[128:131], v[152:155], v[116:119]
	v_mfma_f32_16x16x32_bf16 v[112:115], v[136:139], v[152:155], v[112:115]
	v_mfma_f32_16x16x32_bf16 v[100:103], v[128:131], v[180:183], v[100:103]
	v_mfma_f32_16x16x32_bf16 v[96:99], v[136:139], v[180:183], v[96:99]
	v_mfma_f32_16x16x32_bf16 v[84:87], v[128:131], v[188:191], v[84:87]
	v_mfma_f32_16x16x32_bf16 v[80:83], v[136:139], v[188:191], v[80:83]
	v_mfma_f32_16x16x32_bf16 v[124:127], v[132:135], v[148:151], v[124:127]
	v_mfma_f32_16x16x32_bf16 v[120:123], v[140:143], v[148:151], v[120:123]
	v_mfma_f32_16x16x32_bf16 v[116:119], v[132:135], v[156:159], v[116:119]
	v_mfma_f32_16x16x32_bf16 v[112:115], v[140:143], v[156:159], v[112:115]
	v_mfma_f32_16x16x32_bf16 v[100:103], v[132:135], v[184:187], v[100:103]
	v_mfma_f32_16x16x32_bf16 v[96:99], v[140:143], v[184:187], v[96:99]
	v_mfma_f32_16x16x32_bf16 v[84:87], v[132:135], v[192:195], v[84:87]
	v_mfma_f32_16x16x32_bf16 v[80:83], v[140:143], v[192:195], v[80:83]
	s_barrier
	s_mov_b32 m0, s56
	ds_read_b128 v[196:199], v208 offset:49152
	ds_read_b128 v[200:203], v208 offset:50176
	ds_read_b128 v[210:213], v208 offset:51200
	global_load_lds_dwordx4 v160, s[8:9]
	s_mov_b32 m0, s57
	ds_read_b128 v[214:217], v208 offset:52224
	global_load_lds_dwordx4 v162, s[8:9]
	s_barrier
	s_waitcnt lgkmcnt(0)
	v_mfma_f32_16x16x32_bf16 v[108:111], v[196:199], v[144:147], v[108:111]
	v_mfma_f32_16x16x32_bf16 v[104:107], v[210:213], v[144:147], v[104:107]
	v_mfma_f32_16x16x32_bf16 v[92:95], v[196:199], v[152:155], v[92:95]
	v_mfma_f32_16x16x32_bf16 v[88:91], v[210:213], v[152:155], v[88:91]
	v_mfma_f32_16x16x32_bf16 v[76:79], v[196:199], v[180:183], v[76:79]
	v_mfma_f32_16x16x32_bf16 v[72:75], v[210:213], v[180:183], v[72:75]
	v_mfma_f32_16x16x32_bf16 v[68:71], v[196:199], v[188:191], v[68:71]
	v_mfma_f32_16x16x32_bf16 v[64:67], v[210:213], v[188:191], v[64:67]
	v_mfma_f32_16x16x32_bf16 v[108:111], v[200:203], v[148:151], v[108:111]
	v_mfma_f32_16x16x32_bf16 v[104:107], v[214:217], v[148:151], v[104:107]
	v_mfma_f32_16x16x32_bf16 v[92:95], v[200:203], v[156:159], v[92:95]
	v_mfma_f32_16x16x32_bf16 v[88:91], v[214:217], v[156:159], v[88:91]
	v_mfma_f32_16x16x32_bf16 v[76:79], v[200:203], v[184:187], v[76:79]
	v_mfma_f32_16x16x32_bf16 v[72:75], v[214:217], v[184:187], v[72:75]
	v_mfma_f32_16x16x32_bf16 v[68:71], v[200:203], v[192:195], v[68:71]
	v_mfma_f32_16x16x32_bf16 v[64:67], v[214:217], v[192:195], v[64:67]
	s_barrier
	ds_read_b128 v[144:147], v209 offset:49152
	ds_read_b128 v[148:151], v209 offset:50176
	ds_read_b128 v[152:155], v209 offset:51200
	ds_read_b128 v[156:159], v209 offset:52224
	ds_read_b128 v[180:183], v209 offset:53248
	ds_read_b128 v[184:187], v209 offset:54272
	ds_read_b128 v[188:191], v209 offset:55296
	ds_read_b128 v[192:195], v209 offset:56320
	s_add_i32 m0, s54, 0x18000
	s_nop 0
	global_load_lds_dwordx4 v160, s[98:99]
	s_add_i32 m0, s54, 0x1a000
	s_nop 0
	global_load_lds_dwordx4 v162, s[98:99]
	s_barrier
	s_waitcnt lgkmcnt(0)
	v_mfma_f32_16x16x32_bf16 v[60:63], v[128:131], v[144:147], v[60:63]
	v_mfma_f32_16x16x32_bf16 v[56:59], v[136:139], v[144:147], v[56:59]
	v_mfma_f32_16x16x32_bf16 v[52:55], v[128:131], v[152:155], v[52:55]
	v_mfma_f32_16x16x32_bf16 v[48:51], v[136:139], v[152:155], v[48:51]
	v_mfma_f32_16x16x32_bf16 v[36:39], v[128:131], v[180:183], v[36:39]
	v_mfma_f32_16x16x32_bf16 v[32:35], v[136:139], v[180:183], v[32:35]
	v_mfma_f32_16x16x32_bf16 v[20:23], v[128:131], v[188:191], v[20:23]
	v_mfma_f32_16x16x32_bf16 v[16:19], v[136:139], v[188:191], v[16:19]
	v_mfma_f32_16x16x32_bf16 v[60:63], v[132:135], v[148:151], v[60:63]
	v_mfma_f32_16x16x32_bf16 v[56:59], v[140:143], v[148:151], v[56:59]
	v_mfma_f32_16x16x32_bf16 v[52:55], v[132:135], v[156:159], v[52:55]
	v_mfma_f32_16x16x32_bf16 v[48:51], v[140:143], v[156:159], v[48:51]
	v_mfma_f32_16x16x32_bf16 v[36:39], v[132:135], v[184:187], v[36:39]
	v_mfma_f32_16x16x32_bf16 v[32:35], v[140:143], v[184:187], v[32:35]
	v_mfma_f32_16x16x32_bf16 v[20:23], v[132:135], v[192:195], v[20:23]
	v_mfma_f32_16x16x32_bf16 v[16:19], v[140:143], v[192:195], v[16:19]
	s_barrier
	s_mov_b32 m0, s60
	s_nop 0
	global_load_lds_dwordx4 v160, s[100:101]
	s_mov_b32 m0, s61
	s_nop 0
	global_load_lds_dwordx4 v162, s[100:101]
	s_add_i32 m0, s54, 0x1c000
	s_add_u32 s2, s2, 0x40080
	s_addc_u32 s3, s3, 0
	global_load_lds_dwordx4 v160, s[2:3]
	s_add_i32 m0, s54, 0x1e000
	s_add_i32 s41, s41, 2
	global_load_lds_dwordx4 v162, s[2:3]
	s_waitcnt vmcnt(6)
	s_barrier
	v_mfma_f32_16x16x32_bf16 v[44:47], v[196:199], v[144:147], v[44:47]
	v_mfma_f32_16x16x32_bf16 v[40:43], v[210:213], v[144:147], v[40:43]
	v_mfma_f32_16x16x32_bf16 v[28:31], v[196:199], v[152:155], v[28:31]
	v_mfma_f32_16x16x32_bf16 v[24:27], v[210:213], v[152:155], v[24:27]
	v_mfma_f32_16x16x32_bf16 v[12:15], v[196:199], v[180:183], v[12:15]
	v_mfma_f32_16x16x32_bf16 v[8:11], v[210:213], v[180:183], v[8:11]
	v_mfma_f32_16x16x32_bf16 v[4:7], v[196:199], v[188:191], v[4:7]
	v_mfma_f32_16x16x32_bf16 v[0:3], v[210:213], v[188:191], v[0:3]
	v_mfma_f32_16x16x32_bf16 v[44:47], v[200:203], v[148:151], v[44:47]
	v_mfma_f32_16x16x32_bf16 v[40:43], v[214:217], v[148:151], v[40:43]
	v_mfma_f32_16x16x32_bf16 v[28:31], v[200:203], v[156:159], v[28:31]
	v_mfma_f32_16x16x32_bf16 v[24:27], v[214:217], v[156:159], v[24:27]
	v_mfma_f32_16x16x32_bf16 v[12:15], v[200:203], v[184:187], v[12:15]
	v_mfma_f32_16x16x32_bf16 v[8:11], v[214:217], v[184:187], v[8:11]
	v_mfma_f32_16x16x32_bf16 v[4:7], v[200:203], v[192:195], v[4:7]
	v_mfma_f32_16x16x32_bf16 v[0:3], v[214:217], v[192:195], v[0:3]
	s_add_u32 s6, s6, 0x100
	s_addc_u32 s7, s7, 0
	s_add_u32 s39, s39, 0x100
	s_addc_u32 s40, s40, 0
	s_cmp_gt_u32 s41, 13
	s_barrier
	s_cbranch_scc0 .LBB0_355
	s_lshl_b32 s1, s0, 8
	v_mov_b32_e32 v211, v206
	v_mov_b32_e32 v210, v207
	s_add_i32 s1, s1, s59
	s_cmp_lt_i32 s20, 3
	v_add_u32_e32 v180, s1, v211
	s_mov_b64 s[2:3], -1
	s_cbranch_scc0 .LBB0_490
	s_cmp_gt_i32 s0, 15
	s_cselect_b64 s[2:3], -1, 0
	s_cmp_lt_i32 s0, 16
	s_cselect_b64 s[38:39], -1, 0
	s_cmp_eq_u32 s20, 2
	s_cselect_b64 s[8:9], -1, 0
	s_cmp_lg_u32 s20, 2
	s_cselect_b64 s[0:1], -1, 0
	s_and_b64 s[40:41], s[8:9], s[22:23]
	v_lshlrev_b32_e32 v182, 2, v210
	s_mov_b64 s[6:7], -1
	s_and_b64 vcc, exec, s[40:41]
	v_ashrrev_i32_e32 v183, 31, v182
	s_cbranch_vccnz .LBB0_447
	s_and_b64 s[6:7], s[8:9], exec
	s_cselect_b32 s6, s46, s44
	s_cselect_b32 s7, s47, s45
	v_mov_b32_e32 v128, s7
	v_mov_b32_e32 v129, s6
	v_lshl_add_u64 v[128:129], v[182:183], 2, v[128:129]
	global_load_dwordx4 v[140:143], v[128:129], off
	global_load_dwordx4 v[136:139], v[128:129], off offset:64
	global_load_dwordx4 v[132:135], v[128:129], off offset:128
	s_nop 0
	global_load_dwordx4 v[128:131], v[128:129], off offset:192
	v_mul_f32_e32 v144, v125, v125
	v_mul_f32_e32 v145, v127, v127
	v_fmac_f32_e32 v144, v124, v124
	v_fmac_f32_e32 v145, v126, v126
	v_add_f32_e32 v144, v144, v145
	v_mul_f32_e32 v145, v121, v121
	v_mul_f32_e32 v146, v123, v123
	v_fmac_f32_e32 v145, v120, v120
	v_fmac_f32_e32 v146, v122, v122
	v_add_f32_e32 v145, v145, v146
	v_add_f32_e32 v144, v144, v145
	v_mul_f32_e32 v145, v109, v109
	v_mul_f32_e32 v146, v111, v111
	v_fmac_f32_e32 v145, v108, v108
	v_fmac_f32_e32 v146, v110, v110
	v_add_f32_e32 v145, v145, v146
	v_add_f32_e32 v144, v144, v145
	v_mul_f32_e32 v145, v105, v105
	v_mul_f32_e32 v146, v107, v107
	v_fmac_f32_e32 v145, v104, v104
	v_fmac_f32_e32 v146, v106, v106
	v_add_f32_e32 v145, v145, v146
	v_add_f32_e32 v144, v144, v145
	v_mov_b32_e32 v145, v144
	s_nop 1
	v_permlane16_swap_b32_e32 v144, v145
	v_add_f32_e32 v144, v144, v145
	v_mov_b32_e32 v145, v144
	s_nop 1
	v_permlane32_swap_b32_e32 v144, v145
	v_add_f32_e32 v144, v144, v145
	v_fmamk_f32 v144, v144, 0x3c800000, v225
	v_cmp_gt_f32_e32 vcc, s93, v144
	v_mul_f32_e32 v145, 0x4b800000, v144
	v_and_b32_e32 v202, 63, v211
	v_cndmask_b32_e32 v144, v144, v145, vcc
	v_rsq_f32_e32 v144, v144
	v_cndmask_b32_e64 v168, 0, 1, s[2:3]
	v_cmp_ne_u32_e64 s[6:7], 1, v168
	v_lshlrev_b32_e32 v186, 7, v202
	v_mul_f32_e32 v145, 0x45800000, v144
	v_cndmask_b32_e32 v152, v144, v145, vcc
	v_pk_mul_f32 v[144:145], v[124:125], v[152:153] op_sel_hi:[1,0]
	v_pk_mul_f32 v[146:147], v[126:127], v[152:153] op_sel_hi:[1,0]
	v_pk_mul_f32 v[148:149], v[108:109], v[152:153] op_sel_hi:[1,0]
	v_pk_mul_f32 v[150:151], v[110:111], v[152:153] op_sel_hi:[1,0]
	v_pk_mul_f32 v[184:185], v[104:105], v[152:153] op_sel_hi:[1,0]
	s_andn2_b64 vcc, exec, s[2:3]
	s_waitcnt vmcnt(0)
	v_pk_mul_f32 v[158:159], v[142:143], v[146:147]
	v_pk_mul_f32 v[156:157], v[140:141], v[144:145]
	v_pk_mul_f32 v[144:145], v[120:121], v[152:153] op_sel_hi:[1,0]
	v_pk_mul_f32 v[146:147], v[122:123], v[152:153] op_sel_hi:[1,0]
	v_pk_mul_f32 v[152:153], v[106:107], v[152:153] op_sel_hi:[1,0]
	v_pk_mul_f32 v[146:147], v[138:139], v[146:147]
	v_pk_mul_f32 v[144:145], v[136:137], v[144:145]
	v_pk_mul_f32 v[150:151], v[134:135], v[150:151]
	v_pk_mul_f32 v[148:149], v[132:133], v[148:149]
	v_pk_mul_f32 v[154:155], v[130:131], v[152:153]
	v_pk_mul_f32 v[152:153], v[128:129], v[184:185]
	v_lshl_add_u64 v[184:185], v[182:183], 3, s[18:19]
	s_cbranch_vccnz .LBB0_360
	v_lshlrev_b32_e32 v168, 1, v180
	v_and_b32_e32 v168, 0xf80, v168
	v_lshl_add_u64 v[188:189], v[184:185], 0, v[168:169]
	global_load_dwordx4 v[190:193], v[188:189], off offset:16
	global_load_dwordx4 v[194:197], v[188:189], off
	v_mov_b32_e32 v187, v169
	s_waitcnt vmcnt(0)
	v_mul_f32_e32 v198, v158, v190
	v_mov_b32_e32 v188, v194
	v_mov_b32_e32 v189, v196
	v_mov_b32_e32 v196, v195
	v_mul_f32_e32 v200, v146, v191
	v_mul_f32_e32 v204, v146, v190
	v_mul_f32_e32 v212, v158, v191
	v_mov_b32_e32 v146, v159
	v_mov_b32_e32 v158, v147
	v_pk_mul_f32 v[194:195], v[144:145], v[196:197]
	v_pk_mul_f32 v[144:145], v[144:145], v[188:189]
	v_pk_mul_f32 v[190:191], v[146:147], v[192:193]
	v_pk_mul_f32 v[146:147], v[158:159], v[192:193]
	v_lshl_add_u64 v[192:193], v[184:185], 0, v[186:187]
	v_mov_b32_e32 v199, v190
	v_mov_b32_e32 v201, v191
	v_pk_fma_f32 v[190:191], v[156:157], v[188:189], v[194:195] neg_lo:[0,0,1] neg_hi:[0,0,1]
	v_pk_fma_f32 v[144:145], v[156:157], v[196:197], v[144:145]
	global_load_dwordx4 v[156:159], v[192:193], off offset:16
	s_nop 0
	global_load_dwordx4 v[192:195], v[192:193], off
	v_pk_add_f32 v[188:189], v[198:199], v[200:201] neg_lo:[0,1] neg_hi:[0,1]
	v_mov_b32_e32 v213, v147
	v_mov_b32_e32 v205, v146
	v_pk_add_f32 v[146:147], v[212:213], v[204:205]
	s_waitcnt vmcnt(0)
	v_mul_f32_e32 v198, v150, v156
	v_mul_f32_e32 v200, v154, v157
	v_mul_f32_e32 v156, v154, v156
	v_mov_b32_e32 v154, v151
	v_mov_b32_e32 v197, v194
	v_mov_b32_e32 v194, v193
	v_mul_f32_e32 v204, v150, v157
	v_pk_mul_f32 v[212:213], v[154:155], v[158:159]
	v_mov_b32_e32 v150, v155
	v_mov_b32_e32 v196, v192
	v_pk_mul_f32 v[192:193], v[152:153], v[194:195]
	v_mov_b32_e32 v199, v212
	v_mov_b32_e32 v201, v213
	v_pk_mul_f32 v[150:151], v[150:151], v[158:159]
	v_pk_mul_f32 v[152:153], v[152:153], v[196:197]
	v_pk_fma_f32 v[192:193], v[148:149], v[196:197], v[192:193] neg_lo:[0,0,1] neg_hi:[0,0,1]
	v_pk_add_f32 v[196:197], v[198:199], v[200:201] neg_lo:[0,1] neg_hi:[0,1]
	v_mov_b32_e32 v205, v151
	v_mov_b32_e32 v157, v150
	v_pk_fma_f32 v[152:153], v[148:149], v[194:195], v[152:153]
	v_pk_add_f32 v[154:155], v[204:205], v[156:157]
	v_mov_b32_e32 v148, v192
	v_mov_b32_e32 v149, v193
	v_mov_b32_e32 v150, v196
	v_mov_b32_e32 v151, v197
	v_mov_b32_e32 v156, v190
	v_mov_b32_e32 v157, v191
	v_mov_b32_e32 v158, v188
	v_mov_b32_e32 v159, v189

.LBB0_677:
	s_ashr_i32 s23, s22, 31
	v_cmp_lt_i64_e32 vcc, s[24:25], v[174:175]
	s_lshl_b64 s[24:25], s[22:23], 19
	s_add_u32 s24, s36, s24
	s_addc_u32 s25, s37, s25
	s_and_b64 s[26:27], vcc, exec
	s_cselect_b32 s1, s25, s9
	s_cselect_b32 s7, s24, s8
	s_ashr_i32 s21, s20, 31
	s_lshl_b64 s[26:27], s[20:21], 19
	s_add_u32 s26, s38, s26
	s_addc_u32 s27, s39, s27
	s_and_b64 s[28:29], vcc, exec
	s_cselect_b32 s21, s27, s3
	s_cselect_b32 s23, s26, s2
	s_add_u32 s8, s8, 0x40080
	s_addc_u32 s9, s9, 0
	s_add_u32 s56, s2, 0x100
	s_addc_u32 s57, s3, 0
	s_mov_b32 s58, -2
	s_add_u32 s2, s8, 0xfffc0080
	s_addc_u32 s3, s9, -1
	ds_read_b128 v[48:51], v206
	ds_read_b128 v[52:55], v206 offset:1024
	ds_read_b128 v[60:63], v206 offset:2048
	ds_read_b128 v[68:71], v206 offset:3072
	s_cmp_eq_u32 s58, 12
	s_cselect_b32 s29, s1, s3
	s_cselect_b32 s28, s7, s2
	s_cselect_b32 s3, s21, s57
	s_cselect_b32 s2, s23, s56
	ds_read_b128 v[72:75], v207
	ds_read_b128 v[76:79], v207 offset:1024
	ds_read_b128 v[80:83], v207 offset:2048
	ds_read_b128 v[84:87], v207 offset:3072
	ds_read_b128 v[160:163], v207 offset:4096
	ds_read_b128 v[164:167], v207 offset:5120
	ds_read_b128 v[192:195], v207 offset:6144
	ds_read_b128 v[196:199], v207 offset:7168
	s_barrier
	s_waitcnt lgkmcnt(0)
	v_mfma_f32_16x16x32_bf16 v[156:159], v[48:51], v[72:75], 0
	v_mfma_f32_16x16x32_bf16 v[152:155], v[60:63], v[72:75], 0
	v_mfma_f32_16x16x32_bf16 v[140:143], v[48:51], v[80:83], 0
	v_mfma_f32_16x16x32_bf16 v[136:139], v[60:63], v[80:83], 0
	v_mfma_f32_16x16x32_bf16 v[124:127], v[48:51], v[160:163], 0
	v_mfma_f32_16x16x32_bf16 v[120:123], v[60:63], v[160:163], 0
	v_mfma_f32_16x16x32_bf16 v[108:111], v[48:51], v[192:195], 0
	v_mfma_f32_16x16x32_bf16 v[104:107], v[60:63], v[192:195], 0
	v_mfma_f32_16x16x32_bf16 v[156:159], v[52:55], v[76:79], v[156:159]
	v_mfma_f32_16x16x32_bf16 v[152:155], v[68:71], v[76:79], v[152:155]
	v_mfma_f32_16x16x32_bf16 v[140:143], v[52:55], v[84:87], v[140:143]
	v_mfma_f32_16x16x32_bf16 v[136:139], v[68:71], v[84:87], v[136:139]
	v_mfma_f32_16x16x32_bf16 v[124:127], v[52:55], v[164:167], v[124:127]
	v_mfma_f32_16x16x32_bf16 v[120:123], v[68:71], v[164:167], v[120:123]
	v_mfma_f32_16x16x32_bf16 v[108:111], v[52:55], v[196:199], v[108:111]
	v_mfma_f32_16x16x32_bf16 v[104:107], v[68:71], v[196:199], v[104:107]
	s_barrier
	s_add_i32 m0, s41, 0xc000
	ds_read_b128 v[200:203], v206 offset:16384
	ds_read_b128 v[208:211], v206 offset:17408
	ds_read_b128 v[212:215], v206 offset:18432
	global_load_lds_dwordx4 v188, s[8:9]
	s_add_i32 m0, s41, 0xe000
	ds_read_b128 v[216:219], v206 offset:19456
	global_load_lds_dwordx4 v190, s[8:9]
	s_add_u32 s98, s2, 0x80
	s_addc_u32 s99, s3, 0
	s_barrier
	s_waitcnt lgkmcnt(0)
	v_mfma_f32_16x16x32_bf16 v[148:151], v[200:203], v[72:75], 0
	v_mfma_f32_16x16x32_bf16 v[72:75], v[212:215], v[72:75], 0
	v_mfma_f32_16x16x32_bf16 v[148:151], v[208:211], v[76:79], v[148:151]
	v_mfma_f32_16x16x32_bf16 v[72:75], v[216:219], v[76:79], v[72:75]
	v_mfma_f32_16x16x32_bf16 v[76:79], v[200:203], v[80:83], 0
	v_mfma_f32_16x16x32_bf16 v[80:83], v[212:215], v[80:83], 0
	v_mfma_f32_16x16x32_bf16 v[112:115], v[212:215], v[160:163], 0
	v_mfma_f32_16x16x32_bf16 v[100:103], v[200:203], v[192:195], 0
	v_mfma_f32_16x16x32_bf16 v[96:99], v[212:215], v[192:195], 0
	v_mfma_f32_16x16x32_bf16 v[76:79], v[208:211], v[84:87], v[76:79]
	v_mfma_f32_16x16x32_bf16 v[80:83], v[216:219], v[84:87], v[80:83]
	v_mfma_f32_16x16x32_bf16 v[84:87], v[200:203], v[160:163], 0
	v_mfma_f32_16x16x32_bf16 v[112:115], v[216:219], v[164:167], v[112:115]
	v_mfma_f32_16x16x32_bf16 v[100:103], v[208:211], v[196:199], v[100:103]
	v_mfma_f32_16x16x32_bf16 v[96:99], v[216:219], v[196:199], v[96:99]
	v_mfma_f32_16x16x32_bf16 v[84:87], v[208:211], v[164:167], v[84:87]
	s_add_u32 s100, s28, 0x80
	s_addc_u32 s101, s29, 0
	s_barrier
	ds_read_b128 v[116:119], v207 offset:16384
	ds_read_b128 v[128:131], v207 offset:17408
	ds_read_b128 v[132:135], v207 offset:18432
	ds_read_b128 v[144:147], v207 offset:19456
	ds_read_b128 v[160:163], v207 offset:20480
	ds_read_b128 v[164:167], v207 offset:21504
	ds_read_b128 v[192:195], v207 offset:22528
	ds_read_b128 v[196:199], v207 offset:23552
	s_add_i32 m0, s40, 0x10000
	s_nop 0
	global_load_lds_dwordx4 v182, s[2:3]
	s_add_i32 m0, s40, 0x12000
	s_nop 0
	global_load_lds_dwordx4 v186, s[2:3]
	s_barrier
	s_waitcnt lgkmcnt(0)
	v_mfma_f32_16x16x32_bf16 v[92:95], v[48:51], v[116:119], 0
	v_mfma_f32_16x16x32_bf16 v[88:91], v[60:63], v[116:119], 0
	v_mfma_f32_16x16x32_bf16 v[44:47], v[48:51], v[132:135], 0
	v_mfma_f32_16x16x32_bf16 v[40:43], v[60:63], v[132:135], 0
	v_mfma_f32_16x16x32_bf16 v[28:31], v[48:51], v[160:163], 0
	v_mfma_f32_16x16x32_bf16 v[24:27], v[60:63], v[160:163], 0
	v_mfma_f32_16x16x32_bf16 v[12:15], v[48:51], v[192:195], 0
	v_mfma_f32_16x16x32_bf16 v[8:11], v[60:63], v[192:195], 0
	v_mfma_f32_16x16x32_bf16 v[92:95], v[52:55], v[128:131], v[92:95]
	v_mfma_f32_16x16x32_bf16 v[88:91], v[68:71], v[128:131], v[88:91]
	v_mfma_f32_16x16x32_bf16 v[44:47], v[52:55], v[144:147], v[44:47]
	v_mfma_f32_16x16x32_bf16 v[40:43], v[68:71], v[144:147], v[40:43]
	v_mfma_f32_16x16x32_bf16 v[28:31], v[52:55], v[164:167], v[28:31]
	v_mfma_f32_16x16x32_bf16 v[24:27], v[68:71], v[164:167], v[24:27]
	v_mfma_f32_16x16x32_bf16 v[12:15], v[52:55], v[196:199], v[12:15]
	v_mfma_f32_16x16x32_bf16 v[8:11], v[68:71], v[196:199], v[8:11]
	s_barrier
	s_mov_b32 m0, s41
	s_nop 0
	global_load_lds_dwordx4 v180, s[28:29]
	s_mov_b32 m0, s42
	s_nop 0
	global_load_lds_dwordx4 v184, s[28:29]
	s_add_i32 m0, s40, 0x14000
	s_add_u32 s60, s2, 0x40000
	s_addc_u32 s61, s3, 0
	global_load_lds_dwordx4 v182, s[60:61]
	s_add_i32 m0, s40, 0x16000
	s_add_u32 s28, s28, 0x40000
	s_addc_u32 s29, s29, 0
	global_load_lds_dwordx4 v186, s[60:61]
	s_waitcnt vmcnt(6)
	s_barrier
	v_mfma_f32_16x16x32_bf16 v[36:39], v[200:203], v[132:135], 0
	v_mfma_f32_16x16x32_bf16 v[32:35], v[212:215], v[132:135], 0
	v_mfma_f32_16x16x32_bf16 v[20:23], v[200:203], v[160:163], 0
	v_mfma_f32_16x16x32_bf16 v[16:19], v[212:215], v[160:163], 0
	v_mfma_f32_16x16x32_bf16 v[4:7], v[200:203], v[192:195], 0
	v_mfma_f32_16x16x32_bf16 v[0:3], v[212:215], v[192:195], 0
	v_mfma_f32_16x16x32_bf16 v[48:51], v[200:203], v[116:119], 0
	v_mfma_f32_16x16x32_bf16 v[52:55], v[212:215], v[116:119], 0
	v_mfma_f32_16x16x32_bf16 v[36:39], v[208:211], v[144:147], v[36:39]
	v_mfma_f32_16x16x32_bf16 v[32:35], v[216:219], v[144:147], v[32:35]
	v_mfma_f32_16x16x32_bf16 v[20:23], v[208:211], v[164:167], v[20:23]
	v_mfma_f32_16x16x32_bf16 v[16:19], v[216:219], v[164:167], v[16:19]
	v_mfma_f32_16x16x32_bf16 v[4:7], v[208:211], v[196:199], v[4:7]
	v_mfma_f32_16x16x32_bf16 v[0:3], v[216:219], v[196:199], v[0:3]
	v_mfma_f32_16x16x32_bf16 v[48:51], v[208:211], v[128:131], v[48:51]
	v_mfma_f32_16x16x32_bf16 v[52:55], v[216:219], v[128:131], v[52:55]
	s_barrier
	ds_read_b128 v[56:59], v206 offset:32768
	ds_read_b128 v[60:63], v206 offset:33792
	ds_read_b128 v[64:67], v206 offset:34816
	ds_read_b128 v[68:71], v206 offset:35840
	ds_read_b128 v[116:119], v207 offset:32768
	ds_read_b128 v[128:131], v207 offset:33792
	ds_read_b128 v[160:163], v207 offset:34816
	ds_read_b128 v[164:167], v207 offset:35840
	ds_read_b128 v[192:195], v207 offset:36864
	ds_read_b128 v[196:199], v207 offset:37888
	ds_read_b128 v[200:203], v207 offset:38912
	ds_read_b128 v[208:211], v207 offset:39936
	s_barrier
	s_waitcnt lgkmcnt(0)
	v_mfma_f32_16x16x32_bf16 v[132:135], v[56:59], v[116:119], v[156:159]
	v_mfma_f32_16x16x32_bf16 v[156:159], v[60:63], v[128:131], v[132:135]
	v_mfma_f32_16x16x32_bf16 v[132:135], v[64:67], v[116:119], v[152:155]
	v_mfma_f32_16x16x32_bf16 v[152:155], v[68:71], v[128:131], v[132:135]
	v_mfma_f32_16x16x32_bf16 v[132:135], v[56:59], v[160:163], v[140:143]
	v_mfma_f32_16x16x32_bf16 v[140:143], v[60:63], v[164:167], v[132:135]
	v_mfma_f32_16x16x32_bf16 v[132:135], v[64:67], v[160:163], v[136:139]
	v_mfma_f32_16x16x32_bf16 v[124:127], v[56:59], v[192:195], v[124:127]
	v_mfma_f32_16x16x32_bf16 v[120:123], v[64:67], v[192:195], v[120:123]
	v_mfma_f32_16x16x32_bf16 v[108:111], v[56:59], v[200:203], v[108:111]
	v_mfma_f32_16x16x32_bf16 v[104:107], v[64:67], v[200:203], v[104:107]
	v_mfma_f32_16x16x32_bf16 v[136:139], v[68:71], v[164:167], v[132:135]
	v_mfma_f32_16x16x32_bf16 v[124:127], v[60:63], v[196:199], v[124:127]
	v_mfma_f32_16x16x32_bf16 v[120:123], v[68:71], v[196:199], v[120:123]
	v_mfma_f32_16x16x32_bf16 v[108:111], v[60:63], v[208:211], v[108:111]
	v_mfma_f32_16x16x32_bf16 v[104:107], v[68:71], v[208:211], v[104:107]
	s_barrier
	s_mov_b32 m0, s43
	ds_read_b128 v[212:215], v206 offset:49152
	ds_read_b128 v[216:219], v206 offset:50176
	ds_read_b128 v[220:223], v206 offset:51200
	global_load_lds_dwordx4 v180, s[28:29]
	s_mov_b32 m0, s44
	ds_read_b128 v[236:239], v206 offset:52224
	global_load_lds_dwordx4 v184, s[28:29]
	s_barrier
	s_waitcnt lgkmcnt(0)
	v_mfma_f32_16x16x32_bf16 v[72:75], v[220:223], v[116:119], v[72:75]
	v_mfma_f32_16x16x32_bf16 v[132:135], v[212:215], v[116:119], v[148:151]
	v_mfma_f32_16x16x32_bf16 v[144:147], v[236:239], v[128:131], v[72:75]
	v_mfma_f32_16x16x32_bf16 v[72:75], v[212:215], v[160:163], v[76:79]
	v_mfma_f32_16x16x32_bf16 v[148:151], v[216:219], v[128:131], v[132:135]
	v_mfma_f32_16x16x32_bf16 v[132:135], v[216:219], v[164:167], v[72:75]
	v_mfma_f32_16x16x32_bf16 v[72:75], v[220:223], v[160:163], v[80:83]
	v_mfma_f32_16x16x32_bf16 v[128:131], v[236:239], v[164:167], v[72:75]
	v_mfma_f32_16x16x32_bf16 v[72:75], v[212:215], v[192:195], v[84:87]
	v_mfma_f32_16x16x32_bf16 v[116:119], v[216:219], v[196:199], v[72:75]
	v_mfma_f32_16x16x32_bf16 v[72:75], v[220:223], v[192:195], v[112:115]
	v_mfma_f32_16x16x32_bf16 v[112:115], v[236:239], v[196:199], v[72:75]
	v_mfma_f32_16x16x32_bf16 v[72:75], v[212:215], v[200:203], v[100:103]
	v_mfma_f32_16x16x32_bf16 v[100:103], v[216:219], v[208:211], v[72:75]
	v_mfma_f32_16x16x32_bf16 v[72:75], v[220:223], v[200:203], v[96:99]
	v_mfma_f32_16x16x32_bf16 v[96:99], v[236:239], v[208:211], v[72:75]
	s_barrier
	s_nop 2
	ds_read_b128 v[72:75], v207 offset:49152
	ds_read_b128 v[76:79], v207 offset:50176
	ds_read_b128 v[80:83], v207 offset:51200
	ds_read_b128 v[84:87], v207 offset:52224
	ds_read_b128 v[160:163], v207 offset:53248
	ds_read_b128 v[164:167], v207 offset:54272
	ds_read_b128 v[192:195], v207 offset:55296
	ds_read_b128 v[196:199], v207 offset:56320
	s_add_i32 m0, s40, 0x18000
	s_nop 0
	global_load_lds_dwordx4 v182, s[98:99]
	s_add_i32 m0, s40, 0x1a000
	s_nop 0
	global_load_lds_dwordx4 v186, s[98:99]
	s_barrier
	s_waitcnt lgkmcnt(0)
	v_mfma_f32_16x16x32_bf16 v[92:95], v[56:59], v[72:75], v[92:95]
	v_mfma_f32_16x16x32_bf16 v[88:91], v[64:67], v[72:75], v[88:91]
	v_mfma_f32_16x16x32_bf16 v[44:47], v[56:59], v[80:83], v[44:47]
	v_mfma_f32_16x16x32_bf16 v[40:43], v[64:67], v[80:83], v[40:43]
	v_mfma_f32_16x16x32_bf16 v[28:31], v[56:59], v[160:163], v[28:31]
	v_mfma_f32_16x16x32_bf16 v[24:27], v[64:67], v[160:163], v[24:27]
	v_mfma_f32_16x16x32_bf16 v[12:15], v[56:59], v[192:195], v[12:15]
	v_mfma_f32_16x16x32_bf16 v[8:11], v[64:67], v[192:195], v[8:11]
	v_mfma_f32_16x16x32_bf16 v[92:95], v[60:63], v[76:79], v[92:95]
	v_mfma_f32_16x16x32_bf16 v[88:91], v[68:71], v[76:79], v[88:91]
	v_mfma_f32_16x16x32_bf16 v[44:47], v[60:63], v[84:87], v[44:47]
	v_mfma_f32_16x16x32_bf16 v[40:43], v[68:71], v[84:87], v[40:43]
	v_mfma_f32_16x16x32_bf16 v[28:31], v[60:63], v[164:167], v[28:31]
	v_mfma_f32_16x16x32_bf16 v[24:27], v[68:71], v[164:167], v[24:27]
	v_mfma_f32_16x16x32_bf16 v[12:15], v[60:63], v[196:199], v[12:15]
	v_mfma_f32_16x16x32_bf16 v[8:11], v[68:71], v[196:199], v[8:11]
	s_barrier
	s_mov_b32 m0, s53
	s_nop 0
	global_load_lds_dwordx4 v180, s[100:101]
	s_mov_b32 m0, s54
	s_nop 0
	global_load_lds_dwordx4 v184, s[100:101]
	s_add_i32 m0, s40, 0x1c000
	s_add_u32 s2, s2, 0x40080
	s_addc_u32 s3, s3, 0
	global_load_lds_dwordx4 v182, s[2:3]
	s_add_i32 m0, s40, 0x1e000
	s_add_i32 s58, s58, 2
	global_load_lds_dwordx4 v186, s[2:3]
	s_waitcnt vmcnt(6)
	s_barrier
	v_mfma_f32_16x16x32_bf16 v[48:51], v[212:215], v[72:75], v[48:51]
	v_mfma_f32_16x16x32_bf16 v[64:67], v[216:219], v[76:79], v[48:51]
	v_mfma_f32_16x16x32_bf16 v[48:51], v[220:223], v[72:75], v[52:55]
	v_mfma_f32_16x16x32_bf16 v[36:39], v[212:215], v[80:83], v[36:39]
	v_mfma_f32_16x16x32_bf16 v[32:35], v[220:223], v[80:83], v[32:35]
	v_mfma_f32_16x16x32_bf16 v[20:23], v[212:215], v[160:163], v[20:23]
	v_mfma_f32_16x16x32_bf16 v[16:19], v[220:223], v[160:163], v[16:19]
	v_mfma_f32_16x16x32_bf16 v[4:7], v[212:215], v[192:195], v[4:7]
	v_mfma_f32_16x16x32_bf16 v[0:3], v[220:223], v[192:195], v[0:3]
	v_mfma_f32_16x16x32_bf16 v[56:59], v[236:239], v[76:79], v[48:51]
	v_mfma_f32_16x16x32_bf16 v[36:39], v[216:219], v[84:87], v[36:39]
	v_mfma_f32_16x16x32_bf16 v[32:35], v[236:239], v[84:87], v[32:35]
	v_mfma_f32_16x16x32_bf16 v[20:23], v[216:219], v[164:167], v[20:23]
	v_mfma_f32_16x16x32_bf16 v[16:19], v[236:239], v[164:167], v[16:19]
	v_mfma_f32_16x16x32_bf16 v[4:7], v[216:219], v[196:199], v[4:7]
	v_mfma_f32_16x16x32_bf16 v[0:3], v[236:239], v[196:199], v[0:3]
	s_add_u32 s8, s8, 0x100
	s_addc_u32 s9, s9, 0
	s_add_u32 s56, s56, 0x100
	s_addc_u32 s57, s57, 0
	s_cmp_gt_u32 s58, 13
	s_barrier
.LBB0_678:
	s_add_u32 s2, s8, 0xfffc0080
	s_addc_u32 s3, s9, -1
	ds_read_b128 v[48:51], v206
	ds_read_b128 v[52:55], v206 offset:1024
	ds_read_b128 v[60:63], v206 offset:2048
	ds_read_b128 v[68:71], v206 offset:3072
	s_cmp_eq_u32 s58, 12
	s_cselect_b32 s29, s1, s3
	s_cselect_b32 s28, s7, s2
	s_cselect_b32 s3, s21, s57
	s_cselect_b32 s2, s23, s56
	ds_read_b128 v[72:75], v207
	ds_read_b128 v[76:79], v207 offset:1024
	ds_read_b128 v[80:83], v207 offset:2048
	ds_read_b128 v[84:87], v207 offset:3072
	ds_read_b128 v[160:163], v207 offset:4096
	ds_read_b128 v[164:167], v207 offset:5120
	ds_read_b128 v[192:195], v207 offset:6144
	ds_read_b128 v[196:199], v207 offset:7168
	s_barrier
	s_waitcnt lgkmcnt(0)
	v_mfma_f32_16x16x32_bf16 v[156:159], v[48:51], v[72:75], v[156:159]
	v_mfma_f32_16x16x32_bf16 v[152:155], v[60:63], v[72:75], v[152:155]
	v_mfma_f32_16x16x32_bf16 v[140:143], v[48:51], v[80:83], v[140:143]
	v_mfma_f32_16x16x32_bf16 v[136:139], v[60:63], v[80:83], v[136:139]
	v_mfma_f32_16x16x32_bf16 v[124:127], v[48:51], v[160:163], v[124:127]
	v_mfma_f32_16x16x32_bf16 v[120:123], v[60:63], v[160:163], v[120:123]
	v_mfma_f32_16x16x32_bf16 v[108:111], v[48:51], v[192:195], v[108:111]
	v_mfma_f32_16x16x32_bf16 v[104:107], v[60:63], v[192:195], v[104:107]
	v_mfma_f32_16x16x32_bf16 v[156:159], v[52:55], v[76:79], v[156:159]
	v_mfma_f32_16x16x32_bf16 v[152:155], v[68:71], v[76:79], v[152:155]
	v_mfma_f32_16x16x32_bf16 v[140:143], v[52:55], v[84:87], v[140:143]
	v_mfma_f32_16x16x32_bf16 v[136:139], v[68:71], v[84:87], v[136:139]
	v_mfma_f32_16x16x32_bf16 v[124:127], v[52:55], v[164:167], v[124:127]
	v_mfma_f32_16x16x32_bf16 v[120:123], v[68:71], v[164:167], v[120:123]
	v_mfma_f32_16x16x32_bf16 v[108:111], v[52:55], v[196:199], v[108:111]
	v_mfma_f32_16x16x32_bf16 v[104:107], v[68:71], v[196:199], v[104:107]
	s_barrier
	s_add_i32 m0, s41, 0xc000
	ds_read_b128 v[200:203], v206 offset:16384
	ds_read_b128 v[208:211], v206 offset:17408
	ds_read_b128 v[212:215], v206 offset:18432
	global_load_lds_dwordx4 v188, s[8:9]
	s_add_i32 m0, s41, 0xe000
	ds_read_b128 v[216:219], v206 offset:19456
	global_load_lds_dwordx4 v190, s[8:9]
	s_add_u32 s98, s2, 0x80
	s_addc_u32 s99, s3, 0
	s_barrier
	s_waitcnt lgkmcnt(0)
	v_mfma_f32_16x16x32_bf16 v[148:151], v[200:203], v[72:75], v[148:151]
	v_mfma_f32_16x16x32_bf16 v[72:75], v[212:215], v[72:75], v[144:147]
	v_mfma_f32_16x16x32_bf16 v[148:151], v[208:211], v[76:79], v[148:151]
	v_mfma_f32_16x16x32_bf16 v[72:75], v[216:219], v[76:79], v[72:75]
	v_mfma_f32_16x16x32_bf16 v[76:79], v[200:203], v[80:83], v[132:135]
	v_mfma_f32_16x16x32_bf16 v[80:83], v[212:215], v[80:83], v[128:131]
	v_mfma_f32_16x16x32_bf16 v[112:115], v[212:215], v[160:163], v[112:115]
	v_mfma_f32_16x16x32_bf16 v[100:103], v[200:203], v[192:195], v[100:103]
	v_mfma_f32_16x16x32_bf16 v[96:99], v[212:215], v[192:195], v[96:99]
	v_mfma_f32_16x16x32_bf16 v[76:79], v[208:211], v[84:87], v[76:79]
	v_mfma_f32_16x16x32_bf16 v[80:83], v[216:219], v[84:87], v[80:83]
	v_mfma_f32_16x16x32_bf16 v[84:87], v[200:203], v[160:163], v[116:119]
	v_mfma_f32_16x16x32_bf16 v[112:115], v[216:219], v[164:167], v[112:115]
	v_mfma_f32_16x16x32_bf16 v[100:103], v[208:211], v[196:199], v[100:103]
	v_mfma_f32_16x16x32_bf16 v[96:99], v[216:219], v[196:199], v[96:99]
	v_mfma_f32_16x16x32_bf16 v[84:87], v[208:211], v[164:167], v[84:87]
	s_add_u32 s100, s28, 0x80
	s_addc_u32 s101, s29, 0
	s_barrier
	ds_read_b128 v[116:119], v207 offset:16384
	ds_read_b128 v[128:131], v207 offset:17408
	ds_read_b128 v[132:135], v207 offset:18432
	ds_read_b128 v[144:147], v207 offset:19456
	ds_read_b128 v[160:163], v207 offset:20480
	ds_read_b128 v[164:167], v207 offset:21504
	ds_read_b128 v[192:195], v207 offset:22528
	ds_read_b128 v[196:199], v207 offset:23552
	s_add_i32 m0, s40, 0x10000
	s_nop 0
	global_load_lds_dwordx4 v182, s[2:3]
	s_add_i32 m0, s40, 0x12000
	s_nop 0
	global_load_lds_dwordx4 v186, s[2:3]
	s_barrier
	s_waitcnt lgkmcnt(0)
	v_mfma_f32_16x16x32_bf16 v[92:95], v[48:51], v[116:119], v[92:95]
	v_mfma_f32_16x16x32_bf16 v[88:91], v[60:63], v[116:119], v[88:91]
	v_mfma_f32_16x16x32_bf16 v[44:47], v[48:51], v[132:135], v[44:47]
	v_mfma_f32_16x16x32_bf16 v[40:43], v[60:63], v[132:135], v[40:43]
	v_mfma_f32_16x16x32_bf16 v[28:31], v[48:51], v[160:163], v[28:31]
	v_mfma_f32_16x16x32_bf16 v[24:27], v[60:63], v[160:163], v[24:27]
	v_mfma_f32_16x16x32_bf16 v[12:15], v[48:51], v[192:195], v[12:15]
	v_mfma_f32_16x16x32_bf16 v[8:11], v[60:63], v[192:195], v[8:11]
	v_mfma_f32_16x16x32_bf16 v[92:95], v[52:55], v[128:131], v[92:95]
	v_mfma_f32_16x16x32_bf16 v[88:91], v[68:71], v[128:131], v[88:91]
	v_mfma_f32_16x16x32_bf16 v[44:47], v[52:55], v[144:147], v[44:47]
	v_mfma_f32_16x16x32_bf16 v[40:43], v[68:71], v[144:147], v[40:43]
	v_mfma_f32_16x16x32_bf16 v[28:31], v[52:55], v[164:167], v[28:31]
	v_mfma_f32_16x16x32_bf16 v[24:27], v[68:71], v[164:167], v[24:27]
	v_mfma_f32_16x16x32_bf16 v[12:15], v[52:55], v[196:199], v[12:15]
	v_mfma_f32_16x16x32_bf16 v[8:11], v[68:71], v[196:199], v[8:11]
	s_barrier
	s_mov_b32 m0, s41
	s_nop 0
	global_load_lds_dwordx4 v180, s[28:29]
	s_mov_b32 m0, s42
	s_nop 0
	global_load_lds_dwordx4 v184, s[28:29]
	s_add_i32 m0, s40, 0x14000
	s_add_u32 s60, s2, 0x40000
	s_addc_u32 s61, s3, 0
	global_load_lds_dwordx4 v182, s[60:61]
	s_add_i32 m0, s40, 0x16000
	s_add_u32 s28, s28, 0x40000
	s_addc_u32 s29, s29, 0
	global_load_lds_dwordx4 v186, s[60:61]
	s_waitcnt vmcnt(6)
	s_barrier
	v_mfma_f32_16x16x32_bf16 v[36:39], v[200:203], v[132:135], v[36:39]
	v_mfma_f32_16x16x32_bf16 v[32:35], v[212:215], v[132:135], v[32:35]
	v_mfma_f32_16x16x32_bf16 v[20:23], v[200:203], v[160:163], v[20:23]
	v_mfma_f32_16x16x32_bf16 v[16:19], v[212:215], v[160:163], v[16:19]
	v_mfma_f32_16x16x32_bf16 v[4:7], v[200:203], v[192:195], v[4:7]
	v_mfma_f32_16x16x32_bf16 v[0:3], v[212:215], v[192:195], v[0:3]
	v_mfma_f32_16x16x32_bf16 v[48:51], v[200:203], v[116:119], v[64:67]
	v_mfma_f32_16x16x32_bf16 v[52:55], v[212:215], v[116:119], v[56:59]
	v_mfma_f32_16x16x32_bf16 v[36:39], v[208:211], v[144:147], v[36:39]
	v_mfma_f32_16x16x32_bf16 v[32:35], v[216:219], v[144:147], v[32:35]
	v_mfma_f32_16x16x32_bf16 v[20:23], v[208:211], v[164:167], v[20:23]
	v_mfma_f32_16x16x32_bf16 v[16:19], v[216:219], v[164:167], v[16:19]
	v_mfma_f32_16x16x32_bf16 v[4:7], v[208:211], v[196:199], v[4:7]
	v_mfma_f32_16x16x32_bf16 v[0:3], v[216:219], v[196:199], v[0:3]
	v_mfma_f32_16x16x32_bf16 v[48:51], v[208:211], v[128:131], v[48:51]
	v_mfma_f32_16x16x32_bf16 v[52:55], v[216:219], v[128:131], v[52:55]
	s_barrier
	ds_read_b128 v[56:59], v206 offset:32768
	ds_read_b128 v[60:63], v206 offset:33792
	ds_read_b128 v[64:67], v206 offset:34816
	ds_read_b128 v[68:71], v206 offset:35840
	ds_read_b128 v[116:119], v207 offset:32768
	ds_read_b128 v[128:131], v207 offset:33792
	ds_read_b128 v[160:163], v207 offset:34816
	ds_read_b128 v[164:167], v207 offset:35840
	ds_read_b128 v[192:195], v207 offset:36864
	ds_read_b128 v[196:199], v207 offset:37888
	ds_read_b128 v[200:203], v207 offset:38912
	ds_read_b128 v[208:211], v207 offset:39936
	s_barrier
	s_waitcnt lgkmcnt(0)
	v_mfma_f32_16x16x32_bf16 v[132:135], v[56:59], v[116:119], v[156:159]
	v_mfma_f32_16x16x32_bf16 v[156:159], v[60:63], v[128:131], v[132:135]
	v_mfma_f32_16x16x32_bf16 v[132:135], v[64:67], v[116:119], v[152:155]
	v_mfma_f32_16x16x32_bf16 v[152:155], v[68:71], v[128:131], v[132:135]
	v_mfma_f32_16x16x32_bf16 v[132:135], v[56:59], v[160:163], v[140:143]
	v_mfma_f32_16x16x32_bf16 v[140:143], v[60:63], v[164:167], v[132:135]
	v_mfma_f32_16x16x32_bf16 v[132:135], v[64:67], v[160:163], v[136:139]
	v_mfma_f32_16x16x32_bf16 v[124:127], v[56:59], v[192:195], v[124:127]
	v_mfma_f32_16x16x32_bf16 v[120:123], v[64:67], v[192:195], v[120:123]
	v_mfma_f32_16x16x32_bf16 v[108:111], v[56:59], v[200:203], v[108:111]
	v_mfma_f32_16x16x32_bf16 v[104:107], v[64:67], v[200:203], v[104:107]
	v_mfma_f32_16x16x32_bf16 v[136:139], v[68:71], v[164:167], v[132:135]
	v_mfma_f32_16x16x32_bf16 v[124:127], v[60:63], v[196:199], v[124:127]
	v_mfma_f32_16x16x32_bf16 v[120:123], v[68:71], v[196:199], v[120:123]
	v_mfma_f32_16x16x32_bf16 v[108:111], v[60:63], v[208:211], v[108:111]
	v_mfma_f32_16x16x32_bf16 v[104:107], v[68:71], v[208:211], v[104:107]
	s_barrier
	s_mov_b32 m0, s43
	ds_read_b128 v[212:215], v206 offset:49152
	ds_read_b128 v[216:219], v206 offset:50176
	ds_read_b128 v[220:223], v206 offset:51200
	global_load_lds_dwordx4 v180, s[28:29]
	s_mov_b32 m0, s44
	ds_read_b128 v[236:239], v206 offset:52224
	global_load_lds_dwordx4 v184, s[28:29]
	s_barrier
	s_waitcnt lgkmcnt(0)
	v_mfma_f32_16x16x32_bf16 v[72:75], v[220:223], v[116:119], v[72:75]
	v_mfma_f32_16x16x32_bf16 v[132:135], v[212:215], v[116:119], v[148:151]
	v_mfma_f32_16x16x32_bf16 v[144:147], v[236:239], v[128:131], v[72:75]
	v_mfma_f32_16x16x32_bf16 v[72:75], v[212:215], v[160:163], v[76:79]
	v_mfma_f32_16x16x32_bf16 v[148:151], v[216:219], v[128:131], v[132:135]
	v_mfma_f32_16x16x32_bf16 v[132:135], v[216:219], v[164:167], v[72:75]
	v_mfma_f32_16x16x32_bf16 v[72:75], v[220:223], v[160:163], v[80:83]
	v_mfma_f32_16x16x32_bf16 v[128:131], v[236:239], v[164:167], v[72:75]
	v_mfma_f32_16x16x32_bf16 v[72:75], v[212:215], v[192:195], v[84:87]
	v_mfma_f32_16x16x32_bf16 v[116:119], v[216:219], v[196:199], v[72:75]
	v_mfma_f32_16x16x32_bf16 v[72:75], v[220:223], v[192:195], v[112:115]
	v_mfma_f32_16x16x32_bf16 v[112:115], v[236:239], v[196:199], v[72:75]
	v_mfma_f32_16x16x32_bf16 v[72:75], v[212:215], v[200:203], v[100:103]
	v_mfma_f32_16x16x32_bf16 v[100:103], v[216:219], v[208:211], v[72:75]
	v_mfma_f32_16x16x32_bf16 v[72:75], v[220:223], v[200:203], v[96:99]
	v_mfma_f32_16x16x32_bf16 v[96:99], v[236:239], v[208:211], v[72:75]
	s_barrier
	s_nop 2
	ds_read_b128 v[72:75], v207 offset:49152
	ds_read_b128 v[76:79], v207 offset:50176
	ds_read_b128 v[80:83], v207 offset:51200
	ds_read_b128 v[84:87], v207 offset:52224
	ds_read_b128 v[160:163], v207 offset:53248
	ds_read_b128 v[164:167], v207 offset:54272
	ds_read_b128 v[192:195], v207 offset:55296
	ds_read_b128 v[196:199], v207 offset:56320
	s_add_i32 m0, s40, 0x18000
	s_nop 0
	global_load_lds_dwordx4 v182, s[98:99]
	s_add_i32 m0, s40, 0x1a000
	s_nop 0
	global_load_lds_dwordx4 v186, s[98:99]
	s_barrier
	s_waitcnt lgkmcnt(0)
	v_mfma_f32_16x16x32_bf16 v[92:95], v[56:59], v[72:75], v[92:95]
	v_mfma_f32_16x16x32_bf16 v[88:91], v[64:67], v[72:75], v[88:91]
	v_mfma_f32_16x16x32_bf16 v[44:47], v[56:59], v[80:83], v[44:47]
	v_mfma_f32_16x16x32_bf16 v[40:43], v[64:67], v[80:83], v[40:43]
	v_mfma_f32_16x16x32_bf16 v[28:31], v[56:59], v[160:163], v[28:31]
	v_mfma_f32_16x16x32_bf16 v[24:27], v[64:67], v[160:163], v[24:27]
	v_mfma_f32_16x16x32_bf16 v[12:15], v[56:59], v[192:195], v[12:15]
	v_mfma_f32_16x16x32_bf16 v[8:11], v[64:67], v[192:195], v[8:11]
	v_mfma_f32_16x16x32_bf16 v[92:95], v[60:63], v[76:79], v[92:95]
	v_mfma_f32_16x16x32_bf16 v[88:91], v[68:71], v[76:79], v[88:91]
	v_mfma_f32_16x16x32_bf16 v[44:47], v[60:63], v[84:87], v[44:47]
	v_mfma_f32_16x16x32_bf16 v[40:43], v[68:71], v[84:87], v[40:43]
	v_mfma_f32_16x16x32_bf16 v[28:31], v[60:63], v[164:167], v[28:31]
	v_mfma_f32_16x16x32_bf16 v[24:27], v[68:71], v[164:167], v[24:27]
	v_mfma_f32_16x16x32_bf16 v[12:15], v[60:63], v[196:199], v[12:15]
	v_mfma_f32_16x16x32_bf16 v[8:11], v[68:71], v[196:199], v[8:11]
	s_barrier
	s_mov_b32 m0, s53
	s_nop 0
	global_load_lds_dwordx4 v180, s[100:101]
	s_mov_b32 m0, s54
	s_nop 0
	global_load_lds_dwordx4 v184, s[100:101]
	s_add_i32 m0, s40, 0x1c000
	s_add_u32 s2, s2, 0x40080
	s_addc_u32 s3, s3, 0
	global_load_lds_dwordx4 v182, s[2:3]
	s_add_i32 m0, s40, 0x1e000
	s_add_i32 s58, s58, 2
	global_load_lds_dwordx4 v186, s[2:3]
	s_waitcnt vmcnt(6)
	s_barrier
	v_mfma_f32_16x16x32_bf16 v[48:51], v[212:215], v[72:75], v[48:51]
	v_mfma_f32_16x16x32_bf16 v[64:67], v[216:219], v[76:79], v[48:51]
	v_mfma_f32_16x16x32_bf16 v[48:51], v[220:223], v[72:75], v[52:55]
	v_mfma_f32_16x16x32_bf16 v[36:39], v[212:215], v[80:83], v[36:39]
	v_mfma_f32_16x16x32_bf16 v[32:35], v[220:223], v[80:83], v[32:35]
	v_mfma_f32_16x16x32_bf16 v[20:23], v[212:215], v[160:163], v[20:23]
	v_mfma_f32_16x16x32_bf16 v[16:19], v[220:223], v[160:163], v[16:19]
	v_mfma_f32_16x16x32_bf16 v[4:7], v[212:215], v[192:195], v[4:7]
	v_mfma_f32_16x16x32_bf16 v[0:3], v[220:223], v[192:195], v[0:3]
	v_mfma_f32_16x16x32_bf16 v[56:59], v[236:239], v[76:79], v[48:51]
	v_mfma_f32_16x16x32_bf16 v[36:39], v[216:219], v[84:87], v[36:39]
	v_mfma_f32_16x16x32_bf16 v[32:35], v[236:239], v[84:87], v[32:35]
	v_mfma_f32_16x16x32_bf16 v[20:23], v[216:219], v[164:167], v[20:23]
	v_mfma_f32_16x16x32_bf16 v[16:19], v[236:239], v[164:167], v[16:19]
	v_mfma_f32_16x16x32_bf16 v[4:7], v[216:219], v[196:199], v[4:7]
	v_mfma_f32_16x16x32_bf16 v[0:3], v[236:239], v[196:199], v[0:3]
	s_add_u32 s8, s8, 0x100
	s_addc_u32 s9, s9, 0
	s_add_u32 s56, s56, 0x100
	s_addc_u32 s57, s57, 0
	s_cmp_gt_u32 s58, 13
	s_barrier
	s_cbranch_scc0 .LBB0_678
	s_lshl_b32 s1, s0, 8
	s_add_i32 s2, s1, s51
	s_lshl_b32 s1, s6, 8
	v_mov_b32_e32 v160, v205
	v_mov_b32_e32 v208, v204
	s_or_b32 s1, s1, s52
	s_nop 0
	v_lshl_add_u32 v192, v208, 3, s1
	s_add_i32 s1, s0, -16
	s_lshr_b32 s1, s1, 3
	s_add_i32 s1, s1, 1
	s_cmp_gt_i32 s0, 15
	s_cselect_b32 s3, s1, 0
	s_mul_i32 s96, s3, 0x1800
	s_lshl_b64 s[0:1], s[96:97], 2
	s_add_u32 s0, s45, s0
	v_ashrrev_i32_e32 v193, 31, v192
	s_addc_u32 s1, s46, s1
	v_lshlrev_b64 v[196:197], 2, v[192:193]
	s_lshl_b32 s96, s3, 10
	v_lshl_add_u64 v[48:49], s[0:1], 0, v[196:197]
	s_lshl_b64 s[0:1], s[96:97], 2
	s_add_u32 s0, s49, s0
	s_addc_u32 s1, s50, s1
	v_lshl_add_u64 v[52:53], s[0:1], 0, v[196:197]
	global_load_dwordx4 v[80:83], v[48:49], off offset:16
	global_load_dwordx4 v[84:87], v[48:49], off
	global_load_dwordx4 v[72:75], v[52:53], off offset:16
	global_load_dwordx4 v[76:79], v[52:53], off
	global_load_dwordx4 v[60:63], v[48:49], off offset:528
	global_load_dwordx4 v[68:71], v[48:49], off offset:512
	s_nop 0
	global_load_dwordx4 v[48:51], v[52:53], off offset:528
	s_nop 0
	global_load_dwordx4 v[52:55], v[52:53], off offset:512
	v_add_u32_e32 v194, s2, v160
	v_ashrrev_i32_e32 v195, 31, v194
	v_lshlrev_b64 v[160:161], 10, v[194:195]
	v_lshl_add_u64 v[198:199], v[160:161], 0, v[192:193]
	v_cndmask_b32_e64 v160, 0, 1, s[74:75]
	v_cmp_gt_i32_e64 s[0:1], s71, v194
	v_cmp_ne_u32_e64 s[6:7], 1, v160
	s_andn2_b64 vcc, exec, s[74:75]
	s_mov_b64 s[2:3], -1
	s_cbranch_vccnz .LBB0_681
	v_lshl_add_u64 v[160:161], v[198:199], 1, s[14:15]
	v_mov_b32_e32 v222, v160
	v_mov_b32_e32 v223, v161
	global_load_dwordx4 v[210:213], v[222:223], off
	global_load_dwordx4 v[214:217], v[222:223], off offset:256
	s_mov_b64 s[80:81], 0x8000
	v_lshl_add_u64 v[222:223], v[222:223], 0, s[80:81]
	global_load_dwordx4 v[218:221], v[222:223], off
	global_load_dwordx4 v[236:239], v[222:223], off offset:256
	s_mov_b64 s[2:3], 0
	s_waitcnt vmcnt(3)
	v_lshlrev_b32_e32 v164, 16, v210
	v_and_b32_e32 v165, 0xffff0000, v210
	v_lshlrev_b32_e32 v166, 16, v211
	v_and_b32_e32 v167, 0xffff0000, v211
	v_lshlrev_b32_e32 v160, 16, v212
	v_and_b32_e32 v161, 0xffff0000, v212
	v_lshlrev_b32_e32 v162, 16, v213
	v_and_b32_e32 v163, 0xffff0000, v213
	s_mov_b64 s[80:81], 0x8000
	v_lshl_add_u64 v[222:223], v[222:223], 0, s[80:81]
	global_load_dwordx4 v[210:213], v[222:223], off

.LBB0_879:
	s_ashr_i32 s39, s38, 31
	v_cmp_lt_i64_e32 vcc, s[12:13], v[178:179]
	s_lshl_b64 s[12:13], s[38:39], 19
	s_add_u32 s40, s49, s12
	s_addc_u32 s41, s50, s13
	s_lshl_b32 s84, s82, 18
	s_add_u32 s40, s40, s84
	s_addc_u32 s41, s41, 0
	s_and_b64 s[12:13], vcc, exec
	s_cselect_b32 s1, s41, s11
	s_cselect_b32 s9, s40, s10
	s_ashr_i32 s37, s36, 31
	s_lshl_b64 s[12:13], s[36:37], 19
	s_add_u32 s42, s51, s12
	s_addc_u32 s43, s52, s13
	s_and_b64 s[12:13], vcc, exec
	s_cselect_b32 s14, s43, s3
	s_cselect_b32 s15, s42, s2
	s_add_u32 s10, s10, 0x40080
	s_addc_u32 s11, s11, 0
	s_add_u32 s37, s2, 0x100
	s_addc_u32 s39, s3, 0
	s_mov_b32 s67, -2
	s_cmp_lg_u32 s83, 0
	s_cbranch_scc1 .Lup_half_peel
	s_add_u32 s2, s10, 0xfffc0080
	s_addc_u32 s3, s11, -1
	ds_read_b128 v[48:51], v237
	ds_read_b128 v[52:55], v237 offset:1024
	ds_read_b128 v[104:107], v237 offset:2048
	ds_read_b128 v[108:111], v237 offset:3072
	s_cmp_eq_u32 s67, 12
	s_cselect_b32 s13, s1, s3
	s_cselect_b32 s12, s9, s2
	s_cselect_b32 s3, s14, s39
	s_cselect_b32 s2, s15, s37
	ds_read_b128 v[112:115], v238
	ds_read_b128 v[116:119], v238 offset:1024
	ds_read_b128 v[120:123], v238 offset:2048
	ds_read_b128 v[156:159], v238 offset:3072
	ds_read_b128 v[160:163], v238 offset:4096
	ds_read_b128 v[164:167], v238 offset:5120
	ds_read_b128 v[190:193], v238 offset:6144
	ds_read_b128 v[194:197], v238 offset:7168
	s_barrier
	s_waitcnt lgkmcnt(0)
	v_mfma_f32_16x16x32_bf16 v[152:155], v[48:51], v[112:115], 0
	v_mfma_f32_16x16x32_bf16 v[68:71], v[104:107], v[112:115], 0
	v_mfma_f32_16x16x32_bf16 v[148:151], v[48:51], v[120:123], 0
	v_mfma_f32_16x16x32_bf16 v[64:67], v[104:107], v[120:123], 0
	v_mfma_f32_16x16x32_bf16 v[136:139], v[48:51], v[160:163], 0
	v_mfma_f32_16x16x32_bf16 v[44:47], v[104:107], v[160:163], 0
	v_mfma_f32_16x16x32_bf16 v[128:131], v[48:51], v[190:193], 0
	v_mfma_f32_16x16x32_bf16 v[40:43], v[104:107], v[190:193], 0
	v_mfma_f32_16x16x32_bf16 v[152:155], v[52:55], v[116:119], v[152:155]
	v_mfma_f32_16x16x32_bf16 v[68:71], v[108:111], v[116:119], v[68:71]
	v_mfma_f32_16x16x32_bf16 v[148:151], v[52:55], v[156:159], v[148:151]
	v_mfma_f32_16x16x32_bf16 v[64:67], v[108:111], v[156:159], v[64:67]
	v_mfma_f32_16x16x32_bf16 v[136:139], v[52:55], v[164:167], v[136:139]
	v_mfma_f32_16x16x32_bf16 v[44:47], v[108:111], v[164:167], v[44:47]
	v_mfma_f32_16x16x32_bf16 v[128:131], v[52:55], v[194:197], v[128:131]
	v_mfma_f32_16x16x32_bf16 v[40:43], v[108:111], v[194:197], v[40:43]
	s_barrier
	s_add_i32 m0, s54, 0xc000
	ds_read_b128 v[198:201], v237 offset:16384
	ds_read_b128 v[202:205], v237 offset:17408
	ds_read_b128 v[206:209], v237 offset:18432
	global_load_lds_dwordx4 v186, s[10:11]
	s_add_i32 m0, s54, 0xe000
	ds_read_b128 v[210:213], v237 offset:19456
	global_load_lds_dwordx4 v188, s[10:11]
	s_add_u32 s98, s2, 0x80
	s_addc_u32 s99, s3, 0
	s_barrier
	s_waitcnt lgkmcnt(0)
	v_mfma_f32_16x16x32_bf16 v[144:147], v[198:201], v[112:115], 0
	v_mfma_f32_16x16x32_bf16 v[60:63], v[206:209], v[112:115], 0
	v_mfma_f32_16x16x32_bf16 v[56:59], v[206:209], v[120:123], 0
	v_mfma_f32_16x16x32_bf16 v[36:39], v[206:209], v[160:163], 0
	v_mfma_f32_16x16x32_bf16 v[32:35], v[206:209], v[190:193], 0
	v_mfma_f32_16x16x32_bf16 v[144:147], v[202:205], v[116:119], v[144:147]
	v_mfma_f32_16x16x32_bf16 v[60:63], v[210:213], v[116:119], v[60:63]
	v_mfma_f32_16x16x32_bf16 v[112:115], v[198:201], v[120:123], 0
	v_mfma_f32_16x16x32_bf16 v[56:59], v[210:213], v[156:159], v[56:59]
	v_mfma_f32_16x16x32_bf16 v[116:119], v[198:201], v[160:163], 0
	v_mfma_f32_16x16x32_bf16 v[36:39], v[210:213], v[164:167], v[36:39]
	v_mfma_f32_16x16x32_bf16 v[120:123], v[198:201], v[190:193], 0
	v_mfma_f32_16x16x32_bf16 v[32:35], v[210:213], v[194:197], v[32:35]
	v_mfma_f32_16x16x32_bf16 v[112:115], v[202:205], v[156:159], v[112:115]
	v_mfma_f32_16x16x32_bf16 v[116:119], v[202:205], v[164:167], v[116:119]
	v_mfma_f32_16x16x32_bf16 v[120:123], v[202:205], v[194:197], v[120:123]
	s_add_u32 s100, s12, 0x80
	s_addc_u32 s101, s13, 0
	s_barrier
	ds_read_b128 v[124:127], v238 offset:16384
	ds_read_b128 v[132:135], v238 offset:17408
	ds_read_b128 v[140:143], v238 offset:18432
	ds_read_b128 v[156:159], v238 offset:19456
	ds_read_b128 v[160:163], v238 offset:20480
	ds_read_b128 v[164:167], v238 offset:21504
	ds_read_b128 v[190:193], v238 offset:22528
	ds_read_b128 v[194:197], v238 offset:23552
	s_add_i32 m0, s53, 0x10000
	s_nop 0
	global_load_lds_dwordx4 v168, s[2:3]
	s_add_i32 m0, s53, 0x12000
	s_nop 0
	global_load_lds_dwordx4 v184, s[2:3]
	s_barrier
	s_waitcnt lgkmcnt(0)
	v_mfma_f32_16x16x32_bf16 v[100:103], v[48:51], v[124:127], 0
	v_mfma_f32_16x16x32_bf16 v[28:31], v[104:107], v[124:127], 0
	v_mfma_f32_16x16x32_bf16 v[96:99], v[48:51], v[140:143], 0
	v_mfma_f32_16x16x32_bf16 v[24:27], v[104:107], v[140:143], 0
	v_mfma_f32_16x16x32_bf16 v[84:87], v[48:51], v[160:163], 0
	v_mfma_f32_16x16x32_bf16 v[12:15], v[104:107], v[160:163], 0
	v_mfma_f32_16x16x32_bf16 v[8:11], v[104:107], v[190:193], 0
	v_mfma_f32_16x16x32_bf16 v[100:103], v[52:55], v[132:135], v[100:103]
	v_mfma_f32_16x16x32_bf16 v[28:31], v[108:111], v[132:135], v[28:31]
	v_mfma_f32_16x16x32_bf16 v[96:99], v[52:55], v[156:159], v[96:99]
	v_mfma_f32_16x16x32_bf16 v[24:27], v[108:111], v[156:159], v[24:27]
	v_mfma_f32_16x16x32_bf16 v[84:87], v[52:55], v[164:167], v[84:87]
	v_mfma_f32_16x16x32_bf16 v[12:15], v[108:111], v[164:167], v[12:15]
	v_mfma_f32_16x16x32_bf16 v[48:51], v[48:51], v[190:193], 0
	v_mfma_f32_16x16x32_bf16 v[8:11], v[108:111], v[194:197], v[8:11]
	v_mfma_f32_16x16x32_bf16 v[48:51], v[52:55], v[194:197], v[48:51]
	s_barrier
	s_mov_b32 m0, s54
	s_nop 0
	global_load_lds_dwordx4 v180, s[12:13]
	s_mov_b32 m0, s55
	s_nop 0
	global_load_lds_dwordx4 v182, s[12:13]
	s_add_i32 m0, s53, 0x14000
	s_add_u32 s68, s2, 0x40000
	s_addc_u32 s69, s3, 0
	global_load_lds_dwordx4 v168, s[68:69]
	s_add_i32 m0, s53, 0x16000
	s_add_u32 s12, s12, 0x40000
	s_addc_u32 s13, s13, 0
	global_load_lds_dwordx4 v184, s[68:69]
	s_waitcnt vmcnt(6)
	s_barrier
	v_mfma_f32_16x16x32_bf16 v[76:79], v[198:201], v[140:143], 0
	v_mfma_f32_16x16x32_bf16 v[20:23], v[206:209], v[124:127], 0
	v_mfma_f32_16x16x32_bf16 v[88:91], v[202:205], v[156:159], v[76:79]
	v_mfma_f32_16x16x32_bf16 v[16:19], v[206:209], v[140:143], 0
	v_mfma_f32_16x16x32_bf16 v[76:79], v[198:201], v[160:163], 0
	v_mfma_f32_16x16x32_bf16 v[4:7], v[206:209], v[160:163], 0
	v_mfma_f32_16x16x32_bf16 v[72:75], v[198:201], v[190:193], 0
	v_mfma_f32_16x16x32_bf16 v[0:3], v[206:209], v[190:193], 0
	v_mfma_f32_16x16x32_bf16 v[52:55], v[198:201], v[124:127], 0
	v_mfma_f32_16x16x32_bf16 v[20:23], v[210:213], v[132:135], v[20:23]
	v_mfma_f32_16x16x32_bf16 v[16:19], v[210:213], v[156:159], v[16:19]
	v_mfma_f32_16x16x32_bf16 v[80:83], v[202:205], v[164:167], v[76:79]
	v_mfma_f32_16x16x32_bf16 v[4:7], v[210:213], v[164:167], v[4:7]
	v_mfma_f32_16x16x32_bf16 v[72:75], v[202:205], v[194:197], v[72:75]
	v_mfma_f32_16x16x32_bf16 v[0:3], v[210:213], v[194:197], v[0:3]
	v_mfma_f32_16x16x32_bf16 v[52:55], v[202:205], v[132:135], v[52:55]
	s_barrier
	ds_read_b128 v[76:79], v237 offset:32768
	ds_read_b128 v[92:95], v237 offset:33792
	ds_read_b128 v[104:107], v237 offset:34816
	ds_read_b128 v[108:111], v237 offset:35840
	ds_read_b128 v[124:127], v238 offset:32768
	ds_read_b128 v[132:135], v238 offset:33792
	ds_read_b128 v[156:159], v238 offset:34816
	ds_read_b128 v[160:163], v238 offset:35840
	ds_read_b128 v[164:167], v238 offset:36864
	ds_read_b128 v[190:193], v238 offset:37888
	ds_read_b128 v[194:197], v238 offset:38912
	ds_read_b128 v[198:201], v238 offset:39936
	s_barrier
	s_waitcnt lgkmcnt(0)
	v_mfma_f32_16x16x32_bf16 v[140:143], v[76:79], v[124:127], v[152:155]
	v_mfma_f32_16x16x32_bf16 v[152:155], v[92:95], v[132:135], v[140:143]
	v_mfma_f32_16x16x32_bf16 v[68:71], v[104:107], v[124:127], v[68:71]
	v_mfma_f32_16x16x32_bf16 v[140:143], v[76:79], v[156:159], v[148:151]
	v_mfma_f32_16x16x32_bf16 v[64:67], v[104:107], v[156:159], v[64:67]
	v_mfma_f32_16x16x32_bf16 v[136:139], v[76:79], v[164:167], v[136:139]
	v_mfma_f32_16x16x32_bf16 v[44:47], v[104:107], v[164:167], v[44:47]
	v_mfma_f32_16x16x32_bf16 v[128:131], v[76:79], v[194:197], v[128:131]
	v_mfma_f32_16x16x32_bf16 v[40:43], v[104:107], v[194:197], v[40:43]
	v_mfma_f32_16x16x32_bf16 v[68:71], v[108:111], v[132:135], v[68:71]
	v_mfma_f32_16x16x32_bf16 v[148:151], v[92:95], v[160:163], v[140:143]
	v_mfma_f32_16x16x32_bf16 v[64:67], v[108:111], v[160:163], v[64:67]
	v_mfma_f32_16x16x32_bf16 v[136:139], v[92:95], v[190:193], v[136:139]
	v_mfma_f32_16x16x32_bf16 v[44:47], v[108:111], v[190:193], v[44:47]
	v_mfma_f32_16x16x32_bf16 v[128:131], v[92:95], v[198:201], v[128:131]
	v_mfma_f32_16x16x32_bf16 v[40:43], v[108:111], v[198:201], v[40:43]
	s_barrier
	s_mov_b32 m0, s56
	ds_read_b128 v[202:205], v237 offset:49152
	ds_read_b128 v[206:209], v237 offset:50176
	ds_read_b128 v[210:213], v237 offset:51200
	global_load_lds_dwordx4 v180, s[12:13]
	s_mov_b32 m0, s57
	ds_read_b128 v[214:217], v237 offset:52224
	global_load_lds_dwordx4 v182, s[12:13]
	s_barrier
	s_waitcnt lgkmcnt(0)
	v_mfma_f32_16x16x32_bf16 v[140:143], v[202:205], v[124:127], v[144:147]
	v_mfma_f32_16x16x32_bf16 v[112:115], v[202:205], v[156:159], v[112:115]
	v_mfma_f32_16x16x32_bf16 v[144:147], v[206:209], v[132:135], v[140:143]
	v_mfma_f32_16x16x32_bf16 v[60:63], v[210:213], v[124:127], v[60:63]
	v_mfma_f32_16x16x32_bf16 v[140:143], v[206:209], v[160:163], v[112:115]
	v_mfma_f32_16x16x32_bf16 v[112:115], v[202:205], v[164:167], v[116:119]
	v_mfma_f32_16x16x32_bf16 v[60:63], v[214:217], v[132:135], v[60:63]
	v_mfma_f32_16x16x32_bf16 v[56:59], v[210:213], v[156:159], v[56:59]
	v_mfma_f32_16x16x32_bf16 v[132:135], v[206:209], v[190:193], v[112:115]
	v_mfma_f32_16x16x32_bf16 v[36:39], v[210:213], v[164:167], v[36:39]
	v_mfma_f32_16x16x32_bf16 v[112:115], v[202:205], v[194:197], v[120:123]
	v_mfma_f32_16x16x32_bf16 v[32:35], v[210:213], v[194:197], v[32:35]
	v_mfma_f32_16x16x32_bf16 v[56:59], v[214:217], v[160:163], v[56:59]
	v_mfma_f32_16x16x32_bf16 v[36:39], v[214:217], v[190:193], v[36:39]
	v_mfma_f32_16x16x32_bf16 v[124:127], v[206:209], v[198:201], v[112:115]
	v_mfma_f32_16x16x32_bf16 v[32:35], v[214:217], v[198:201], v[32:35]
	s_barrier
	ds_read_b128 v[112:115], v238 offset:49152
	ds_read_b128 v[116:119], v238 offset:50176
	ds_read_b128 v[120:123], v238 offset:51200
	ds_read_b128 v[156:159], v238 offset:52224
	ds_read_b128 v[160:163], v238 offset:53248
	ds_read_b128 v[164:167], v238 offset:54272
	ds_read_b128 v[190:193], v238 offset:55296
	ds_read_b128 v[194:197], v238 offset:56320
	s_add_i32 m0, s53, 0x18000
	s_nop 0
	global_load_lds_dwordx4 v168, s[98:99]
	s_add_i32 m0, s53, 0x1a000
	s_nop 0
	global_load_lds_dwordx4 v184, s[98:99]
	s_barrier
	s_waitcnt lgkmcnt(0)
	v_mfma_f32_16x16x32_bf16 v[100:103], v[76:79], v[112:115], v[100:103]
	v_mfma_f32_16x16x32_bf16 v[28:31], v[104:107], v[112:115], v[28:31]
	v_mfma_f32_16x16x32_bf16 v[96:99], v[76:79], v[120:123], v[96:99]
	v_mfma_f32_16x16x32_bf16 v[24:27], v[104:107], v[120:123], v[24:27]
	v_mfma_f32_16x16x32_bf16 v[84:87], v[76:79], v[160:163], v[84:87]
	v_mfma_f32_16x16x32_bf16 v[12:15], v[104:107], v[160:163], v[12:15]
	v_mfma_f32_16x16x32_bf16 v[48:51], v[76:79], v[190:193], v[48:51]
	v_mfma_f32_16x16x32_bf16 v[8:11], v[104:107], v[190:193], v[8:11]
	v_mfma_f32_16x16x32_bf16 v[100:103], v[92:95], v[116:119], v[100:103]
	v_mfma_f32_16x16x32_bf16 v[28:31], v[108:111], v[116:119], v[28:31]
	v_mfma_f32_16x16x32_bf16 v[96:99], v[92:95], v[156:159], v[96:99]
	v_mfma_f32_16x16x32_bf16 v[24:27], v[108:111], v[156:159], v[24:27]
	v_mfma_f32_16x16x32_bf16 v[84:87], v[92:95], v[164:167], v[84:87]
	v_mfma_f32_16x16x32_bf16 v[12:15], v[108:111], v[164:167], v[12:15]
	v_mfma_f32_16x16x32_bf16 v[76:79], v[92:95], v[194:197], v[48:51]
	v_mfma_f32_16x16x32_bf16 v[8:11], v[108:111], v[194:197], v[8:11]
	s_barrier
	s_mov_b32 m0, s62
	s_nop 0
	global_load_lds_dwordx4 v180, s[100:101]
	s_mov_b32 m0, s63
	s_nop 0
	global_load_lds_dwordx4 v182, s[100:101]
	s_add_i32 m0, s53, 0x1c000
	s_add_u32 s2, s2, 0x40080
	s_addc_u32 s3, s3, 0
	global_load_lds_dwordx4 v168, s[2:3]
	s_add_i32 m0, s53, 0x1e000
	s_add_i32 s67, s67, 2
	global_load_lds_dwordx4 v184, s[2:3]
	s_waitcnt vmcnt(6)
	s_barrier
	v_mfma_f32_16x16x32_bf16 v[48:51], v[202:205], v[112:115], v[52:55]
	v_mfma_f32_16x16x32_bf16 v[92:95], v[206:209], v[116:119], v[48:51]
	v_mfma_f32_16x16x32_bf16 v[48:51], v[202:205], v[120:123], v[88:91]
	v_mfma_f32_16x16x32_bf16 v[88:91], v[206:209], v[156:159], v[48:51]
	v_mfma_f32_16x16x32_bf16 v[48:51], v[202:205], v[160:163], v[80:83]
	v_mfma_f32_16x16x32_bf16 v[20:23], v[210:213], v[112:115], v[20:23]
	v_mfma_f32_16x16x32_bf16 v[16:19], v[210:213], v[120:123], v[16:19]
	v_mfma_f32_16x16x32_bf16 v[80:83], v[206:209], v[164:167], v[48:51]
	v_mfma_f32_16x16x32_bf16 v[4:7], v[210:213], v[160:163], v[4:7]
	v_mfma_f32_16x16x32_bf16 v[48:51], v[202:205], v[190:193], v[72:75]
	v_mfma_f32_16x16x32_bf16 v[0:3], v[210:213], v[190:193], v[0:3]
	v_mfma_f32_16x16x32_bf16 v[20:23], v[214:217], v[116:119], v[20:23]
	v_mfma_f32_16x16x32_bf16 v[16:19], v[214:217], v[156:159], v[16:19]
	v_mfma_f32_16x16x32_bf16 v[4:7], v[214:217], v[164:167], v[4:7]
	v_mfma_f32_16x16x32_bf16 v[72:75], v[206:209], v[194:197], v[48:51]
	v_mfma_f32_16x16x32_bf16 v[0:3], v[214:217], v[194:197], v[0:3]
	s_add_u32 s10, s10, 0x100
	s_addc_u32 s11, s11, 0
	s_add_u32 s37, s37, 0x100
	s_addc_u32 s39, s39, 0
	s_cmp_gt_u32 s67, 13
	s_barrier
.LBB0_880:
	s_add_u32 s2, s10, 0xfffc0080
	s_addc_u32 s3, s11, -1
	ds_read_b128 v[48:51], v237
	ds_read_b128 v[52:55], v237 offset:1024
	ds_read_b128 v[104:107], v237 offset:2048
	ds_read_b128 v[108:111], v237 offset:3072
	s_cmp_eq_u32 s67, 12
	s_cselect_b32 s13, s1, s3
	s_cselect_b32 s12, s9, s2
	s_cselect_b32 s3, s14, s39
	s_cselect_b32 s2, s15, s37
	ds_read_b128 v[112:115], v238
	ds_read_b128 v[116:119], v238 offset:1024
	ds_read_b128 v[120:123], v238 offset:2048
	ds_read_b128 v[156:159], v238 offset:3072
	ds_read_b128 v[160:163], v238 offset:4096
	ds_read_b128 v[164:167], v238 offset:5120
	ds_read_b128 v[190:193], v238 offset:6144
	ds_read_b128 v[194:197], v238 offset:7168
	s_barrier
	s_waitcnt lgkmcnt(0)
	v_mfma_f32_16x16x32_bf16 v[152:155], v[48:51], v[112:115], v[152:155]
	v_mfma_f32_16x16x32_bf16 v[68:71], v[104:107], v[112:115], v[68:71]
	v_mfma_f32_16x16x32_bf16 v[148:151], v[48:51], v[120:123], v[148:151]
	v_mfma_f32_16x16x32_bf16 v[64:67], v[104:107], v[120:123], v[64:67]
	v_mfma_f32_16x16x32_bf16 v[136:139], v[48:51], v[160:163], v[136:139]
	v_mfma_f32_16x16x32_bf16 v[44:47], v[104:107], v[160:163], v[44:47]
	v_mfma_f32_16x16x32_bf16 v[128:131], v[48:51], v[190:193], v[128:131]
	v_mfma_f32_16x16x32_bf16 v[40:43], v[104:107], v[190:193], v[40:43]
	v_mfma_f32_16x16x32_bf16 v[152:155], v[52:55], v[116:119], v[152:155]
	v_mfma_f32_16x16x32_bf16 v[68:71], v[108:111], v[116:119], v[68:71]
	v_mfma_f32_16x16x32_bf16 v[148:151], v[52:55], v[156:159], v[148:151]
	v_mfma_f32_16x16x32_bf16 v[64:67], v[108:111], v[156:159], v[64:67]
	v_mfma_f32_16x16x32_bf16 v[136:139], v[52:55], v[164:167], v[136:139]
	v_mfma_f32_16x16x32_bf16 v[44:47], v[108:111], v[164:167], v[44:47]
	v_mfma_f32_16x16x32_bf16 v[128:131], v[52:55], v[194:197], v[128:131]
	v_mfma_f32_16x16x32_bf16 v[40:43], v[108:111], v[194:197], v[40:43]
	s_barrier
	s_add_i32 m0, s54, 0xc000
	ds_read_b128 v[198:201], v237 offset:16384
	ds_read_b128 v[202:205], v237 offset:17408
	ds_read_b128 v[206:209], v237 offset:18432
	global_load_lds_dwordx4 v186, s[10:11]
	s_add_i32 m0, s54, 0xe000
	ds_read_b128 v[210:213], v237 offset:19456
	global_load_lds_dwordx4 v188, s[10:11]
	s_add_u32 s98, s2, 0x80
	s_addc_u32 s99, s3, 0
	s_barrier
	s_waitcnt lgkmcnt(0)
	v_mfma_f32_16x16x32_bf16 v[144:147], v[198:201], v[112:115], v[144:147]
	v_mfma_f32_16x16x32_bf16 v[60:63], v[206:209], v[112:115], v[60:63]
	v_mfma_f32_16x16x32_bf16 v[56:59], v[206:209], v[120:123], v[56:59]
	v_mfma_f32_16x16x32_bf16 v[36:39], v[206:209], v[160:163], v[36:39]
	v_mfma_f32_16x16x32_bf16 v[32:35], v[206:209], v[190:193], v[32:35]
	v_mfma_f32_16x16x32_bf16 v[144:147], v[202:205], v[116:119], v[144:147]
	v_mfma_f32_16x16x32_bf16 v[60:63], v[210:213], v[116:119], v[60:63]
	v_mfma_f32_16x16x32_bf16 v[112:115], v[198:201], v[120:123], v[140:143]
	v_mfma_f32_16x16x32_bf16 v[56:59], v[210:213], v[156:159], v[56:59]
	v_mfma_f32_16x16x32_bf16 v[116:119], v[198:201], v[160:163], v[132:135]
	v_mfma_f32_16x16x32_bf16 v[36:39], v[210:213], v[164:167], v[36:39]
	v_mfma_f32_16x16x32_bf16 v[120:123], v[198:201], v[190:193], v[124:127]
	v_mfma_f32_16x16x32_bf16 v[32:35], v[210:213], v[194:197], v[32:35]
	v_mfma_f32_16x16x32_bf16 v[112:115], v[202:205], v[156:159], v[112:115]
	v_mfma_f32_16x16x32_bf16 v[116:119], v[202:205], v[164:167], v[116:119]
	v_mfma_f32_16x16x32_bf16 v[120:123], v[202:205], v[194:197], v[120:123]
	s_add_u32 s100, s12, 0x80
	s_addc_u32 s101, s13, 0
	s_barrier
	ds_read_b128 v[124:127], v238 offset:16384
	ds_read_b128 v[132:135], v238 offset:17408
	ds_read_b128 v[140:143], v238 offset:18432
	ds_read_b128 v[156:159], v238 offset:19456
	ds_read_b128 v[160:163], v238 offset:20480
	ds_read_b128 v[164:167], v238 offset:21504
	ds_read_b128 v[190:193], v238 offset:22528
	ds_read_b128 v[194:197], v238 offset:23552
	s_add_i32 m0, s53, 0x10000
	s_nop 0
	global_load_lds_dwordx4 v168, s[2:3]
	s_add_i32 m0, s53, 0x12000
	s_nop 0
	global_load_lds_dwordx4 v184, s[2:3]
	s_barrier
	s_waitcnt lgkmcnt(0)
	v_mfma_f32_16x16x32_bf16 v[100:103], v[48:51], v[124:127], v[100:103]
	v_mfma_f32_16x16x32_bf16 v[28:31], v[104:107], v[124:127], v[28:31]
	v_mfma_f32_16x16x32_bf16 v[96:99], v[48:51], v[140:143], v[96:99]
	v_mfma_f32_16x16x32_bf16 v[24:27], v[104:107], v[140:143], v[24:27]
	v_mfma_f32_16x16x32_bf16 v[84:87], v[48:51], v[160:163], v[84:87]
	v_mfma_f32_16x16x32_bf16 v[12:15], v[104:107], v[160:163], v[12:15]
	v_mfma_f32_16x16x32_bf16 v[8:11], v[104:107], v[190:193], v[8:11]
	v_mfma_f32_16x16x32_bf16 v[100:103], v[52:55], v[132:135], v[100:103]
	v_mfma_f32_16x16x32_bf16 v[28:31], v[108:111], v[132:135], v[28:31]
	v_mfma_f32_16x16x32_bf16 v[96:99], v[52:55], v[156:159], v[96:99]
	v_mfma_f32_16x16x32_bf16 v[24:27], v[108:111], v[156:159], v[24:27]
	v_mfma_f32_16x16x32_bf16 v[84:87], v[52:55], v[164:167], v[84:87]
	v_mfma_f32_16x16x32_bf16 v[12:15], v[108:111], v[164:167], v[12:15]
	v_mfma_f32_16x16x32_bf16 v[48:51], v[48:51], v[190:193], v[76:79]
	v_mfma_f32_16x16x32_bf16 v[8:11], v[108:111], v[194:197], v[8:11]
	v_mfma_f32_16x16x32_bf16 v[48:51], v[52:55], v[194:197], v[48:51]
	s_barrier
	s_mov_b32 m0, s54
	s_nop 0
	global_load_lds_dwordx4 v180, s[12:13]
	s_mov_b32 m0, s55
	s_nop 0
	global_load_lds_dwordx4 v182, s[12:13]
	s_add_i32 m0, s53, 0x14000
	s_add_u32 s68, s2, 0x40000
	s_addc_u32 s69, s3, 0
	global_load_lds_dwordx4 v168, s[68:69]
	s_add_i32 m0, s53, 0x16000
	s_add_u32 s12, s12, 0x40000
	s_addc_u32 s13, s13, 0
	global_load_lds_dwordx4 v184, s[68:69]
	s_waitcnt vmcnt(6)
	s_barrier
	v_mfma_f32_16x16x32_bf16 v[76:79], v[198:201], v[140:143], v[88:91]
	v_mfma_f32_16x16x32_bf16 v[20:23], v[206:209], v[124:127], v[20:23]
	v_mfma_f32_16x16x32_bf16 v[88:91], v[202:205], v[156:159], v[76:79]
	v_mfma_f32_16x16x32_bf16 v[16:19], v[206:209], v[140:143], v[16:19]
	v_mfma_f32_16x16x32_bf16 v[76:79], v[198:201], v[160:163], v[80:83]
	v_mfma_f32_16x16x32_bf16 v[4:7], v[206:209], v[160:163], v[4:7]
	v_mfma_f32_16x16x32_bf16 v[72:75], v[198:201], v[190:193], v[72:75]
	v_mfma_f32_16x16x32_bf16 v[0:3], v[206:209], v[190:193], v[0:3]
	v_mfma_f32_16x16x32_bf16 v[52:55], v[198:201], v[124:127], v[92:95]
	v_mfma_f32_16x16x32_bf16 v[20:23], v[210:213], v[132:135], v[20:23]
	v_mfma_f32_16x16x32_bf16 v[16:19], v[210:213], v[156:159], v[16:19]
	v_mfma_f32_16x16x32_bf16 v[80:83], v[202:205], v[164:167], v[76:79]
	v_mfma_f32_16x16x32_bf16 v[4:7], v[210:213], v[164:167], v[4:7]
	v_mfma_f32_16x16x32_bf16 v[72:75], v[202:205], v[194:197], v[72:75]
	v_mfma_f32_16x16x32_bf16 v[0:3], v[210:213], v[194:197], v[0:3]
	v_mfma_f32_16x16x32_bf16 v[52:55], v[202:205], v[132:135], v[52:55]
	s_barrier
	ds_read_b128 v[76:79], v237 offset:32768
	ds_read_b128 v[92:95], v237 offset:33792
	ds_read_b128 v[104:107], v237 offset:34816
	ds_read_b128 v[108:111], v237 offset:35840
	ds_read_b128 v[124:127], v238 offset:32768
	ds_read_b128 v[132:135], v238 offset:33792
	ds_read_b128 v[156:159], v238 offset:34816
	ds_read_b128 v[160:163], v238 offset:35840
	ds_read_b128 v[164:167], v238 offset:36864
	ds_read_b128 v[190:193], v238 offset:37888
	ds_read_b128 v[194:197], v238 offset:38912
	ds_read_b128 v[198:201], v238 offset:39936
	s_barrier
	s_waitcnt lgkmcnt(0)
	v_mfma_f32_16x16x32_bf16 v[140:143], v[76:79], v[124:127], v[152:155]
	v_mfma_f32_16x16x32_bf16 v[152:155], v[92:95], v[132:135], v[140:143]
	v_mfma_f32_16x16x32_bf16 v[68:71], v[104:107], v[124:127], v[68:71]
	v_mfma_f32_16x16x32_bf16 v[140:143], v[76:79], v[156:159], v[148:151]
	v_mfma_f32_16x16x32_bf16 v[64:67], v[104:107], v[156:159], v[64:67]
	v_mfma_f32_16x16x32_bf16 v[136:139], v[76:79], v[164:167], v[136:139]
	v_mfma_f32_16x16x32_bf16 v[44:47], v[104:107], v[164:167], v[44:47]
	v_mfma_f32_16x16x32_bf16 v[128:131], v[76:79], v[194:197], v[128:131]
	v_mfma_f32_16x16x32_bf16 v[40:43], v[104:107], v[194:197], v[40:43]
	v_mfma_f32_16x16x32_bf16 v[68:71], v[108:111], v[132:135], v[68:71]
	v_mfma_f32_16x16x32_bf16 v[148:151], v[92:95], v[160:163], v[140:143]
	v_mfma_f32_16x16x32_bf16 v[64:67], v[108:111], v[160:163], v[64:67]
	v_mfma_f32_16x16x32_bf16 v[136:139], v[92:95], v[190:193], v[136:139]
	v_mfma_f32_16x16x32_bf16 v[44:47], v[108:111], v[190:193], v[44:47]
	v_mfma_f32_16x16x32_bf16 v[128:131], v[92:95], v[198:201], v[128:131]
	v_mfma_f32_16x16x32_bf16 v[40:43], v[108:111], v[198:201], v[40:43]
	s_barrier
	s_mov_b32 m0, s56
	ds_read_b128 v[202:205], v237 offset:49152
	ds_read_b128 v[206:209], v237 offset:50176
	ds_read_b128 v[210:213], v237 offset:51200
	global_load_lds_dwordx4 v180, s[12:13]
	s_mov_b32 m0, s57
	ds_read_b128 v[214:217], v237 offset:52224
	global_load_lds_dwordx4 v182, s[12:13]
	s_barrier
	s_waitcnt lgkmcnt(0)
	v_mfma_f32_16x16x32_bf16 v[140:143], v[202:205], v[124:127], v[144:147]
	v_mfma_f32_16x16x32_bf16 v[112:115], v[202:205], v[156:159], v[112:115]
	v_mfma_f32_16x16x32_bf16 v[144:147], v[206:209], v[132:135], v[140:143]
	v_mfma_f32_16x16x32_bf16 v[60:63], v[210:213], v[124:127], v[60:63]
	v_mfma_f32_16x16x32_bf16 v[140:143], v[206:209], v[160:163], v[112:115]
	v_mfma_f32_16x16x32_bf16 v[112:115], v[202:205], v[164:167], v[116:119]
	v_mfma_f32_16x16x32_bf16 v[60:63], v[214:217], v[132:135], v[60:63]
	v_mfma_f32_16x16x32_bf16 v[56:59], v[210:213], v[156:159], v[56:59]
	v_mfma_f32_16x16x32_bf16 v[132:135], v[206:209], v[190:193], v[112:115]
	v_mfma_f32_16x16x32_bf16 v[36:39], v[210:213], v[164:167], v[36:39]
	v_mfma_f32_16x16x32_bf16 v[112:115], v[202:205], v[194:197], v[120:123]
	v_mfma_f32_16x16x32_bf16 v[32:35], v[210:213], v[194:197], v[32:35]
	v_mfma_f32_16x16x32_bf16 v[56:59], v[214:217], v[160:163], v[56:59]
	v_mfma_f32_16x16x32_bf16 v[36:39], v[214:217], v[190:193], v[36:39]
	v_mfma_f32_16x16x32_bf16 v[124:127], v[206:209], v[198:201], v[112:115]
	v_mfma_f32_16x16x32_bf16 v[32:35], v[214:217], v[198:201], v[32:35]
	s_barrier
	ds_read_b128 v[112:115], v238 offset:49152
	ds_read_b128 v[116:119], v238 offset:50176
	ds_read_b128 v[120:123], v238 offset:51200
	ds_read_b128 v[156:159], v238 offset:52224
	ds_read_b128 v[160:163], v238 offset:53248
	ds_read_b128 v[164:167], v238 offset:54272
	ds_read_b128 v[190:193], v238 offset:55296
	ds_read_b128 v[194:197], v238 offset:56320
	s_add_i32 m0, s53, 0x18000
	s_nop 0
	global_load_lds_dwordx4 v168, s[98:99]
	s_add_i32 m0, s53, 0x1a000
	s_nop 0
	global_load_lds_dwordx4 v184, s[98:99]
	s_barrier
	s_waitcnt lgkmcnt(0)
	v_mfma_f32_16x16x32_bf16 v[100:103], v[76:79], v[112:115], v[100:103]
	v_mfma_f32_16x16x32_bf16 v[28:31], v[104:107], v[112:115], v[28:31]
	v_mfma_f32_16x16x32_bf16 v[96:99], v[76:79], v[120:123], v[96:99]
	v_mfma_f32_16x16x32_bf16 v[24:27], v[104:107], v[120:123], v[24:27]
	v_mfma_f32_16x16x32_bf16 v[84:87], v[76:79], v[160:163], v[84:87]
	v_mfma_f32_16x16x32_bf16 v[12:15], v[104:107], v[160:163], v[12:15]
	v_mfma_f32_16x16x32_bf16 v[48:51], v[76:79], v[190:193], v[48:51]
	v_mfma_f32_16x16x32_bf16 v[8:11], v[104:107], v[190:193], v[8:11]
	v_mfma_f32_16x16x32_bf16 v[100:103], v[92:95], v[116:119], v[100:103]
	v_mfma_f32_16x16x32_bf16 v[28:31], v[108:111], v[116:119], v[28:31]
	v_mfma_f32_16x16x32_bf16 v[96:99], v[92:95], v[156:159], v[96:99]
	v_mfma_f32_16x16x32_bf16 v[24:27], v[108:111], v[156:159], v[24:27]
	v_mfma_f32_16x16x32_bf16 v[84:87], v[92:95], v[164:167], v[84:87]
	v_mfma_f32_16x16x32_bf16 v[12:15], v[108:111], v[164:167], v[12:15]
	v_mfma_f32_16x16x32_bf16 v[76:79], v[92:95], v[194:197], v[48:51]
	v_mfma_f32_16x16x32_bf16 v[8:11], v[108:111], v[194:197], v[8:11]
	s_barrier
	s_mov_b32 m0, s62
	s_nop 0
	global_load_lds_dwordx4 v180, s[100:101]
	s_mov_b32 m0, s63
	s_nop 0
	global_load_lds_dwordx4 v182, s[100:101]
	s_add_i32 m0, s53, 0x1c000
	s_add_u32 s2, s2, 0x40080
	s_addc_u32 s3, s3, 0
	global_load_lds_dwordx4 v168, s[2:3]
	s_add_i32 m0, s53, 0x1e000
	s_add_i32 s67, s67, 2
	global_load_lds_dwordx4 v184, s[2:3]
	s_waitcnt vmcnt(6)
	s_barrier
	v_mfma_f32_16x16x32_bf16 v[48:51], v[202:205], v[112:115], v[52:55]
	v_mfma_f32_16x16x32_bf16 v[92:95], v[206:209], v[116:119], v[48:51]
	v_mfma_f32_16x16x32_bf16 v[48:51], v[202:205], v[120:123], v[88:91]
	v_mfma_f32_16x16x32_bf16 v[88:91], v[206:209], v[156:159], v[48:51]
	v_mfma_f32_16x16x32_bf16 v[48:51], v[202:205], v[160:163], v[80:83]
	v_mfma_f32_16x16x32_bf16 v[20:23], v[210:213], v[112:115], v[20:23]
	v_mfma_f32_16x16x32_bf16 v[16:19], v[210:213], v[120:123], v[16:19]
	v_mfma_f32_16x16x32_bf16 v[80:83], v[206:209], v[164:167], v[48:51]
	v_mfma_f32_16x16x32_bf16 v[4:7], v[210:213], v[160:163], v[4:7]
	v_mfma_f32_16x16x32_bf16 v[48:51], v[202:205], v[190:193], v[72:75]
	v_mfma_f32_16x16x32_bf16 v[0:3], v[210:213], v[190:193], v[0:3]
	v_mfma_f32_16x16x32_bf16 v[20:23], v[214:217], v[116:119], v[20:23]
	v_mfma_f32_16x16x32_bf16 v[16:19], v[214:217], v[156:159], v[16:19]
	v_mfma_f32_16x16x32_bf16 v[4:7], v[214:217], v[164:167], v[4:7]
	v_mfma_f32_16x16x32_bf16 v[72:75], v[206:209], v[194:197], v[48:51]
	v_mfma_f32_16x16x32_bf16 v[0:3], v[214:217], v[194:197], v[0:3]
	s_add_u32 s10, s10, 0x100
	s_addc_u32 s11, s11, 0
	s_add_u32 s37, s37, 0x100
	s_addc_u32 s39, s39, 0
	s_cmp_gt_u32 s67, 13
	s_barrier
	s_cbranch_scc0 .LBB0_880

.LBB0_1048:
	s_add_u32 s56, s2, 0x100
	s_addc_u32 s57, s3, 0
	s_mov_b32 s58, -2
	s_add_u32 s2, s24, 0x100
	s_addc_u32 s3, s25, 0
	ds_read_b128 v[40:43], v194
	ds_read_b128 v[44:47], v194 offset:1024
	ds_read_b128 v[48:51], v194 offset:2048
	ds_read_b128 v[52:55], v194 offset:3072
	s_cmp_eq_u32 s58, 40
	s_cselect_b32 s27, s1, s3
	s_cselect_b32 s26, s0, s2
	s_cselect_b32 s9, s23, s57
	s_cselect_b32 s8, s22, s56
	ds_read_b128 v[56:59], v195
	ds_read_b128 v[60:63], v195 offset:1024
	ds_read_b128 v[72:75], v195 offset:2048
	ds_read_b128 v[84:87], v195 offset:3072
	ds_read_b128 v[182:185], v195 offset:4096
	ds_read_b128 v[186:189], v195 offset:5120
	ds_read_b128 v[196:199], v195 offset:6144
	ds_read_b128 v[200:203], v195 offset:7168
	s_barrier
	s_waitcnt lgkmcnt(0)
	v_mfma_f32_16x16x32_bf16 v[156:159], v[40:43], v[56:59], 0
	v_mfma_f32_16x16x32_bf16 v[152:155], v[48:51], v[56:59], 0
	v_mfma_f32_16x16x32_bf16 v[140:143], v[40:43], v[72:75], 0
	v_mfma_f32_16x16x32_bf16 v[136:139], v[48:51], v[72:75], 0
	v_mfma_f32_16x16x32_bf16 v[124:127], v[40:43], v[182:185], 0
	v_mfma_f32_16x16x32_bf16 v[120:123], v[48:51], v[182:185], 0
	v_mfma_f32_16x16x32_bf16 v[108:111], v[40:43], v[196:199], 0
	v_mfma_f32_16x16x32_bf16 v[104:107], v[48:51], v[196:199], 0
	v_mfma_f32_16x16x32_bf16 v[156:159], v[44:47], v[60:63], v[156:159]
	v_mfma_f32_16x16x32_bf16 v[152:155], v[52:55], v[60:63], v[152:155]
	v_mfma_f32_16x16x32_bf16 v[140:143], v[44:47], v[84:87], v[140:143]
	v_mfma_f32_16x16x32_bf16 v[136:139], v[52:55], v[84:87], v[136:139]
	v_mfma_f32_16x16x32_bf16 v[124:127], v[44:47], v[186:189], v[124:127]
	v_mfma_f32_16x16x32_bf16 v[120:123], v[52:55], v[186:189], v[120:123]
	v_mfma_f32_16x16x32_bf16 v[108:111], v[44:47], v[200:203], v[108:111]
	v_mfma_f32_16x16x32_bf16 v[104:107], v[52:55], v[200:203], v[104:107]
	s_barrier
	s_add_i32 m0, s37, 0xc000
	ds_read_b128 v[204:207], v194 offset:16384
	ds_read_b128 v[208:211], v194 offset:17408
	ds_read_b128 v[212:215], v194 offset:18432
	global_load_lds_dwordx4 v166, s[24:25]
	s_add_i32 m0, s37, 0xe000
	ds_read_b128 v[216:219], v194 offset:19456
	global_load_lds_dwordx4 v180, s[24:25]
	s_add_u32 s98, s8, 0x80
	s_addc_u32 s99, s9, 0
	s_barrier
	s_waitcnt lgkmcnt(0)
	v_mfma_f32_16x16x32_bf16 v[148:151], v[204:207], v[56:59], 0
	v_mfma_f32_16x16x32_bf16 v[56:59], v[212:215], v[56:59], 0
	v_mfma_f32_16x16x32_bf16 v[148:151], v[208:211], v[60:63], v[148:151]
	v_mfma_f32_16x16x32_bf16 v[56:59], v[216:219], v[60:63], v[56:59]
	v_mfma_f32_16x16x32_bf16 v[60:63], v[204:207], v[72:75], 0
	v_mfma_f32_16x16x32_bf16 v[72:75], v[212:215], v[72:75], 0
	v_mfma_f32_16x16x32_bf16 v[112:115], v[212:215], v[182:185], 0
	v_mfma_f32_16x16x32_bf16 v[100:103], v[204:207], v[196:199], 0
	v_mfma_f32_16x16x32_bf16 v[96:99], v[212:215], v[196:199], 0
	v_mfma_f32_16x16x32_bf16 v[60:63], v[208:211], v[84:87], v[60:63]
	v_mfma_f32_16x16x32_bf16 v[72:75], v[216:219], v[84:87], v[72:75]
	v_mfma_f32_16x16x32_bf16 v[84:87], v[204:207], v[182:185], 0
	v_mfma_f32_16x16x32_bf16 v[112:115], v[216:219], v[186:189], v[112:115]
	v_mfma_f32_16x16x32_bf16 v[100:103], v[208:211], v[200:203], v[100:103]
	v_mfma_f32_16x16x32_bf16 v[96:99], v[216:219], v[200:203], v[96:99]
	v_mfma_f32_16x16x32_bf16 v[84:87], v[208:211], v[186:189], v[84:87]
	s_add_u32 s100, s26, 0x80
	s_addc_u32 s101, s27, 0
	s_barrier
	ds_read_b128 v[116:119], v195 offset:16384
	ds_read_b128 v[128:131], v195 offset:17408
	ds_read_b128 v[132:135], v195 offset:18432
	ds_read_b128 v[144:147], v195 offset:19456
	ds_read_b128 v[182:185], v195 offset:20480
	ds_read_b128 v[186:189], v195 offset:21504
	ds_read_b128 v[196:199], v195 offset:22528
	ds_read_b128 v[200:203], v195 offset:23552
	s_add_i32 m0, s36, 0x10000
	s_nop 0
	global_load_lds_dwordx4 v168, s[8:9]
	s_add_i32 m0, s36, 0x12000
	s_nop 0
	global_load_lds_dwordx4 v164, s[8:9]
	s_barrier
	s_waitcnt lgkmcnt(0)
	v_mfma_f32_16x16x32_bf16 v[92:95], v[40:43], v[116:119], 0
	v_mfma_f32_16x16x32_bf16 v[88:91], v[48:51], v[116:119], 0
	v_mfma_f32_16x16x32_bf16 v[68:71], v[40:43], v[132:135], 0
	v_mfma_f32_16x16x32_bf16 v[64:67], v[48:51], v[132:135], 0
	v_mfma_f32_16x16x32_bf16 v[28:31], v[40:43], v[182:185], 0
	v_mfma_f32_16x16x32_bf16 v[24:27], v[48:51], v[182:185], 0
	v_mfma_f32_16x16x32_bf16 v[12:15], v[40:43], v[196:199], 0
	v_mfma_f32_16x16x32_bf16 v[8:11], v[48:51], v[196:199], 0
	v_mfma_f32_16x16x32_bf16 v[92:95], v[44:47], v[128:131], v[92:95]
	v_mfma_f32_16x16x32_bf16 v[88:91], v[52:55], v[128:131], v[88:91]
	v_mfma_f32_16x16x32_bf16 v[68:71], v[44:47], v[144:147], v[68:71]
	v_mfma_f32_16x16x32_bf16 v[64:67], v[52:55], v[144:147], v[64:67]
	v_mfma_f32_16x16x32_bf16 v[28:31], v[44:47], v[186:189], v[28:31]
	v_mfma_f32_16x16x32_bf16 v[24:27], v[52:55], v[186:189], v[24:27]
	v_mfma_f32_16x16x32_bf16 v[12:15], v[44:47], v[200:203], v[12:15]
	v_mfma_f32_16x16x32_bf16 v[8:11], v[52:55], v[200:203], v[8:11]
	s_barrier
	s_mov_b32 m0, s37
	s_nop 0
	global_load_lds_dwordx4 v160, s[26:27]
	s_mov_b32 m0, s38
	s_nop 0
	global_load_lds_dwordx4 v162, s[26:27]
	s_add_i32 m0, s36, 0x14000
	s_add_u32 s24, s8, 0xb0000
	s_addc_u32 s25, s9, 0
	global_load_lds_dwordx4 v168, s[24:25]
	s_add_i32 m0, s36, 0x16000
	s_nop 0
	global_load_lds_dwordx4 v164, s[24:25]
	s_waitcnt vmcnt(6)
	s_barrier
	v_mfma_f32_16x16x32_bf16 v[36:39], v[204:207], v[132:135], 0
	v_mfma_f32_16x16x32_bf16 v[32:35], v[212:215], v[132:135], 0
	v_mfma_f32_16x16x32_bf16 v[20:23], v[204:207], v[182:185], 0
	v_mfma_f32_16x16x32_bf16 v[16:19], v[212:215], v[182:185], 0
	v_mfma_f32_16x16x32_bf16 v[4:7], v[204:207], v[196:199], 0
	v_mfma_f32_16x16x32_bf16 v[0:3], v[212:215], v[196:199], 0
	v_mfma_f32_16x16x32_bf16 v[40:43], v[204:207], v[116:119], 0
	v_mfma_f32_16x16x32_bf16 v[44:47], v[212:215], v[116:119], 0
	v_mfma_f32_16x16x32_bf16 v[36:39], v[208:211], v[144:147], v[36:39]
	v_mfma_f32_16x16x32_bf16 v[32:35], v[216:219], v[144:147], v[32:35]
	v_mfma_f32_16x16x32_bf16 v[20:23], v[208:211], v[186:189], v[20:23]
	v_mfma_f32_16x16x32_bf16 v[16:19], v[216:219], v[186:189], v[16:19]
	v_mfma_f32_16x16x32_bf16 v[4:7], v[208:211], v[200:203], v[4:7]
	v_mfma_f32_16x16x32_bf16 v[0:3], v[216:219], v[200:203], v[0:3]
	v_mfma_f32_16x16x32_bf16 v[40:43], v[208:211], v[128:131], v[40:43]
	v_mfma_f32_16x16x32_bf16 v[44:47], v[216:219], v[128:131], v[44:47]
	s_barrier
	ds_read_b128 v[48:51], v194 offset:32768
	ds_read_b128 v[52:55], v194 offset:33792
	ds_read_b128 v[76:79], v194 offset:34816
	ds_read_b128 v[80:83], v194 offset:35840
	s_add_u32 s24, s26, 0xb0000
	s_addc_u32 s25, s27, 0
	ds_read_b128 v[116:119], v195 offset:32768
	ds_read_b128 v[128:131], v195 offset:33792
	ds_read_b128 v[182:185], v195 offset:34816
	ds_read_b128 v[186:189], v195 offset:35840
	ds_read_b128 v[196:199], v195 offset:36864
	ds_read_b128 v[200:203], v195 offset:37888
	ds_read_b128 v[204:207], v195 offset:38912
	ds_read_b128 v[208:211], v195 offset:39936
	s_barrier
	s_waitcnt lgkmcnt(0)
	v_mfma_f32_16x16x32_bf16 v[132:135], v[48:51], v[116:119], v[156:159]
	v_mfma_f32_16x16x32_bf16 v[156:159], v[52:55], v[128:131], v[132:135]
	v_mfma_f32_16x16x32_bf16 v[132:135], v[76:79], v[116:119], v[152:155]
	v_mfma_f32_16x16x32_bf16 v[152:155], v[80:83], v[128:131], v[132:135]
	v_mfma_f32_16x16x32_bf16 v[132:135], v[48:51], v[182:185], v[140:143]
	v_mfma_f32_16x16x32_bf16 v[140:143], v[52:55], v[186:189], v[132:135]
	v_mfma_f32_16x16x32_bf16 v[132:135], v[76:79], v[182:185], v[136:139]
	v_mfma_f32_16x16x32_bf16 v[124:127], v[48:51], v[196:199], v[124:127]
	v_mfma_f32_16x16x32_bf16 v[120:123], v[76:79], v[196:199], v[120:123]
	v_mfma_f32_16x16x32_bf16 v[108:111], v[48:51], v[204:207], v[108:111]
	v_mfma_f32_16x16x32_bf16 v[104:107], v[76:79], v[204:207], v[104:107]
	v_mfma_f32_16x16x32_bf16 v[136:139], v[80:83], v[186:189], v[132:135]
	v_mfma_f32_16x16x32_bf16 v[124:127], v[52:55], v[200:203], v[124:127]
	v_mfma_f32_16x16x32_bf16 v[120:123], v[80:83], v[200:203], v[120:123]
	v_mfma_f32_16x16x32_bf16 v[108:111], v[52:55], v[208:211], v[108:111]
	v_mfma_f32_16x16x32_bf16 v[104:107], v[80:83], v[208:211], v[104:107]
	s_barrier
	s_mov_b32 m0, s39
	ds_read_b128 v[212:215], v194 offset:49152
	ds_read_b128 v[216:219], v194 offset:50176
	ds_read_b128 v[220:223], v194 offset:51200
	global_load_lds_dwordx4 v160, s[24:25]
	s_mov_b32 m0, s40
	ds_read_b128 v[236:239], v194 offset:52224
	global_load_lds_dwordx4 v162, s[24:25]
	s_barrier
	s_waitcnt lgkmcnt(0)
	v_mfma_f32_16x16x32_bf16 v[56:59], v[220:223], v[116:119], v[56:59]
	v_mfma_f32_16x16x32_bf16 v[132:135], v[212:215], v[116:119], v[148:151]
	v_mfma_f32_16x16x32_bf16 v[144:147], v[236:239], v[128:131], v[56:59]
	v_mfma_f32_16x16x32_bf16 v[56:59], v[212:215], v[182:185], v[60:63]
	v_mfma_f32_16x16x32_bf16 v[148:151], v[216:219], v[128:131], v[132:135]
	v_mfma_f32_16x16x32_bf16 v[132:135], v[216:219], v[186:189], v[56:59]
	v_mfma_f32_16x16x32_bf16 v[56:59], v[220:223], v[182:185], v[72:75]
	v_mfma_f32_16x16x32_bf16 v[128:131], v[236:239], v[186:189], v[56:59]
	v_mfma_f32_16x16x32_bf16 v[56:59], v[212:215], v[196:199], v[84:87]
	v_mfma_f32_16x16x32_bf16 v[116:119], v[216:219], v[200:203], v[56:59]
	v_mfma_f32_16x16x32_bf16 v[56:59], v[220:223], v[196:199], v[112:115]
	v_mfma_f32_16x16x32_bf16 v[112:115], v[236:239], v[200:203], v[56:59]
	v_mfma_f32_16x16x32_bf16 v[56:59], v[212:215], v[204:207], v[100:103]
	v_mfma_f32_16x16x32_bf16 v[100:103], v[216:219], v[208:211], v[56:59]
	v_mfma_f32_16x16x32_bf16 v[56:59], v[220:223], v[204:207], v[96:99]
	v_mfma_f32_16x16x32_bf16 v[96:99], v[236:239], v[208:211], v[56:59]
	s_barrier
	s_nop 2
	ds_read_b128 v[56:59], v195 offset:49152
	ds_read_b128 v[60:63], v195 offset:50176
	ds_read_b128 v[72:75], v195 offset:51200
	ds_read_b128 v[84:87], v195 offset:52224
	ds_read_b128 v[182:185], v195 offset:53248
	ds_read_b128 v[186:189], v195 offset:54272
	ds_read_b128 v[196:199], v195 offset:55296
	ds_read_b128 v[200:203], v195 offset:56320
	s_add_i32 m0, s36, 0x18000
	s_nop 0
	global_load_lds_dwordx4 v168, s[98:99]
	s_add_i32 m0, s36, 0x1a000
	s_nop 0
	global_load_lds_dwordx4 v164, s[98:99]
	s_barrier
	s_waitcnt lgkmcnt(0)
	v_mfma_f32_16x16x32_bf16 v[92:95], v[48:51], v[56:59], v[92:95]
	v_mfma_f32_16x16x32_bf16 v[88:91], v[76:79], v[56:59], v[88:91]
	v_mfma_f32_16x16x32_bf16 v[68:71], v[48:51], v[72:75], v[68:71]
	v_mfma_f32_16x16x32_bf16 v[64:67], v[76:79], v[72:75], v[64:67]
	v_mfma_f32_16x16x32_bf16 v[28:31], v[48:51], v[182:185], v[28:31]
	v_mfma_f32_16x16x32_bf16 v[24:27], v[76:79], v[182:185], v[24:27]
	v_mfma_f32_16x16x32_bf16 v[12:15], v[48:51], v[196:199], v[12:15]
	v_mfma_f32_16x16x32_bf16 v[8:11], v[76:79], v[196:199], v[8:11]
	v_mfma_f32_16x16x32_bf16 v[92:95], v[52:55], v[60:63], v[92:95]
	v_mfma_f32_16x16x32_bf16 v[88:91], v[80:83], v[60:63], v[88:91]
	v_mfma_f32_16x16x32_bf16 v[68:71], v[52:55], v[84:87], v[68:71]
	v_mfma_f32_16x16x32_bf16 v[64:67], v[80:83], v[84:87], v[64:67]
	v_mfma_f32_16x16x32_bf16 v[28:31], v[52:55], v[186:189], v[28:31]
	v_mfma_f32_16x16x32_bf16 v[24:27], v[80:83], v[186:189], v[24:27]
	v_mfma_f32_16x16x32_bf16 v[12:15], v[52:55], v[200:203], v[12:15]
	v_mfma_f32_16x16x32_bf16 v[8:11], v[80:83], v[200:203], v[8:11]
	s_barrier
	s_mov_b32 m0, s47
	s_nop 0
	global_load_lds_dwordx4 v160, s[100:101]
	s_mov_b32 m0, s49
	s_nop 0
	global_load_lds_dwordx4 v162, s[100:101]
	s_add_i32 m0, s36, 0x1c000
	s_add_u32 s8, s8, 0xb0080
	s_addc_u32 s9, s9, 0
	global_load_lds_dwordx4 v168, s[8:9]
	s_add_i32 m0, s36, 0x1e000
	s_add_i32 s58, s58, 2
	global_load_lds_dwordx4 v164, s[8:9]
	s_waitcnt vmcnt(6)
	s_barrier
	v_mfma_f32_16x16x32_bf16 v[40:43], v[212:215], v[56:59], v[40:43]
	v_mfma_f32_16x16x32_bf16 v[80:83], v[216:219], v[60:63], v[40:43]
	v_mfma_f32_16x16x32_bf16 v[40:43], v[220:223], v[56:59], v[44:47]
	v_mfma_f32_16x16x32_bf16 v[36:39], v[212:215], v[72:75], v[36:39]
	v_mfma_f32_16x16x32_bf16 v[32:35], v[220:223], v[72:75], v[32:35]
	v_mfma_f32_16x16x32_bf16 v[20:23], v[212:215], v[182:185], v[20:23]
	v_mfma_f32_16x16x32_bf16 v[16:19], v[220:223], v[182:185], v[16:19]
	v_mfma_f32_16x16x32_bf16 v[4:7], v[212:215], v[196:199], v[4:7]
	v_mfma_f32_16x16x32_bf16 v[0:3], v[220:223], v[196:199], v[0:3]
	v_mfma_f32_16x16x32_bf16 v[76:79], v[236:239], v[60:63], v[40:43]
	v_mfma_f32_16x16x32_bf16 v[36:39], v[216:219], v[84:87], v[36:39]
	v_mfma_f32_16x16x32_bf16 v[32:35], v[236:239], v[84:87], v[32:35]
	v_mfma_f32_16x16x32_bf16 v[20:23], v[216:219], v[186:189], v[20:23]
	v_mfma_f32_16x16x32_bf16 v[16:19], v[236:239], v[186:189], v[16:19]
	v_mfma_f32_16x16x32_bf16 v[4:7], v[216:219], v[200:203], v[4:7]
	v_mfma_f32_16x16x32_bf16 v[0:3], v[236:239], v[200:203], v[0:3]
	s_add_u32 s56, s56, 0x100
	s_addc_u32 s57, s57, 0
	s_cmp_gt_u32 s58, 41
	s_mov_b64 s[24:25], s[2:3]
	s_barrier
.LBB0_1049:
	s_add_u32 s2, s24, 0x100
	s_addc_u32 s3, s25, 0
	ds_read_b128 v[40:43], v194
	ds_read_b128 v[44:47], v194 offset:1024
	ds_read_b128 v[48:51], v194 offset:2048
	ds_read_b128 v[52:55], v194 offset:3072
	s_cmp_eq_u32 s58, 40
	s_cselect_b32 s27, s1, s3
	s_cselect_b32 s26, s0, s2
	s_cselect_b32 s9, s23, s57
	s_cselect_b32 s8, s22, s56
	ds_read_b128 v[56:59], v195
	ds_read_b128 v[60:63], v195 offset:1024
	ds_read_b128 v[72:75], v195 offset:2048
	ds_read_b128 v[84:87], v195 offset:3072
	ds_read_b128 v[182:185], v195 offset:4096
	ds_read_b128 v[186:189], v195 offset:5120
	ds_read_b128 v[196:199], v195 offset:6144
	ds_read_b128 v[200:203], v195 offset:7168
	s_barrier
	s_waitcnt lgkmcnt(0)
	v_mfma_f32_16x16x32_bf16 v[156:159], v[40:43], v[56:59], v[156:159]
	v_mfma_f32_16x16x32_bf16 v[152:155], v[48:51], v[56:59], v[152:155]
	v_mfma_f32_16x16x32_bf16 v[140:143], v[40:43], v[72:75], v[140:143]
	v_mfma_f32_16x16x32_bf16 v[136:139], v[48:51], v[72:75], v[136:139]
	v_mfma_f32_16x16x32_bf16 v[124:127], v[40:43], v[182:185], v[124:127]
	v_mfma_f32_16x16x32_bf16 v[120:123], v[48:51], v[182:185], v[120:123]
	v_mfma_f32_16x16x32_bf16 v[108:111], v[40:43], v[196:199], v[108:111]
	v_mfma_f32_16x16x32_bf16 v[104:107], v[48:51], v[196:199], v[104:107]
	v_mfma_f32_16x16x32_bf16 v[156:159], v[44:47], v[60:63], v[156:159]
	v_mfma_f32_16x16x32_bf16 v[152:155], v[52:55], v[60:63], v[152:155]
	v_mfma_f32_16x16x32_bf16 v[140:143], v[44:47], v[84:87], v[140:143]
	v_mfma_f32_16x16x32_bf16 v[136:139], v[52:55], v[84:87], v[136:139]
	v_mfma_f32_16x16x32_bf16 v[124:127], v[44:47], v[186:189], v[124:127]
	v_mfma_f32_16x16x32_bf16 v[120:123], v[52:55], v[186:189], v[120:123]
	v_mfma_f32_16x16x32_bf16 v[108:111], v[44:47], v[200:203], v[108:111]
	v_mfma_f32_16x16x32_bf16 v[104:107], v[52:55], v[200:203], v[104:107]
	s_barrier
	s_add_i32 m0, s37, 0xc000
	ds_read_b128 v[204:207], v194 offset:16384
	ds_read_b128 v[208:211], v194 offset:17408
	ds_read_b128 v[212:215], v194 offset:18432
	global_load_lds_dwordx4 v166, s[24:25]
	s_add_i32 m0, s37, 0xe000
	ds_read_b128 v[216:219], v194 offset:19456
	global_load_lds_dwordx4 v180, s[24:25]
	s_add_u32 s98, s8, 0x80
	s_addc_u32 s99, s9, 0
	s_barrier
	s_waitcnt lgkmcnt(0)
	v_mfma_f32_16x16x32_bf16 v[148:151], v[204:207], v[56:59], v[148:151]
	v_mfma_f32_16x16x32_bf16 v[56:59], v[212:215], v[56:59], v[144:147]
	v_mfma_f32_16x16x32_bf16 v[148:151], v[208:211], v[60:63], v[148:151]
	v_mfma_f32_16x16x32_bf16 v[56:59], v[216:219], v[60:63], v[56:59]
	v_mfma_f32_16x16x32_bf16 v[60:63], v[204:207], v[72:75], v[132:135]
	v_mfma_f32_16x16x32_bf16 v[72:75], v[212:215], v[72:75], v[128:131]
	v_mfma_f32_16x16x32_bf16 v[112:115], v[212:215], v[182:185], v[112:115]
	v_mfma_f32_16x16x32_bf16 v[100:103], v[204:207], v[196:199], v[100:103]
	v_mfma_f32_16x16x32_bf16 v[96:99], v[212:215], v[196:199], v[96:99]
	v_mfma_f32_16x16x32_bf16 v[60:63], v[208:211], v[84:87], v[60:63]
	v_mfma_f32_16x16x32_bf16 v[72:75], v[216:219], v[84:87], v[72:75]
	v_mfma_f32_16x16x32_bf16 v[84:87], v[204:207], v[182:185], v[116:119]
	v_mfma_f32_16x16x32_bf16 v[112:115], v[216:219], v[186:189], v[112:115]
	v_mfma_f32_16x16x32_bf16 v[100:103], v[208:211], v[200:203], v[100:103]
	v_mfma_f32_16x16x32_bf16 v[96:99], v[216:219], v[200:203], v[96:99]
	v_mfma_f32_16x16x32_bf16 v[84:87], v[208:211], v[186:189], v[84:87]
	s_add_u32 s100, s26, 0x80
	s_addc_u32 s101, s27, 0
	s_barrier
	ds_read_b128 v[116:119], v195 offset:16384
	ds_read_b128 v[128:131], v195 offset:17408
	ds_read_b128 v[132:135], v195 offset:18432
	ds_read_b128 v[144:147], v195 offset:19456
	ds_read_b128 v[182:185], v195 offset:20480
	ds_read_b128 v[186:189], v195 offset:21504
	ds_read_b128 v[196:199], v195 offset:22528
	ds_read_b128 v[200:203], v195 offset:23552
	s_add_i32 m0, s36, 0x10000
	s_nop 0
	global_load_lds_dwordx4 v168, s[8:9]
	s_add_i32 m0, s36, 0x12000
	s_nop 0
	global_load_lds_dwordx4 v164, s[8:9]
	s_barrier
	s_waitcnt lgkmcnt(0)
	v_mfma_f32_16x16x32_bf16 v[92:95], v[40:43], v[116:119], v[92:95]
	v_mfma_f32_16x16x32_bf16 v[88:91], v[48:51], v[116:119], v[88:91]
	v_mfma_f32_16x16x32_bf16 v[68:71], v[40:43], v[132:135], v[68:71]
	v_mfma_f32_16x16x32_bf16 v[64:67], v[48:51], v[132:135], v[64:67]
	v_mfma_f32_16x16x32_bf16 v[28:31], v[40:43], v[182:185], v[28:31]
	v_mfma_f32_16x16x32_bf16 v[24:27], v[48:51], v[182:185], v[24:27]
	v_mfma_f32_16x16x32_bf16 v[12:15], v[40:43], v[196:199], v[12:15]
	v_mfma_f32_16x16x32_bf16 v[8:11], v[48:51], v[196:199], v[8:11]
	v_mfma_f32_16x16x32_bf16 v[92:95], v[44:47], v[128:131], v[92:95]
	v_mfma_f32_16x16x32_bf16 v[88:91], v[52:55], v[128:131], v[88:91]
	v_mfma_f32_16x16x32_bf16 v[68:71], v[44:47], v[144:147], v[68:71]
	v_mfma_f32_16x16x32_bf16 v[64:67], v[52:55], v[144:147], v[64:67]
	v_mfma_f32_16x16x32_bf16 v[28:31], v[44:47], v[186:189], v[28:31]
	v_mfma_f32_16x16x32_bf16 v[24:27], v[52:55], v[186:189], v[24:27]
	v_mfma_f32_16x16x32_bf16 v[12:15], v[44:47], v[200:203], v[12:15]
	v_mfma_f32_16x16x32_bf16 v[8:11], v[52:55], v[200:203], v[8:11]
	s_barrier
	s_mov_b32 m0, s37
	s_nop 0
	global_load_lds_dwordx4 v160, s[26:27]
	s_mov_b32 m0, s38
	s_nop 0
	global_load_lds_dwordx4 v162, s[26:27]
	s_add_i32 m0, s36, 0x14000
	s_add_u32 s24, s8, 0xb0000
	s_addc_u32 s25, s9, 0
	global_load_lds_dwordx4 v168, s[24:25]
	s_add_i32 m0, s36, 0x16000
	s_nop 0
	global_load_lds_dwordx4 v164, s[24:25]
	s_waitcnt vmcnt(6)
	s_barrier
	v_mfma_f32_16x16x32_bf16 v[36:39], v[204:207], v[132:135], v[36:39]
	v_mfma_f32_16x16x32_bf16 v[32:35], v[212:215], v[132:135], v[32:35]
	v_mfma_f32_16x16x32_bf16 v[20:23], v[204:207], v[182:185], v[20:23]
	v_mfma_f32_16x16x32_bf16 v[16:19], v[212:215], v[182:185], v[16:19]
	v_mfma_f32_16x16x32_bf16 v[4:7], v[204:207], v[196:199], v[4:7]
	v_mfma_f32_16x16x32_bf16 v[0:3], v[212:215], v[196:199], v[0:3]
	v_mfma_f32_16x16x32_bf16 v[40:43], v[204:207], v[116:119], v[80:83]
	v_mfma_f32_16x16x32_bf16 v[44:47], v[212:215], v[116:119], v[76:79]
	v_mfma_f32_16x16x32_bf16 v[36:39], v[208:211], v[144:147], v[36:39]
	v_mfma_f32_16x16x32_bf16 v[32:35], v[216:219], v[144:147], v[32:35]
	v_mfma_f32_16x16x32_bf16 v[20:23], v[208:211], v[186:189], v[20:23]
	v_mfma_f32_16x16x32_bf16 v[16:19], v[216:219], v[186:189], v[16:19]
	v_mfma_f32_16x16x32_bf16 v[4:7], v[208:211], v[200:203], v[4:7]
	v_mfma_f32_16x16x32_bf16 v[0:3], v[216:219], v[200:203], v[0:3]
	v_mfma_f32_16x16x32_bf16 v[40:43], v[208:211], v[128:131], v[40:43]
	v_mfma_f32_16x16x32_bf16 v[44:47], v[216:219], v[128:131], v[44:47]
	s_barrier
	ds_read_b128 v[48:51], v194 offset:32768
	ds_read_b128 v[52:55], v194 offset:33792
	ds_read_b128 v[76:79], v194 offset:34816
	ds_read_b128 v[80:83], v194 offset:35840
	s_add_u32 s24, s26, 0xb0000
	s_addc_u32 s25, s27, 0
	ds_read_b128 v[116:119], v195 offset:32768
	ds_read_b128 v[128:131], v195 offset:33792
	ds_read_b128 v[182:185], v195 offset:34816
	ds_read_b128 v[186:189], v195 offset:35840
	ds_read_b128 v[196:199], v195 offset:36864
	ds_read_b128 v[200:203], v195 offset:37888
	ds_read_b128 v[204:207], v195 offset:38912
	ds_read_b128 v[208:211], v195 offset:39936
	s_barrier
	s_waitcnt lgkmcnt(0)
	v_mfma_f32_16x16x32_bf16 v[132:135], v[48:51], v[116:119], v[156:159]
	v_mfma_f32_16x16x32_bf16 v[156:159], v[52:55], v[128:131], v[132:135]
	v_mfma_f32_16x16x32_bf16 v[132:135], v[76:79], v[116:119], v[152:155]
	v_mfma_f32_16x16x32_bf16 v[152:155], v[80:83], v[128:131], v[132:135]
	v_mfma_f32_16x16x32_bf16 v[132:135], v[48:51], v[182:185], v[140:143]
	v_mfma_f32_16x16x32_bf16 v[140:143], v[52:55], v[186:189], v[132:135]
	v_mfma_f32_16x16x32_bf16 v[132:135], v[76:79], v[182:185], v[136:139]
	v_mfma_f32_16x16x32_bf16 v[124:127], v[48:51], v[196:199], v[124:127]
	v_mfma_f32_16x16x32_bf16 v[120:123], v[76:79], v[196:199], v[120:123]
	v_mfma_f32_16x16x32_bf16 v[108:111], v[48:51], v[204:207], v[108:111]
	v_mfma_f32_16x16x32_bf16 v[104:107], v[76:79], v[204:207], v[104:107]
	v_mfma_f32_16x16x32_bf16 v[136:139], v[80:83], v[186:189], v[132:135]
	v_mfma_f32_16x16x32_bf16 v[124:127], v[52:55], v[200:203], v[124:127]
	v_mfma_f32_16x16x32_bf16 v[120:123], v[80:83], v[200:203], v[120:123]
	v_mfma_f32_16x16x32_bf16 v[108:111], v[52:55], v[208:211], v[108:111]
	v_mfma_f32_16x16x32_bf16 v[104:107], v[80:83], v[208:211], v[104:107]
	s_barrier
	s_mov_b32 m0, s39
	ds_read_b128 v[212:215], v194 offset:49152
	ds_read_b128 v[216:219], v194 offset:50176
	ds_read_b128 v[220:223], v194 offset:51200
	global_load_lds_dwordx4 v160, s[24:25]
	s_mov_b32 m0, s40
	ds_read_b128 v[236:239], v194 offset:52224
	global_load_lds_dwordx4 v162, s[24:25]
	s_barrier
	s_waitcnt lgkmcnt(0)
	v_mfma_f32_16x16x32_bf16 v[56:59], v[220:223], v[116:119], v[56:59]
	v_mfma_f32_16x16x32_bf16 v[132:135], v[212:215], v[116:119], v[148:151]
	v_mfma_f32_16x16x32_bf16 v[144:147], v[236:239], v[128:131], v[56:59]
	v_mfma_f32_16x16x32_bf16 v[56:59], v[212:215], v[182:185], v[60:63]
	v_mfma_f32_16x16x32_bf16 v[148:151], v[216:219], v[128:131], v[132:135]
	v_mfma_f32_16x16x32_bf16 v[132:135], v[216:219], v[186:189], v[56:59]
	v_mfma_f32_16x16x32_bf16 v[56:59], v[220:223], v[182:185], v[72:75]
	v_mfma_f32_16x16x32_bf16 v[128:131], v[236:239], v[186:189], v[56:59]
	v_mfma_f32_16x16x32_bf16 v[56:59], v[212:215], v[196:199], v[84:87]
	v_mfma_f32_16x16x32_bf16 v[116:119], v[216:219], v[200:203], v[56:59]
	v_mfma_f32_16x16x32_bf16 v[56:59], v[220:223], v[196:199], v[112:115]
	v_mfma_f32_16x16x32_bf16 v[112:115], v[236:239], v[200:203], v[56:59]
	v_mfma_f32_16x16x32_bf16 v[56:59], v[212:215], v[204:207], v[100:103]
	v_mfma_f32_16x16x32_bf16 v[100:103], v[216:219], v[208:211], v[56:59]
	v_mfma_f32_16x16x32_bf16 v[56:59], v[220:223], v[204:207], v[96:99]
	v_mfma_f32_16x16x32_bf16 v[96:99], v[236:239], v[208:211], v[56:59]
	s_barrier
	s_nop 2
	ds_read_b128 v[56:59], v195 offset:49152
	ds_read_b128 v[60:63], v195 offset:50176
	ds_read_b128 v[72:75], v195 offset:51200
	ds_read_b128 v[84:87], v195 offset:52224
	ds_read_b128 v[182:185], v195 offset:53248
	ds_read_b128 v[186:189], v195 offset:54272
	ds_read_b128 v[196:199], v195 offset:55296
	ds_read_b128 v[200:203], v195 offset:56320
	s_add_i32 m0, s36, 0x18000
	s_nop 0
	global_load_lds_dwordx4 v168, s[98:99]
	s_add_i32 m0, s36, 0x1a000
	s_nop 0
	global_load_lds_dwordx4 v164, s[98:99]
	s_barrier
	s_waitcnt lgkmcnt(0)
	v_mfma_f32_16x16x32_bf16 v[92:95], v[48:51], v[56:59], v[92:95]
	v_mfma_f32_16x16x32_bf16 v[88:91], v[76:79], v[56:59], v[88:91]
	v_mfma_f32_16x16x32_bf16 v[68:71], v[48:51], v[72:75], v[68:71]
	v_mfma_f32_16x16x32_bf16 v[64:67], v[76:79], v[72:75], v[64:67]
	v_mfma_f32_16x16x32_bf16 v[28:31], v[48:51], v[182:185], v[28:31]
	v_mfma_f32_16x16x32_bf16 v[24:27], v[76:79], v[182:185], v[24:27]
	v_mfma_f32_16x16x32_bf16 v[12:15], v[48:51], v[196:199], v[12:15]
	v_mfma_f32_16x16x32_bf16 v[8:11], v[76:79], v[196:199], v[8:11]
	v_mfma_f32_16x16x32_bf16 v[92:95], v[52:55], v[60:63], v[92:95]
	v_mfma_f32_16x16x32_bf16 v[88:91], v[80:83], v[60:63], v[88:91]
	v_mfma_f32_16x16x32_bf16 v[68:71], v[52:55], v[84:87], v[68:71]
	v_mfma_f32_16x16x32_bf16 v[64:67], v[80:83], v[84:87], v[64:67]
	v_mfma_f32_16x16x32_bf16 v[28:31], v[52:55], v[186:189], v[28:31]
	v_mfma_f32_16x16x32_bf16 v[24:27], v[80:83], v[186:189], v[24:27]
	v_mfma_f32_16x16x32_bf16 v[12:15], v[52:55], v[200:203], v[12:15]
	v_mfma_f32_16x16x32_bf16 v[8:11], v[80:83], v[200:203], v[8:11]
	s_barrier
	s_mov_b32 m0, s47
	s_nop 0
	global_load_lds_dwordx4 v160, s[100:101]
	s_mov_b32 m0, s49
	s_nop 0
	global_load_lds_dwordx4 v162, s[100:101]
	s_add_i32 m0, s36, 0x1c000
	s_add_u32 s8, s8, 0xb0080
	s_addc_u32 s9, s9, 0
	global_load_lds_dwordx4 v168, s[8:9]
	s_add_i32 m0, s36, 0x1e000
	s_add_i32 s58, s58, 2
	global_load_lds_dwordx4 v164, s[8:9]
	s_waitcnt vmcnt(6)
	s_barrier
	v_mfma_f32_16x16x32_bf16 v[40:43], v[212:215], v[56:59], v[40:43]
	v_mfma_f32_16x16x32_bf16 v[80:83], v[216:219], v[60:63], v[40:43]
	v_mfma_f32_16x16x32_bf16 v[40:43], v[220:223], v[56:59], v[44:47]
	v_mfma_f32_16x16x32_bf16 v[36:39], v[212:215], v[72:75], v[36:39]
	v_mfma_f32_16x16x32_bf16 v[32:35], v[220:223], v[72:75], v[32:35]
	v_mfma_f32_16x16x32_bf16 v[20:23], v[212:215], v[182:185], v[20:23]
	v_mfma_f32_16x16x32_bf16 v[16:19], v[220:223], v[182:185], v[16:19]
	v_mfma_f32_16x16x32_bf16 v[4:7], v[212:215], v[196:199], v[4:7]
	v_mfma_f32_16x16x32_bf16 v[0:3], v[220:223], v[196:199], v[0:3]
	v_mfma_f32_16x16x32_bf16 v[76:79], v[236:239], v[60:63], v[40:43]
	v_mfma_f32_16x16x32_bf16 v[36:39], v[216:219], v[84:87], v[36:39]
	v_mfma_f32_16x16x32_bf16 v[32:35], v[236:239], v[84:87], v[32:35]
	v_mfma_f32_16x16x32_bf16 v[20:23], v[216:219], v[186:189], v[20:23]
	v_mfma_f32_16x16x32_bf16 v[16:19], v[236:239], v[186:189], v[16:19]
	v_mfma_f32_16x16x32_bf16 v[4:7], v[216:219], v[200:203], v[4:7]
	v_mfma_f32_16x16x32_bf16 v[0:3], v[236:239], v[200:203], v[0:3]
	s_add_u32 s56, s56, 0x100
	s_addc_u32 s57, s57, 0
	s_cmp_gt_u32 s58, 41
	s_mov_b64 s[24:25], s[2:3]
	s_barrier
	s_cbranch_scc0 .LBB0_1049
	s_lshl_b32 s2, s55, 8
	v_mov_b32_e32 v186, v193
	v_mov_b32_e32 v196, v192
	s_or_b32 s2, s2, s46
	v_mov_b32_e32 v52, 0
	v_lshl_add_u32 v182, v196, 3, s2
	s_add_i32 s2, s54, -16
	s_lshr_b32 s2, s2, 3
	s_add_i32 s2, s2, 1
	s_cmp_gt_i32 s54, 15
	s_cselect_b32 s8, s2, 0
	s_mul_i32 s96, s8, 0x1800
	s_lshl_b64 s[2:3], s[96:97], 2
	s_add_u32 s2, s41, s2
	v_ashrrev_i32_e32 v183, 31, v182
	s_addc_u32 s3, s42, s3
	v_lshlrev_b64 v[40:41], 2, v[182:183]
	v_lshl_add_u64 v[42:43], s[2:3], 0, v[40:41]
	global_load_dwordx4 v[72:75], v[42:43], off
	s_lshl_b32 s96, s8, 10
	s_lshl_b64 s[2:3], s[96:97], 2
	s_add_u32 s2, s43, s2
	s_addc_u32 s3, s44, s3
	v_lshl_add_u64 v[184:185], s[2:3], 0, v[40:41]
	s_and_b64 vcc, exec, s[4:5]
	v_mov_b32_e32 v60, 0
	v_mov_b32_e32 v61, v52
	v_mov_b32_e32 v62, 0
	v_mov_b32_e32 v63, 0
	s_cbranch_vccnz .LBB0_1052
	global_load_dwordx4 v[60:63], v[184:185], off
